# FFT complex multiplies: packed FMAs with one useful lane replaced by scalar v_fma, trailing moves folded, twiddle copies dropped
# speedup vs baseline: 1.0251x; 1.0086x over previous
; __device__ __forceinline__ c2 cmul(c2 a, c2 b) { return (c2){a.x * b.x - a.y * b.y, a.x * b.y + a.y * b.x}; }
; __device__ __forceinline__ c2 mni(c2 a) { return (c2){a.y, -a.x}; }
; __device__ __forceinline__ void dft8(c2 (&x)[8]) {
;     const float s = 0.70710678118654752f;
;     const c2 a0 = x[0] + x[4], a4 = x[0] - x[4], a1 = x[1] + x[5], a5 = x[1] - x[5], a2 = x[2] + x[6], a6 = x[2] - x[6], a3 = x[3] + x[7], a7 = x[3] - x[7];
;     const c2 a5w = (c2){(a5.x + a5.y) * s, (a5.y - a5.x) * s};
;     const c2 a6w = mni(a6);
;     const c2 a7w = (c2){(a7.y - a7.x) * s, -(a7.x + a7.y) * s};
;     const c2 b0 = a0 + a2, b1 = a0 - a2, b2 = a1 + a3, b3 = mni(a1 - a3);
;     x[0] = b0 + b2; x[4] = b0 - b2; x[2] = b1 + b3; x[6] = b1 - b3;
;     const c2 c0 = a4 + a6w, c1 = a4 - a6w, c2_ = a5w + a7w, c3 = mni(a5w - a7w);
;     x[1] = c0 + c2_; x[5] = c0 - c2_; x[3] = c1 + c3; x[7] = c1 - c3;
; }
; __device__ __forceinline__ c2 mpi(c2 a) { return (c2){-a.y, a.x}; }
; __device__ __forceinline__ void idft8(c2 (&x)[8]) {
;     const float s = 0.70710678118654752f;
;     const c2 a0 = x[0] + x[4], a4 = x[0] - x[4], a1 = x[1] + x[5], a5 = x[1] - x[5], a2 = x[2] + x[6], a6 = x[2] - x[6], a3 = x[3] + x[7], a7 = x[3] - x[7];
;     const c2 a5w = (c2){(a5.x - a5.y) * s, (a5.x + a5.y) * s};
;     const c2 a6w = mpi(a6);
;     const c2 a7w = (c2){-(a7.x + a7.y) * s, (a7.x - a7.y) * s};
;     const c2 b0 = a0 + a2, b1 = a0 - a2, b2 = a1 + a3, b3 = mpi(a1 - a3);
;     x[0] = b0 + b2; x[4] = b0 - b2; x[2] = b1 + b3; x[6] = b1 - b3;
;     const c2 c0 = a4 + a6w, c1 = a4 - a6w, c2_ = a5w + a7w, c3 = mpi(a5w - a7w);
;     x[1] = c0 + c2_; x[5] = c0 - c2_; x[3] = c1 + c3; x[7] = c1 - c3;
; }
; __device__ __forceinline__ void fwd_s0(c2 (&x)[8], c2* buf, const c2* tws, int tid) {
;     dft8(x);
; #pragma unroll
;     for (int q = 1; q < 8; ++q) x[q] = cmul(x[q], tws[(q - 1) * 512 + tid]);
;     { c2* bp_ = buf + LP(tid);
; #pragma unroll
;     for (int q = 0; q < 8; ++q) bp_[576 * q] = x[q]; }
; }
.LBB0_287:
	s_or_b64 exec, exec, s[72:73]
	s_waitcnt vmcnt(0)
	v_pk_add_f32 v[8:9], v[0:1], v[4:5]
	v_sub_f32_e32 v56, v0, v4
	v_sub_f32_e32 v4, v1, v5
	v_pk_add_f32 v[0:1], v[2:3], v[6:7]
	v_sub_f32_e32 v7, v3, v7
	s_barrier
	v_sub_f32_e32 v5, v2, v6
	v_sub_f32_e32 v6, 0, v7
	v_add_f32_e32 v7, 0, v7
	v_pk_add_f32 v[10:11], v[8:9], v[0:1] neg_lo:[0,1] neg_hi:[0,1]
	v_add_f32_e32 v2, 0, v4
	v_sub_f32_e32 v3, 0, v4
	v_pk_mul_f32 v[6:7], v[6:7], s[20:21]
	v_pk_add_f32 v[0:1], v[8:9], v[0:1]
	v_pk_add_f32 v[8:9], v[10:11], 0 neg_lo:[1,1] neg_hi:[1,1]
	v_xor_b32_e32 v5, 0x80000000, v5
	v_mov_b32_e32 v4, v57
	v_mov_b32_e32 v12, v10
	v_mov_b32_e32 v13, v57
	v_mov_b32_e32 v8, v57
	v_pk_fma_f32 v[16:17], v[2:3], s[20:21], v[6:7] op_sel_hi:[1,0,1]
	v_pk_fma_f32 v[2:3], v[2:3], s[20:21], v[6:7] op_sel_hi:[1,0,1] neg_lo:[0,0,1] neg_hi:[0,0,1]
	v_pk_add_f32 v[14:15], v[12:13], v[8:9]
	v_pk_add_f32 v[8:9], v[12:13], v[8:9] neg_lo:[0,1] neg_hi:[0,1]
	v_pk_add_f32 v[12:13], v[56:57], v[4:5]
	v_pk_add_f32 v[4:5], v[56:57], v[4:5] neg_lo:[0,1] neg_hi:[0,1]
	v_xor_b32_e32 v7, 0x80000000, v2
	v_mov_b32_e32 v6, v3
	v_pk_add_f32 v[2:3], v[12:13], v[16:17]
	v_pk_add_f32 v[12:13], v[12:13], v[16:17] neg_lo:[0,1] neg_hi:[0,1]
	v_pk_add_f32 v[16:17], v[4:5], v[6:7]
	v_pk_add_f32 v[4:5], v[4:5], v[6:7] neg_lo:[0,1] neg_hi:[0,1]
	s_waitcnt lgkmcnt(0)
	v_pk_mul_f32 v[24:25], v[210:211], v[2:3] op_sel:[1,1] op_sel_hi:[0,1]
	v_fma_f32 v26, v210, v2, -v24
	v_fma_f32 v27, v211, v2, v25
	v_pk_add_f32 v[10:11], v[0:1], v[0:1] op_sel:[0,1] op_sel_hi:[1,0]
	s_waitcnt lgkmcnt(0)
	v_pk_mul_f32 v[2:3], v[14:15], v[212:213] op_sel:[1,1] op_sel_hi:[1,0]
	v_pk_add_f32 v[0:1], v[0:1], v[0:1] op_sel:[0,1] op_sel_hi:[0,1] neg_lo:[0,1] neg_hi:[0,1]
	v_fma_f32 v18, v14, v212, -v2
	v_fma_f32 v19, v14, v213, v3
	s_waitcnt lgkmcnt(0)
	v_pk_mul_f32 v[2:3], v[214:215], v[16:17] op_sel:[1,1] op_sel_hi:[0,1]
	v_fma_f32 v6, v214, v16, -v2
	v_fma_f32 v7, v215, v16, v3
	s_waitcnt lgkmcnt(0)
	v_pk_mul_f32 v[2:3], v[216:217], 0 op_sel_hi:[1,0]
	v_mov_b32_e32 v11, v57
	v_fma_f32 v14, v0, v216, -v3
	v_fma_f32 v15, v1, v217, v2
	s_waitcnt lgkmcnt(0)
	v_pk_mul_f32 v[20:21], v[12:13], v[218:219] op_sel:[1,1] op_sel_hi:[1,0]
	v_fma_f32 v22, v12, v218, -v20
	v_fma_f32 v23, v12, v219, v21
	s_waitcnt lgkmcnt(0)
	v_pk_mul_f32 v[12:13], v[8:9], v[220:221] op_sel:[1,1] op_sel_hi:[1,0]
	v_mov_b32_e32 v56, v57
	v_fma_f32 v16, v8, v220, -v12
	v_fma_f32 v17, v8, v221, v13
	s_waitcnt lgkmcnt(0)
	v_pk_mul_f32 v[0:1], v[4:5], v[222:223] op_sel:[1,1] op_sel_hi:[1,0]
	v_add_u32_e32 v191, 0x9000, v117
	v_fma_f32 v8, v4, v222, -v0
	v_fma_f32 v9, v4, v223, v1
	ds_write2st64_b64 v115, v[10:11], v[26:27] offset1:9
	ds_write2st64_b64 v115, v[18:19], v[6:7] offset0:18 offset1:27
	ds_write2st64_b64 v115, v[14:15], v[22:23] offset0:36 offset1:45
	ds_write2st64_b64 v115, v[16:17], v[8:9] offset0:54 offset1:63
	s_waitcnt lgkmcnt(0)
	v_pk_mul_f32 v[8:9], v[210:211], 0 op_sel_hi:[1,0]
	v_add_u32_e32 v192, 0x9800, v117
	v_pk_fma_f32 v[10:11], v[210:211], 0, v[8:9] op_sel:[0,0,1] op_sel_hi:[1,0,0] neg_lo:[0,0,1] neg_hi:[0,0,1]
	v_pk_fma_f32 v[0:1], v[210:211], 0, v[8:9] op_sel_hi:[1,0,0]
	s_waitcnt lgkmcnt(0)
	v_pk_mul_f32 v[14:15], v[218:219], 0 op_sel_hi:[1,0]
	v_mov_b32_e32 v11, v1
	v_pk_mul_f32 v[0:1], v[212:213], 0 op_sel_hi:[1,0]
	v_pk_fma_f32 v[16:17], v[218:219], 0, v[14:15] op_sel:[0,0,1] op_sel_hi:[1,0,0] neg_lo:[0,0,1] neg_hi:[0,0,1]
	v_pk_fma_f32 v[8:9], v[212:213], 0, v[0:1] op_sel:[0,0,1] op_sel_hi:[1,0,0] neg_lo:[0,0,1] neg_hi:[0,0,1]
	v_pk_fma_f32 v[0:1], v[212:213], 0, v[0:1] op_sel_hi:[1,0,0]
	v_pk_fma_f32 v[12:13], v[218:219], 0, v[14:15] op_sel_hi:[1,0,0]
	v_mov_b32_e32 v9, v1
	v_pk_mul_f32 v[0:1], v[214:215], 0 op_sel_hi:[1,0]
	v_mov_b32_e32 v17, v13
	v_pk_fma_f32 v[2:3], v[214:215], 0, v[0:1] op_sel:[0,0,1] op_sel_hi:[1,0,0] neg_lo:[0,0,1] neg_hi:[0,0,1]
	v_pk_fma_f32 v[0:1], v[214:215], 0, v[0:1] op_sel_hi:[1,0,0]
	v_add_u32_e32 v193, 0x9000, v119
	v_mov_b32_e32 v3, v1
	v_pk_mul_f32 v[0:1], v[216:217], 0 op_sel_hi:[1,0]
	v_mov_b32_e32 v63, v57
	v_pk_fma_f32 v[4:5], v[216:217], 0, v[0:1] op_sel:[0,0,1] op_sel_hi:[1,0,0] neg_lo:[0,0,1] neg_hi:[0,0,1]
	v_pk_fma_f32 v[0:1], v[216:217], 0, v[0:1] op_sel_hi:[1,0,0]
	s_movk_i32 s3, 0x2000
	v_mov_b32_e32 v5, v1
	v_mov_b64_e32 v[6:7], v[222:223]
	s_mov_b32 s92, 0
	v_mov_b32_e32 v67, v66
	s_waitcnt lgkmcnt(0)
	v_pk_mul_f32 v[12:13], v[220:221], 0 op_sel_hi:[1,0]
	s_nop 0
	v_pk_fma_f32 v[14:15], v[220:221], 0, v[12:13] op_sel:[0,0,1] op_sel_hi:[1,0,0] neg_lo:[0,0,1] neg_hi:[0,0,1]
	v_pk_fma_f32 v[0:1], v[220:221], 0, v[12:13] op_sel_hi:[1,0,0]
	s_nop 0
	v_mov_b32_e32 v15, v1
	s_waitcnt lgkmcnt(0)
	v_pk_mul_f32 v[0:1], v[6:7], 0 op_sel_hi:[1,0]
	s_nop 0
	v_pk_fma_f32 v[12:13], v[6:7], 0, v[0:1] op_sel:[0,0,1] op_sel_hi:[1,0,0] neg_lo:[0,0,1] neg_hi:[0,0,1]
	v_pk_fma_f32 v[0:1], v[6:7], 0, v[0:1] op_sel_hi:[1,0,0]
	s_nop 0
	v_mov_b32_e32 v13, v1
	ds_write2st64_b64 v115, v[56:57], v[10:11] offset0:72 offset1:81
	ds_write2st64_b64 v115, v[8:9], v[2:3] offset0:90 offset1:99
	ds_write2st64_b64 v115, v[4:5], v[16:17] offset0:108 offset1:117
	ds_write_b64 v115, v[14:15] offset:64512
	ds_write_b64 v116, v[12:13] offset:32256
	s_waitcnt lgkmcnt(0)
	s_barrier
; __device__ __forceinline__ c2 cmul(c2 a, c2 b) { return (c2){a.x * b.x - a.y * b.y, a.x * b.y + a.y * b.x}; }
; __device__ __forceinline__ c2 mni(c2 a) { return (c2){a.y, -a.x}; }
; __device__ __forceinline__ void dft8(c2 (&x)[8]) {
;     const float s = 0.70710678118654752f;
;     const c2 a0 = x[0] + x[4], a4 = x[0] - x[4], a1 = x[1] + x[5], a5 = x[1] - x[5], a2 = x[2] + x[6], a6 = x[2] - x[6], a3 = x[3] + x[7], a7 = x[3] - x[7];
;     const c2 a5w = (c2){(a5.x + a5.y) * s, (a5.y - a5.x) * s};
;     const c2 a6w = mni(a6);
;     const c2 a7w = (c2){(a7.y - a7.x) * s, -(a7.x + a7.y) * s};
;     const c2 b0 = a0 + a2, b1 = a0 - a2, b2 = a1 + a3, b3 = mni(a1 - a3);
;     x[0] = b0 + b2; x[4] = b0 - b2; x[2] = b1 + b3; x[6] = b1 - b3;
;     const c2 c0 = a4 + a6w, c1 = a4 - a6w, c2_ = a5w + a7w, c3 = mni(a5w - a7w);
;     x[1] = c0 + c2_; x[5] = c0 - c2_; x[3] = c1 + c3; x[7] = c1 - c3;
; }
; template <int S> __device__ __forceinline__ void fwd_mid(c2* buf, const c2* tws, int tid) {
;     constexpr int lq = 9 - 3 * S, Q = 1 << lq; const c2* T = tws + (S == 1 ? 3584 : 4032);
;     const int k = tid & (Q - 1), base = ((tid >> lq) << (lq + 3)) + k;
;     c2 x[8];
;     c2* bp_ = buf + LP(base); constexpr int QP = Q + Q / 8;
; #pragma unroll
;     for (int r = 0; r < 8; ++r) x[r] = bp_[r * QP];
;     dft8(x);
; #pragma unroll
;     for (int q = 1; q < 8; ++q) x[q] = cmul(x[q], T[(q - 1) * Q + k]);
; #pragma unroll
;     for (int q = 0; q < 8; ++q) bp_[q * QP] = x[q];
; }
	ds_read2_b64 v[0:3], v117 offset1:72
	v_add_u32_e32 v56, 0x800, v117
	ds_read2_b64 v[4:7], v56 offset0:32 offset1:104
	ds_read2_b64 v[8:11], v117 offset0:144 offset1:216
	ds_read2_b64 v[12:15], v56 offset0:176 offset1:248
	v_mov_b64_e32 v[18:19], v[224:225]
	s_waitcnt lgkmcnt(0)
	v_pk_add_f32 v[16:17], v[0:1], v[4:5]
	v_pk_add_f32 v[0:1], v[0:1], v[4:5] neg_lo:[0,1] neg_hi:[0,1]
	v_pk_add_f32 v[4:5], v[2:3], v[6:7]
	v_pk_add_f32 v[2:3], v[2:3], v[6:7] neg_lo:[0,1] neg_hi:[0,1]
	s_waitcnt lgkmcnt(0)
	v_pk_add_f32 v[6:7], v[8:9], v[12:13]
	v_pk_add_f32 v[8:9], v[8:9], v[12:13] neg_lo:[0,1] neg_hi:[0,1]
	v_pk_add_f32 v[12:13], v[10:11], v[14:15]
	v_pk_add_f32 v[10:11], v[10:11], v[14:15] neg_lo:[0,1] neg_hi:[0,1]
	v_pk_add_f32 v[14:15], v[2:3], v[2:3] op_sel:[1,0]
	v_pk_add_f32 v[2:3], v[2:3], v[2:3] op_sel_hi:[1,0] neg_lo:[0,1] neg_hi:[0,1]
	s_nop 0
	v_mov_b32_e32 v15, v3
	v_xor_b32_e32 v3, 0x80000000, v8
	v_mov_b32_e32 v2, v9
	v_pk_add_f32 v[8:9], v[10:11], v[10:11] op_sel:[1,0] neg_lo:[0,1] neg_hi:[0,1]
	v_pk_add_f32 v[10:11], v[10:11], v[10:11] op_sel_hi:[1,0]
	s_nop 0
	v_mov_b32_e32 v9, v11
	v_pk_add_f32 v[10:11], v[16:17], v[6:7]
	v_pk_add_f32 v[6:7], v[16:17], v[6:7] neg_lo:[0,1] neg_hi:[0,1]
	v_pk_add_f32 v[16:17], v[4:5], v[12:13]
	v_pk_add_f32 v[4:5], v[4:5], v[12:13] neg_lo:[0,1] neg_hi:[0,1]
	v_pk_mul_f32 v[8:9], v[8:9], s[20:21]
	v_xor_b32_e32 v13, 0x80000000, v4
	v_mov_b32_e32 v12, v5
	v_pk_add_f32 v[4:5], v[10:11], v[16:17]
	v_pk_add_f32 v[10:11], v[10:11], v[16:17] neg_lo:[0,1] neg_hi:[0,1]
	v_pk_add_f32 v[16:17], v[6:7], v[12:13]
	v_pk_add_f32 v[6:7], v[6:7], v[12:13] neg_lo:[0,1] neg_hi:[0,1]
	v_pk_add_f32 v[12:13], v[0:1], v[2:3]
	v_pk_add_f32 v[0:1], v[0:1], v[2:3] neg_lo:[0,1] neg_hi:[0,1]
	v_pk_fma_f32 v[2:3], v[14:15], s[20:21], v[8:9] op_sel_hi:[1,0,1]
	v_pk_fma_f32 v[8:9], v[14:15], s[20:21], v[8:9] op_sel_hi:[1,0,1] neg_lo:[0,0,1] neg_hi:[0,0,1]
	s_nop 0
	v_xor_b32_e32 v15, 0x80000000, v8
	v_mov_b32_e32 v14, v9
	v_pk_add_f32 v[8:9], v[12:13], v[2:3]
	v_pk_add_f32 v[2:3], v[12:13], v[2:3] neg_lo:[0,1] neg_hi:[0,1]
	v_pk_add_f32 v[12:13], v[0:1], v[14:15]
	v_pk_add_f32 v[0:1], v[0:1], v[14:15] neg_lo:[0,1] neg_hi:[0,1]
	s_waitcnt lgkmcnt(0)
	v_pk_mul_f32 v[24:25], v[18:19], v[8:9] op_sel:[1,1] op_sel_hi:[0,1]
	v_fma_f32 v26, v18, v8, -v24
	v_fma_f32 v27, v19, v8, v25
	s_nop 0
	s_waitcnt lgkmcnt(0)
	v_pk_mul_f32 v[8:9], v[226:227], v[16:17] op_sel:[1,1] op_sel_hi:[0,1]
	v_fma_f32 v18, v226, v16, -v8
	v_fma_f32 v19, v227, v16, v9
	s_waitcnt lgkmcnt(0)
	v_pk_mul_f32 v[8:9], v[228:229], v[12:13] op_sel:[1,1] op_sel_hi:[0,1]
	v_fma_f32 v14, v228, v12, -v8
	v_fma_f32 v15, v229, v12, v9
	s_waitcnt lgkmcnt(0)
	v_pk_mul_f32 v[20:21], v[232:233], v[2:3] op_sel:[1,1] op_sel_hi:[0,1]
	v_pk_mul_f32 v[8:9], v[10:11], v[230:231] op_sel:[1,1] op_sel_hi:[1,0]
	s_nop 0
	v_fma_f32 v12, v10, v230, -v8
	v_fma_f32 v13, v10, v231, v9
	v_mov_b64_e32 v[10:11], v[236:237]
	v_fma_f32 v22, v232, v2, -v20
	v_fma_f32 v23, v233, v2, v21
	ds_write2_b64 v117, v[4:5], v[26:27] offset1:72
	ds_write2_b64 v117, v[18:19], v[14:15] offset0:144 offset1:216
	s_waitcnt lgkmcnt(0)
	v_pk_mul_f32 v[2:3], v[6:7], v[234:235] op_sel:[1,1] op_sel_hi:[1,0]
	s_nop 0
	v_fma_f32 v16, v6, v234, -v2
	v_fma_f32 v17, v6, v235, v3
	s_waitcnt lgkmcnt(0)
	v_pk_mul_f32 v[2:3], v[10:11], v[0:1] op_sel:[1,1] op_sel_hi:[0,1]
	v_fma_f32 v8, v10, v0, -v2
	v_fma_f32 v9, v11, v0, v3
	ds_read2_b64 v[4:7], v192 offset0:32 offset1:104
	ds_read2_b64 v[0:3], v191 offset1:72
	ds_write2_b64 v56, v[12:13], v[22:23] offset0:32 offset1:104
	ds_write2_b64 v56, v[16:17], v[8:9] offset0:176 offset1:248
	ds_read2_b64 v[8:11], v191 offset0:144 offset1:216
	ds_read2_b64 v[12:15], v192 offset0:176 offset1:248
	v_mov_b64_e32 v[18:19], v[224:225]
	s_waitcnt lgkmcnt(0)
	v_pk_add_f32 v[16:17], v[0:1], v[4:5]
	v_pk_add_f32 v[0:1], v[0:1], v[4:5] neg_lo:[0,1] neg_hi:[0,1]
	v_pk_add_f32 v[4:5], v[2:3], v[6:7]
	v_pk_add_f32 v[2:3], v[2:3], v[6:7] neg_lo:[0,1] neg_hi:[0,1]
	s_waitcnt lgkmcnt(0)
	v_pk_add_f32 v[6:7], v[8:9], v[12:13]
	v_pk_add_f32 v[8:9], v[8:9], v[12:13] neg_lo:[0,1] neg_hi:[0,1]
	v_pk_add_f32 v[12:13], v[10:11], v[14:15]
	v_pk_add_f32 v[10:11], v[10:11], v[14:15] neg_lo:[0,1] neg_hi:[0,1]
	v_pk_add_f32 v[14:15], v[2:3], v[2:3] op_sel:[1,0]
	v_pk_add_f32 v[2:3], v[2:3], v[2:3] op_sel_hi:[1,0] neg_lo:[0,1] neg_hi:[0,1]
	s_nop 0
	v_mov_b32_e32 v15, v3
	v_xor_b32_e32 v3, 0x80000000, v8
	v_mov_b32_e32 v2, v9
	v_pk_add_f32 v[8:9], v[10:11], v[10:11] op_sel:[1,0] neg_lo:[0,1] neg_hi:[0,1]
	v_pk_add_f32 v[10:11], v[10:11], v[10:11] op_sel_hi:[1,0]
	s_nop 0
	v_mov_b32_e32 v9, v11
	v_pk_add_f32 v[10:11], v[16:17], v[6:7]
	v_pk_add_f32 v[6:7], v[16:17], v[6:7] neg_lo:[0,1] neg_hi:[0,1]
	v_pk_add_f32 v[16:17], v[4:5], v[12:13]
	v_pk_add_f32 v[4:5], v[4:5], v[12:13] neg_lo:[0,1] neg_hi:[0,1]
	v_pk_mul_f32 v[8:9], v[8:9], s[20:21]
	v_xor_b32_e32 v13, 0x80000000, v4
	v_mov_b32_e32 v12, v5
	v_pk_add_f32 v[4:5], v[10:11], v[16:17]
	v_pk_add_f32 v[10:11], v[10:11], v[16:17] neg_lo:[0,1] neg_hi:[0,1]
	v_pk_add_f32 v[16:17], v[6:7], v[12:13]
	v_pk_add_f32 v[6:7], v[6:7], v[12:13] neg_lo:[0,1] neg_hi:[0,1]
	v_pk_add_f32 v[12:13], v[0:1], v[2:3]
	v_pk_add_f32 v[0:1], v[0:1], v[2:3] neg_lo:[0,1] neg_hi:[0,1]
	v_pk_fma_f32 v[2:3], v[14:15], s[20:21], v[8:9] op_sel_hi:[1,0,1]
	v_pk_fma_f32 v[8:9], v[14:15], s[20:21], v[8:9] op_sel_hi:[1,0,1] neg_lo:[0,0,1] neg_hi:[0,0,1]
	s_nop 0
	v_xor_b32_e32 v15, 0x80000000, v8
	v_mov_b32_e32 v14, v9
	v_pk_add_f32 v[8:9], v[12:13], v[2:3]
	v_pk_add_f32 v[2:3], v[12:13], v[2:3] neg_lo:[0,1] neg_hi:[0,1]
	v_pk_add_f32 v[12:13], v[0:1], v[14:15]
	v_pk_add_f32 v[0:1], v[0:1], v[14:15] neg_lo:[0,1] neg_hi:[0,1]
	s_waitcnt lgkmcnt(0)
; __device__ __forceinline__ c2 cmul(c2 a, c2 b) { return (c2){a.x * b.x - a.y * b.y, a.x * b.y + a.y * b.x}; }
; __device__ __forceinline__ c2 mni(c2 a) { return (c2){a.y, -a.x}; }
; __device__ __forceinline__ void dft8(c2 (&x)[8]) {
;     const float s = 0.70710678118654752f;
;     const c2 a0 = x[0] + x[4], a4 = x[0] - x[4], a1 = x[1] + x[5], a5 = x[1] - x[5], a2 = x[2] + x[6], a6 = x[2] - x[6], a3 = x[3] + x[7], a7 = x[3] - x[7];
;     const c2 a5w = (c2){(a5.x + a5.y) * s, (a5.y - a5.x) * s};
;     const c2 a6w = mni(a6);
;     const c2 a7w = (c2){(a7.y - a7.x) * s, -(a7.x + a7.y) * s};
;     const c2 b0 = a0 + a2, b1 = a0 - a2, b2 = a1 + a3, b3 = mni(a1 - a3);
;     x[0] = b0 + b2; x[4] = b0 - b2; x[2] = b1 + b3; x[6] = b1 - b3;
;     const c2 c0 = a4 + a6w, c1 = a4 - a6w, c2_ = a5w + a7w, c3 = mni(a5w - a7w);
;     x[1] = c0 + c2_; x[5] = c0 - c2_; x[3] = c1 + c3; x[7] = c1 - c3;
; }
; template <int S> __device__ __forceinline__ void fwd_mid(c2* buf, const c2* tws, int tid) {
;     constexpr int lq = 9 - 3 * S, Q = 1 << lq; const c2* T = tws + (S == 1 ? 3584 : 4032);
;     const int k = tid & (Q - 1), base = ((tid >> lq) << (lq + 3)) + k;
;     c2 x[8];
;     c2* bp_ = buf + LP(base); constexpr int QP = Q + Q / 8;
; #pragma unroll
;     for (int r = 0; r < 8; ++r) x[r] = bp_[r * QP];
;     dft8(x);
; #pragma unroll
;     for (int q = 1; q < 8; ++q) x[q] = cmul(x[q], T[(q - 1) * Q + k]);
; #pragma unroll
;     for (int q = 0; q < 8; ++q) bp_[q * QP] = x[q];
; }
	v_pk_mul_f32 v[24:25], v[18:19], v[8:9] op_sel:[1,1] op_sel_hi:[0,1]
	v_fma_f32 v26, v18, v8, -v24
	v_fma_f32 v27, v19, v8, v25
	s_nop 0
	s_waitcnt lgkmcnt(0)
	v_pk_mul_f32 v[8:9], v[226:227], v[16:17] op_sel:[1,1] op_sel_hi:[0,1]
	v_fma_f32 v18, v226, v16, -v8
	v_fma_f32 v19, v227, v16, v9
	s_waitcnt lgkmcnt(0)
	v_pk_mul_f32 v[8:9], v[228:229], v[12:13] op_sel:[1,1] op_sel_hi:[0,1]
	v_fma_f32 v14, v228, v12, -v8
	v_fma_f32 v15, v229, v12, v9
	s_waitcnt lgkmcnt(0)
	v_pk_mul_f32 v[20:21], v[232:233], v[2:3] op_sel:[1,1] op_sel_hi:[0,1]
	v_pk_mul_f32 v[8:9], v[10:11], v[230:231] op_sel:[1,1] op_sel_hi:[1,0]
	s_nop 0
	v_fma_f32 v12, v10, v230, -v8
	v_fma_f32 v13, v10, v231, v9
	v_mov_b64_e32 v[8:9], v[234:235]
	v_mov_b64_e32 v[10:11], v[236:237]
	v_fma_f32 v22, v232, v2, -v20
	v_fma_f32 v23, v233, v2, v21
	s_nop 0
	s_waitcnt lgkmcnt(0)
	v_pk_mul_f32 v[2:3], v[6:7], v[8:9] op_sel:[1,1] op_sel_hi:[1,0]
	s_nop 0
	v_fma_f32 v16, v6, v8, -v2
	v_fma_f32 v17, v6, v9, v3
	s_waitcnt lgkmcnt(0)
	v_pk_mul_f32 v[2:3], v[10:11], v[0:1] op_sel:[1,1] op_sel_hi:[0,1]
	v_fma_f32 v6, v10, v0, -v2
	v_fma_f32 v7, v11, v0, v3
	s_nop 0
	ds_write2_b64 v191, v[4:5], v[26:27] offset1:72
	ds_write2_b64 v191, v[18:19], v[14:15] offset0:144 offset1:216
	ds_write2_b64 v192, v[12:13], v[22:23] offset0:32 offset1:104
	ds_write2_b64 v192, v[16:17], v[6:7] offset0:176 offset1:248
	s_waitcnt lgkmcnt(0)
	s_barrier
	ds_read2_b64 v[0:3], v119 offset1:9
	ds_read2_b64 v[4:7], v119 offset0:36 offset1:45
	ds_read2_b64 v[8:11], v119 offset0:18 offset1:27
	ds_read2_b64 v[12:15], v119 offset0:54 offset1:63
	v_mov_b64_e32 v[18:19], v[238:239]
	s_waitcnt lgkmcnt(0)
	v_pk_add_f32 v[16:17], v[0:1], v[4:5]
	v_pk_add_f32 v[0:1], v[0:1], v[4:5] neg_lo:[0,1] neg_hi:[0,1]
	v_pk_add_f32 v[4:5], v[2:3], v[6:7]
	v_pk_add_f32 v[2:3], v[2:3], v[6:7] neg_lo:[0,1] neg_hi:[0,1]
	s_waitcnt lgkmcnt(0)
	v_pk_add_f32 v[6:7], v[8:9], v[12:13]
	v_pk_add_f32 v[8:9], v[8:9], v[12:13] neg_lo:[0,1] neg_hi:[0,1]
	v_pk_add_f32 v[12:13], v[10:11], v[14:15]
	v_pk_add_f32 v[10:11], v[10:11], v[14:15] neg_lo:[0,1] neg_hi:[0,1]
	v_pk_add_f32 v[14:15], v[2:3], v[2:3] op_sel:[1,0]
	v_pk_add_f32 v[2:3], v[2:3], v[2:3] op_sel_hi:[1,0] neg_lo:[0,1] neg_hi:[0,1]
	s_nop 0
	v_mov_b32_e32 v15, v3
	v_xor_b32_e32 v3, 0x80000000, v8
	v_mov_b32_e32 v2, v9
	v_pk_add_f32 v[8:9], v[10:11], v[10:11] op_sel:[1,0] neg_lo:[0,1] neg_hi:[0,1]
	v_pk_add_f32 v[10:11], v[10:11], v[10:11] op_sel_hi:[1,0]
	s_nop 0
	v_mov_b32_e32 v9, v11
	v_pk_add_f32 v[10:11], v[16:17], v[6:7]
	v_pk_add_f32 v[6:7], v[16:17], v[6:7] neg_lo:[0,1] neg_hi:[0,1]
	v_pk_add_f32 v[16:17], v[4:5], v[12:13]
	v_pk_add_f32 v[4:5], v[4:5], v[12:13] neg_lo:[0,1] neg_hi:[0,1]
	v_pk_mul_f32 v[8:9], v[8:9], s[20:21]
	v_xor_b32_e32 v13, 0x80000000, v4
	v_mov_b32_e32 v12, v5
	v_pk_add_f32 v[4:5], v[10:11], v[16:17]
	v_pk_add_f32 v[10:11], v[10:11], v[16:17] neg_lo:[0,1] neg_hi:[0,1]
	v_pk_add_f32 v[16:17], v[6:7], v[12:13]
	v_pk_add_f32 v[6:7], v[6:7], v[12:13] neg_lo:[0,1] neg_hi:[0,1]
	v_pk_add_f32 v[12:13], v[0:1], v[2:3]
	v_pk_add_f32 v[0:1], v[0:1], v[2:3] neg_lo:[0,1] neg_hi:[0,1]
	v_pk_fma_f32 v[2:3], v[14:15], s[20:21], v[8:9] op_sel_hi:[1,0,1]
	v_pk_fma_f32 v[8:9], v[14:15], s[20:21], v[8:9] op_sel_hi:[1,0,1] neg_lo:[0,0,1] neg_hi:[0,0,1]
	s_nop 0
	v_xor_b32_e32 v15, 0x80000000, v8
	v_mov_b32_e32 v14, v9
	v_pk_add_f32 v[8:9], v[12:13], v[2:3]
	v_pk_add_f32 v[2:3], v[12:13], v[2:3] neg_lo:[0,1] neg_hi:[0,1]
	v_pk_add_f32 v[12:13], v[0:1], v[14:15]
	v_pk_add_f32 v[0:1], v[0:1], v[14:15] neg_lo:[0,1] neg_hi:[0,1]
	s_waitcnt lgkmcnt(0)
	v_pk_mul_f32 v[24:25], v[18:19], v[8:9] op_sel:[1,1] op_sel_hi:[0,1]
	v_fma_f32 v26, v18, v8, -v24
	v_fma_f32 v27, v19, v8, v25
	s_nop 0
	s_waitcnt lgkmcnt(0)
	v_pk_mul_f32 v[8:9], v[240:241], v[16:17] op_sel:[1,1] op_sel_hi:[0,1]
	v_fma_f32 v18, v240, v16, -v8
	v_fma_f32 v19, v241, v16, v9
	s_waitcnt lgkmcnt(0)
	v_pk_mul_f32 v[8:9], v[242:243], v[12:13] op_sel:[1,1] op_sel_hi:[0,1]
	v_fma_f32 v14, v242, v12, -v8
	v_fma_f32 v15, v243, v12, v9
	s_waitcnt lgkmcnt(0)
	v_pk_mul_f32 v[20:21], v[246:247], v[2:3] op_sel:[1,1] op_sel_hi:[0,1]
	v_pk_mul_f32 v[8:9], v[10:11], v[244:245] op_sel:[1,1] op_sel_hi:[1,0]
	s_nop 0
	v_fma_f32 v12, v10, v244, -v8
	v_fma_f32 v13, v10, v245, v9
	v_mov_b64_e32 v[10:11], v[250:251]
	v_fma_f32 v22, v246, v2, -v20
	v_fma_f32 v23, v247, v2, v21
	ds_write2_b64 v119, v[4:5], v[26:27] offset1:9
	ds_write2_b64 v119, v[18:19], v[14:15] offset0:18 offset1:27
	s_waitcnt lgkmcnt(0)
	v_pk_mul_f32 v[2:3], v[6:7], v[248:249] op_sel:[1,1] op_sel_hi:[1,0]
	s_nop 0
	v_fma_f32 v16, v6, v248, -v2
	v_fma_f32 v17, v6, v249, v3
	s_waitcnt lgkmcnt(0)
	v_pk_mul_f32 v[2:3], v[10:11], v[0:1] op_sel:[1,1] op_sel_hi:[0,1]
	v_fma_f32 v8, v10, v0, -v2
	v_fma_f32 v9, v11, v0, v3
	s_nop 0
	ds_read2_b64 v[0:3], v193 offset1:9
	ds_read2_b64 v[4:7], v193 offset0:36 offset1:45
	ds_write2_b64 v119, v[12:13], v[22:23] offset0:36 offset1:45
	ds_write2_b64 v119, v[16:17], v[8:9] offset0:54 offset1:63
	ds_read2_b64 v[8:11], v193 offset0:18 offset1:27
	ds_read2_b64 v[12:15], v193 offset0:54 offset1:63
	v_mov_b64_e32 v[18:19], v[238:239]
	s_waitcnt lgkmcnt(0)
	v_pk_add_f32 v[16:17], v[0:1], v[4:5]
	v_pk_add_f32 v[0:1], v[0:1], v[4:5] neg_lo:[0,1] neg_hi:[0,1]
	v_pk_add_f32 v[4:5], v[2:3], v[6:7]
	v_pk_add_f32 v[2:3], v[2:3], v[6:7] neg_lo:[0,1] neg_hi:[0,1]
	s_waitcnt lgkmcnt(0)
; __device__ __forceinline__ c2 cmul(c2 a, c2 b) { return (c2){a.x * b.x - a.y * b.y, a.x * b.y + a.y * b.x}; }
; template <int S> __device__ __forceinline__ void fwd_mid(c2* buf, const c2* tws, int tid) {
;     constexpr int lq = 9 - 3 * S, Q = 1 << lq; const c2* T = tws + (S == 1 ? 3584 : 4032);
;     const int k = tid & (Q - 1), base = ((tid >> lq) << (lq + 3)) + k;
;     c2 x[8];
;     c2* bp_ = buf + LP(base); constexpr int QP = Q + Q / 8;
; #pragma unroll
;     for (int r = 0; r < 8; ++r) x[r] = bp_[r * QP];
;     dft8(x);
; #pragma unroll
;     for (int q = 1; q < 8; ++q) x[q] = cmul(x[q], T[(q - 1) * Q + k]);
; #pragma unroll
;     for (int q = 0; q < 8; ++q) bp_[q * QP] = x[q];
; }
; __device__ __forceinline__ void fwd_s3(c2 (&x)[8], const c2* buf, int tid) {
; #pragma unroll
;     for (int r = 0; r < 8; ++r) x[r] = buf[9 * tid + r];
;     dft8(x);
; }
; __device__ __forceinline__ QuadRegs quad_load(const bf16_t* zsrc, const bf16_t* gsrc, int gstart, bool joined, bool first, bool last, int tid) {
;     const bf16_t* src = ((tid >> 8) ? gsrc : zsrc) + gstart; const int ci = tid & 255;
;     QuadRegs R;
; #pragma unroll
;     for (int k = 0; k < 4; ++k) { R.v[k] = *(const u32x4*)(src + 2048 * k + 8 * ci); R.h[k] = 0u; }
	v_pk_add_f32 v[6:7], v[8:9], v[12:13]
	v_pk_add_f32 v[8:9], v[8:9], v[12:13] neg_lo:[0,1] neg_hi:[0,1]
	v_pk_add_f32 v[12:13], v[10:11], v[14:15]
	v_pk_add_f32 v[10:11], v[10:11], v[14:15] neg_lo:[0,1] neg_hi:[0,1]
	v_pk_add_f32 v[14:15], v[2:3], v[2:3] op_sel:[1,0]
	v_pk_add_f32 v[2:3], v[2:3], v[2:3] op_sel_hi:[1,0] neg_lo:[0,1] neg_hi:[0,1]
	s_nop 0
	v_mov_b32_e32 v15, v3
	v_xor_b32_e32 v3, 0x80000000, v8
	v_mov_b32_e32 v2, v9
	v_pk_add_f32 v[8:9], v[10:11], v[10:11] op_sel:[1,0] neg_lo:[0,1] neg_hi:[0,1]
	v_pk_add_f32 v[10:11], v[10:11], v[10:11] op_sel_hi:[1,0]
	s_nop 0
	v_mov_b32_e32 v9, v11
	v_pk_add_f32 v[10:11], v[16:17], v[6:7]
	v_pk_add_f32 v[6:7], v[16:17], v[6:7] neg_lo:[0,1] neg_hi:[0,1]
	v_pk_add_f32 v[16:17], v[4:5], v[12:13]
	v_pk_add_f32 v[4:5], v[4:5], v[12:13] neg_lo:[0,1] neg_hi:[0,1]
	v_pk_mul_f32 v[8:9], v[8:9], s[20:21]
	v_xor_b32_e32 v13, 0x80000000, v4
	v_mov_b32_e32 v12, v5
	v_pk_add_f32 v[4:5], v[10:11], v[16:17]
	v_pk_add_f32 v[10:11], v[10:11], v[16:17] neg_lo:[0,1] neg_hi:[0,1]
	v_pk_add_f32 v[16:17], v[6:7], v[12:13]
	v_pk_add_f32 v[6:7], v[6:7], v[12:13] neg_lo:[0,1] neg_hi:[0,1]
	v_pk_add_f32 v[12:13], v[0:1], v[2:3]
	v_pk_add_f32 v[0:1], v[0:1], v[2:3] neg_lo:[0,1] neg_hi:[0,1]
	v_pk_fma_f32 v[2:3], v[14:15], s[20:21], v[8:9] op_sel_hi:[1,0,1]
	v_pk_fma_f32 v[8:9], v[14:15], s[20:21], v[8:9] op_sel_hi:[1,0,1] neg_lo:[0,0,1] neg_hi:[0,0,1]
	s_nop 0
	v_xor_b32_e32 v15, 0x80000000, v8
	v_mov_b32_e32 v14, v9
	v_pk_add_f32 v[8:9], v[12:13], v[2:3]
	v_pk_add_f32 v[2:3], v[12:13], v[2:3] neg_lo:[0,1] neg_hi:[0,1]
	v_pk_add_f32 v[12:13], v[0:1], v[14:15]
	v_pk_add_f32 v[0:1], v[0:1], v[14:15] neg_lo:[0,1] neg_hi:[0,1]
	s_waitcnt lgkmcnt(0)
	v_pk_mul_f32 v[24:25], v[18:19], v[8:9] op_sel:[1,1] op_sel_hi:[0,1]
	v_fma_f32 v26, v18, v8, -v24
	v_fma_f32 v27, v19, v8, v25
	s_nop 0
	s_waitcnt lgkmcnt(0)
	v_pk_mul_f32 v[8:9], v[240:241], v[16:17] op_sel:[1,1] op_sel_hi:[0,1]
	v_fma_f32 v18, v240, v16, -v8
	v_fma_f32 v19, v241, v16, v9
	s_waitcnt lgkmcnt(0)
	v_pk_mul_f32 v[8:9], v[242:243], v[12:13] op_sel:[1,1] op_sel_hi:[0,1]
	v_fma_f32 v14, v242, v12, -v8
	v_fma_f32 v15, v243, v12, v9
	s_waitcnt lgkmcnt(0)
	v_pk_mul_f32 v[20:21], v[246:247], v[2:3] op_sel:[1,1] op_sel_hi:[0,1]
	v_pk_mul_f32 v[8:9], v[10:11], v[244:245] op_sel:[1,1] op_sel_hi:[1,0]
	s_nop 0
	v_fma_f32 v12, v10, v244, -v8
	v_fma_f32 v13, v10, v245, v9
	v_mov_b64_e32 v[10:11], v[250:251]
	v_fma_f32 v22, v246, v2, -v20
	v_fma_f32 v23, v247, v2, v21
	s_nop 0
	s_waitcnt lgkmcnt(0)
	v_pk_mul_f32 v[2:3], v[6:7], v[248:249] op_sel:[1,1] op_sel_hi:[1,0]
	s_nop 0
	v_fma_f32 v16, v6, v248, -v2
	v_fma_f32 v17, v6, v249, v3
	s_waitcnt lgkmcnt(0)
	v_pk_mul_f32 v[2:3], v[10:11], v[0:1] op_sel:[1,1] op_sel_hi:[0,1]
	v_fma_f32 v6, v10, v0, -v2
	v_fma_f32 v7, v11, v0, v3
	s_nop 0
	v_mov_b32_e32 v0, s78
	v_mov_b32_e32 v1, s79
	v_cndmask_b32_e64 v69, v0, v1, s[0:1]
	v_mov_b32_e32 v0, s68
	v_mov_b32_e32 v1, s69
	v_cndmask_b32_e64 v68, v0, v1, s[0:1]
	v_lshl_add_u64 v[8:9], v[68:69], 0, v[62:63]
	ds_write2_b64 v193, v[4:5], v[26:27] offset1:9
	ds_write2_b64 v193, v[18:19], v[14:15] offset0:18 offset1:27
	ds_write2_b64 v193, v[12:13], v[22:23] offset0:36 offset1:45
	ds_write2_b64 v193, v[16:17], v[6:7] offset0:54 offset1:63
	v_add_co_u32_e32 v4, vcc, s3, v8
	s_movk_i32 s3, 0x3000
	s_nop 0
	v_addc_co_u32_e32 v5, vcc, 0, v9, vcc
	v_add_co_u32_e32 v12, vcc, s3, v8
	s_waitcnt lgkmcnt(0)
	s_nop 0
	v_addc_co_u32_e32 v13, vcc, 0, v9, vcc
	s_barrier
	global_load_dwordx4 v[0:3], v[4:5], off offset:-4096
	s_nop 0
	global_load_dwordx4 v[4:7], v[4:5], off
	s_nop 0
	global_load_dwordx4 v[8:11], v[8:9], off
	s_nop 0
	global_load_dwordx4 v[12:15], v[12:13], off
	ds_read2_b64 v[16:19], v121 offset1:1
	ds_read2_b64 v[20:23], v121 offset0:4 offset1:5
	ds_read2_b64 v[24:27], v121 offset0:2 offset1:3
	ds_read2_b64 v[28:31], v121 offset0:6 offset1:7
	s_waitcnt lgkmcnt(0)
	v_pk_add_f32 v[32:33], v[16:17], v[20:21]
	v_pk_add_f32 v[16:17], v[16:17], v[20:21] neg_lo:[0,1] neg_hi:[0,1]
	v_pk_add_f32 v[20:21], v[18:19], v[22:23]
	v_pk_add_f32 v[18:19], v[18:19], v[22:23] neg_lo:[0,1] neg_hi:[0,1]
	s_waitcnt lgkmcnt(0)
	v_pk_add_f32 v[22:23], v[24:25], v[28:29]
	v_pk_add_f32 v[24:25], v[24:25], v[28:29] neg_lo:[0,1] neg_hi:[0,1]
	v_pk_add_f32 v[28:29], v[26:27], v[30:31]
	v_pk_add_f32 v[26:27], v[26:27], v[30:31] neg_lo:[0,1] neg_hi:[0,1]
	v_pk_add_f32 v[34:35], v[18:19], v[18:19] op_sel:[1,0]
	v_pk_add_f32 v[18:19], v[18:19], v[18:19] op_sel_hi:[1,0] neg_lo:[0,1] neg_hi:[0,1]
	v_pk_add_f32 v[30:31], v[20:21], v[28:29]
	v_mov_b32_e32 v35, v19
	v_xor_b32_e32 v19, 0x80000000, v24
	v_mov_b32_e32 v18, v25
	v_pk_add_f32 v[24:25], v[26:27], v[26:27] op_sel:[1,0] neg_lo:[0,1] neg_hi:[0,1]
	v_pk_add_f32 v[26:27], v[26:27], v[26:27] op_sel_hi:[1,0]
	v_pk_add_f32 v[20:21], v[20:21], v[28:29] neg_lo:[0,1] neg_hi:[0,1]
	v_mov_b32_e32 v25, v27
	v_pk_mul_f32 v[36:37], v[24:25], s[20:21]
	v_pk_add_f32 v[26:27], v[32:33], v[22:23]
	v_pk_add_f32 v[22:23], v[32:33], v[22:23] neg_lo:[0,1] neg_hi:[0,1]
	v_xor_b32_e32 v33, 0x80000000, v20
	v_mov_b32_e32 v32, v21
	v_pk_add_f32 v[24:25], v[26:27], v[30:31]
	v_pk_add_f32 v[26:27], v[26:27], v[30:31] neg_lo:[0,1] neg_hi:[0,1]
	v_pk_add_f32 v[28:29], v[22:23], v[32:33]
	v_pk_add_f32 v[30:31], v[22:23], v[32:33] neg_lo:[0,1] neg_hi:[0,1]
	v_pk_fma_f32 v[22:23], v[34:35], s[20:21], v[36:37] op_sel_hi:[1,0,1] neg_lo:[0,0,1] neg_hi:[0,0,1]
	v_pk_add_f32 v[20:21], v[16:17], v[18:19]
	v_pk_add_f32 v[16:17], v[16:17], v[18:19] neg_lo:[0,1] neg_hi:[0,1]
	v_pk_fma_f32 v[18:19], v[34:35], s[20:21], v[36:37] op_sel_hi:[1,0,1]
	v_xor_b32_e32 v39, 0x80000000, v22
	v_mov_b32_e32 v38, v23
	v_pk_add_f32 v[32:33], v[20:21], v[18:19]
	v_pk_add_f32 v[34:35], v[20:21], v[18:19] neg_lo:[0,1] neg_hi:[0,1]
	v_pk_add_f32 v[36:37], v[16:17], v[38:39]
	v_pk_add_f32 v[38:39], v[16:17], v[38:39] neg_lo:[0,1] neg_hi:[0,1]
	v_lshl_add_u64 v[16:17], v[68:69], 0, v[60:61]
	v_pk_mov_b32 v[40:41], v[24:25], v[24:25] op_sel:[1,0]
	v_pk_mov_b32 v[42:43], v[32:33], v[32:33] op_sel:[1,0]
	v_pk_mov_b32 v[44:45], v[28:29], v[28:29] op_sel:[1,0]
	v_pk_mov_b32 v[46:47], v[36:37], v[36:37] op_sel:[1,0]
	v_pk_mov_b32 v[48:49], v[26:27], v[26:27] op_sel:[1,0]
	v_pk_mov_b32 v[50:51], v[34:35], v[34:35] op_sel:[1,0]
	v_pk_mov_b32 v[52:53], v[30:31], v[30:31] op_sel:[1,0]
	v_pk_mov_b32 v[54:55], v[38:39], v[38:39] op_sel:[1,0]
	v_lshl_add_u64 v[68:69], v[16:17], 0, s[28:29]
	s_branch .LBB0_289
; __device__ __forceinline__ c2 cmul(c2 a, c2 b) { return (c2){a.x * b.x - a.y * b.y, a.x * b.y + a.y * b.x}; }
; #define ZVAL(r, t) ((o == 0) ? dwl((r), (t), zw0, zw1, zw2, zb) : bf2f((r)[8 + (t)]))
; __device__ __forceinline__ void fwd_s0(c2 (&x)[8], c2* buf, const c2* tws, int tid) {
;     dft8(x);
; #pragma unroll
;     for (int q = 1; q < 8; ++q) x[q] = cmul(x[q], tws[(q - 1) * 512 + tid]);
;     { c2* bp_ = buf + LP(tid);
; #pragma unroll
;     for (int q = 0; q < 8; ++q) bp_[576 * q] = x[q]; }
; }
; __device__ __forceinline__ void phase_conv(const Params& p, int o, unsigned char* smem, int wave) {
;     ...
;                 c2 x0[8], x1[8], zk0[4], zk1[4];
; #pragma unroll
;                 for (int r = 0; r < 4; ++r) { const int t = tid + 512 * r;
;                     x0[r] = (c2){ZVAL(raw, t), ZVAL(raw + RAWROW, t)}; x1[r] = (c2){ZVAL(raw + 2 * RAWROW, t), ZVAL(raw + 3 * RAWROW, t)}; zk0[r] = x0[r]; zk1[r] = x1[r];
;                     x0[4 + r] = (c2){0.f, 0.f}; x1[4 + r] = (c2){0.f, 0.f}; }
;                 fft_fwd_regs2(x0, x1, buf0, buf1, tws, tid);
.LBB0_288:
	v_pk_add_f32 v[16:17], v[84:85], 0 op_sel_hi:[1,0]
	v_pk_add_f32 v[18:19], v[82:83], 0 op_sel_hi:[1,0]
	v_pk_add_f32 v[20:21], v[78:79], 0 op_sel_hi:[1,0]
	v_pk_add_f32 v[22:23], v[80:81], 0 op_sel_hi:[1,0]
	v_sub_f32_e32 v90, v81, v80
	v_add_f32_e32 v91, v81, v80
	v_add_f32_e32 v86, v83, v82
	v_sub_f32_e32 v87, v83, v82
	v_pk_mul_f32 v[90:91], v[90:91], s[20:21]
	v_pk_add_f32 v[92:93], v[16:17], v[20:21]
	v_pk_add_f32 v[20:21], v[16:17], v[20:21] neg_lo:[0,1] neg_hi:[0,1]
	v_pk_add_f32 v[94:95], v[18:19], v[22:23]
	v_pk_add_f32 v[16:17], v[18:19], v[22:23] neg_lo:[0,1] neg_hi:[0,1]
	v_xor_b32_e32 v89, 0x80000000, v78
	v_mov_b32_e32 v88, v79
	v_xor_b32_e32 v19, 0x80000000, v16
	v_mov_b32_e32 v18, v17
	v_pk_add_f32 v[16:17], v[92:93], v[94:95]
	v_pk_add_f32 v[22:23], v[92:93], v[94:95] neg_lo:[0,1] neg_hi:[0,1]
	v_pk_fma_f32 v[94:95], v[86:87], s[20:21], v[90:91] op_sel_hi:[1,0,1]
	v_pk_fma_f32 v[86:87], v[86:87], s[20:21], v[90:91] op_sel_hi:[1,0,1] neg_lo:[0,0,1] neg_hi:[0,0,1]
	v_pk_add_f32 v[92:93], v[20:21], v[18:19]
	v_pk_add_f32 v[18:19], v[20:21], v[18:19] neg_lo:[0,1] neg_hi:[0,1]
	v_pk_add_f32 v[20:21], v[84:85], v[88:89]
	v_pk_add_f32 v[88:89], v[84:85], v[88:89] neg_lo:[0,1] neg_hi:[0,1]
	v_xor_b32_e32 v91, 0x80000000, v86
	v_mov_b32_e32 v90, v87
	v_pk_add_f32 v[86:87], v[20:21], v[94:95]
	v_pk_add_f32 v[20:21], v[20:21], v[94:95] neg_lo:[0,1] neg_hi:[0,1]
	v_pk_add_f32 v[94:95], v[88:89], v[90:91]
	v_pk_add_f32 v[88:89], v[88:89], v[90:91] neg_lo:[0,1] neg_hi:[0,1]
	v_add_u32_e32 v63, 0x9000, v121
	v_add_u32_e32 v205, 0x9020, v121
	v_add_u32_e32 v204, 0x9010, v121
	v_add_u32_e32 v206, 0x9030, v121
	s_waitcnt lgkmcnt(0)
	v_mul_f32_e32 v96, v87, v211
	v_mul_f32_e32 v98, v86, v211
	v_fma_f32 v96, v86, v210, -v96
	v_fma_f32 v87, v87, v210, v98
	v_mov_b32_e32 v97, v87
	s_mov_b32 s84, s21
	s_mov_b32 s85, s20
	v_lshl_add_u64 v[68:69], v[68:69], 0, s[28:29]
	s_waitcnt lgkmcnt(0)
	v_mul_f32_e32 v86, v93, v213
	v_fma_f32 v98, v92, v212, -v86
	v_mul_f32_e32 v86, v92, v213
	v_fma_f32 v99, v93, v212, v86
	v_sub_f32_e32 v90, v71, v70
	v_add_f32_e32 v91, v71, v70
	v_pk_mul_f32 v[90:91], v[90:91], s[20:21]
	s_waitcnt lgkmcnt(0)
	v_mul_f32_e32 v86, v95, v215
	v_fma_f32 v100, v94, v214, -v86
	v_mul_f32_e32 v86, v94, v215
	v_fma_f32 v101, v95, v214, v86
	s_waitcnt lgkmcnt(0)
	v_mul_f32_e32 v86, v23, v217
	v_fma_f32 v102, v22, v216, -v86
	v_mul_f32_e32 v86, v22, v217
	v_fma_f32 v23, v23, v216, v86
	v_mov_b32_e32 v103, v23
	v_add_f32_e32 v86, v75, v74
	v_sub_f32_e32 v87, v75, v74
	s_waitcnt lgkmcnt(0)
	v_mul_f32_e32 v22, v21, v219
	v_fma_f32 v194, v20, v218, -v22
	v_mul_f32_e32 v22, v20, v219
	v_fma_f32 v21, v21, v218, v22
	v_mov_b32_e32 v195, v21
	v_pk_add_f32 v[22:23], v[70:71], 0 op_sel_hi:[1,0]
	s_waitcnt lgkmcnt(0)
	v_mul_f32_e32 v20, v19, v221
	v_fma_f32 v196, v18, v220, -v20
	v_mul_f32_e32 v20, v18, v221
	v_fma_f32 v19, v19, v220, v20
	ds_write2st64_b64 v115, v[16:17], v[96:97] offset1:9
	v_mov_b32_e32 v197, v19
	v_pk_add_f32 v[16:17], v[76:77], 0 op_sel_hi:[1,0]
	v_pk_add_f32 v[20:21], v[72:73], 0 op_sel_hi:[1,0]
	s_waitcnt lgkmcnt(0)
	v_mul_f32_e32 v18, v89, v223
	v_fma_f32 v198, v88, v222, -v18
	v_mul_f32_e32 v18, v88, v223
	v_fma_f32 v199, v89, v222, v18
	v_pk_add_f32 v[18:19], v[74:75], 0 op_sel_hi:[1,0]
	v_pk_add_f32 v[92:93], v[16:17], v[20:21]
	v_pk_add_f32 v[20:21], v[16:17], v[20:21] neg_lo:[0,1] neg_hi:[0,1]
	v_pk_add_f32 v[94:95], v[18:19], v[22:23]
	v_pk_add_f32 v[16:17], v[18:19], v[22:23] neg_lo:[0,1] neg_hi:[0,1]
	v_xor_b32_e32 v89, 0x80000000, v72
	v_mov_b32_e32 v88, v73
	v_xor_b32_e32 v19, 0x80000000, v16
	v_mov_b32_e32 v18, v17
	v_pk_add_f32 v[16:17], v[92:93], v[94:95]
	v_pk_add_f32 v[22:23], v[92:93], v[94:95] neg_lo:[0,1] neg_hi:[0,1]
	v_pk_fma_f32 v[94:95], v[86:87], s[20:21], v[90:91] op_sel_hi:[1,0,1]
	v_pk_fma_f32 v[86:87], v[86:87], s[20:21], v[90:91] op_sel_hi:[1,0,1] neg_lo:[0,0,1] neg_hi:[0,0,1]
	ds_write2st64_b64 v115, v[98:99], v[100:101] offset0:18 offset1:27
	ds_write2st64_b64 v115, v[102:103], v[194:195] offset0:36 offset1:45
	ds_write2st64_b64 v115, v[196:197], v[198:199] offset0:54 offset1:63
	v_pk_add_f32 v[92:93], v[20:21], v[18:19]
	v_pk_add_f32 v[18:19], v[20:21], v[18:19] neg_lo:[0,1] neg_hi:[0,1]
	v_pk_add_f32 v[20:21], v[76:77], v[88:89]
	v_pk_add_f32 v[88:89], v[76:77], v[88:89] neg_lo:[0,1] neg_hi:[0,1]
	v_xor_b32_e32 v91, 0x80000000, v86
	v_mov_b32_e32 v90, v87
	v_pk_add_f32 v[86:87], v[20:21], v[94:95]
	v_pk_add_f32 v[20:21], v[20:21], v[94:95] neg_lo:[0,1] neg_hi:[0,1]
	v_pk_add_f32 v[94:95], v[88:89], v[90:91]
	v_pk_add_f32 v[88:89], v[88:89], v[90:91] neg_lo:[0,1] neg_hi:[0,1]
	s_waitcnt lgkmcnt(0)
	v_mul_f32_e32 v96, v87, v211
	v_mul_f32_e32 v98, v86, v211
	v_fma_f32 v96, v86, v210, -v96
	v_fma_f32 v87, v87, v210, v98
	v_mov_b32_e32 v97, v87
	s_waitcnt lgkmcnt(0)
	v_mul_f32_e32 v86, v93, v213
	v_fma_f32 v98, v92, v212, -v86
	v_mul_f32_e32 v86, v92, v213
	v_fma_f32 v99, v93, v212, v86
	s_waitcnt lgkmcnt(0)
	v_mul_f32_e32 v86, v95, v215
	v_fma_f32 v100, v94, v214, -v86
	v_mul_f32_e32 v86, v94, v215
	v_fma_f32 v101, v95, v214, v86
	s_waitcnt lgkmcnt(0)
	v_mul_f32_e32 v86, v23, v217
	v_fma_f32 v102, v22, v216, -v86
	v_mul_f32_e32 v86, v22, v217
	v_fma_f32 v23, v23, v216, v86
	v_mov_b32_e32 v103, v23
	s_waitcnt lgkmcnt(0)
	v_mul_f32_e32 v22, v21, v219
	v_fma_f32 v194, v20, v218, -v22
	v_mul_f32_e32 v22, v20, v219
	v_fma_f32 v21, v21, v218, v22
	v_mov_b32_e32 v195, v21
	s_waitcnt lgkmcnt(0)
	v_mul_f32_e32 v20, v19, v221
	v_fma_f32 v196, v18, v220, -v20
	v_mul_f32_e32 v20, v18, v221
	v_fma_f32 v19, v19, v220, v20
	v_mov_b64_e32 v[94:95], v[222:223]
	v_mov_b32_e32 v197, v19
	ds_write2st64_b64 v115, v[16:17], v[96:97] offset0:72 offset1:81
	ds_write2st64_b64 v115, v[98:99], v[100:101] offset0:90 offset1:99
	ds_write2st64_b64 v115, v[102:103], v[194:195] offset0:108 offset1:117
	s_waitcnt lgkmcnt(0)
	v_mul_f32_e32 v18, v89, v95
	v_fma_f32 v198, v88, v94, -v18
	v_mul_f32_e32 v18, v88, v95
	v_fma_f32 v199, v89, v94, v18
	ds_write_b64 v115, v[196:197] offset:64512
	ds_write_b64 v116, v[198:199] offset:32256
	s_waitcnt lgkmcnt(0)
	s_barrier
; __device__ __forceinline__ c2 cmul(c2 a, c2 b) { return (c2){a.x * b.x - a.y * b.y, a.x * b.y + a.y * b.x}; }
; __device__ __forceinline__ c2 mni(c2 a) { return (c2){a.y, -a.x}; }
; __device__ __forceinline__ void dft8(c2 (&x)[8]) {
;     const float s = 0.70710678118654752f;
;     const c2 a0 = x[0] + x[4], a4 = x[0] - x[4], a1 = x[1] + x[5], a5 = x[1] - x[5], a2 = x[2] + x[6], a6 = x[2] - x[6], a3 = x[3] + x[7], a7 = x[3] - x[7];
;     const c2 a5w = (c2){(a5.x + a5.y) * s, (a5.y - a5.x) * s};
;     const c2 a6w = mni(a6);
;     const c2 a7w = (c2){(a7.y - a7.x) * s, -(a7.x + a7.y) * s};
;     const c2 b0 = a0 + a2, b1 = a0 - a2, b2 = a1 + a3, b3 = mni(a1 - a3);
;     x[0] = b0 + b2; x[4] = b0 - b2; x[2] = b1 + b3; x[6] = b1 - b3;
;     const c2 c0 = a4 + a6w, c1 = a4 - a6w, c2_ = a5w + a7w, c3 = mni(a5w - a7w);
;     x[1] = c0 + c2_; x[5] = c0 - c2_; x[3] = c1 + c3; x[7] = c1 - c3;
; }
; template <int S> __device__ __forceinline__ void fwd_mid(c2* buf, const c2* tws, int tid) {
;     constexpr int lq = 9 - 3 * S, Q = 1 << lq; const c2* T = tws + (S == 1 ? 3584 : 4032);
;     const int k = tid & (Q - 1), base = ((tid >> lq) << (lq + 3)) + k;
;     c2 x[8];
;     c2* bp_ = buf + LP(base); constexpr int QP = Q + Q / 8;
; #pragma unroll
;     for (int r = 0; r < 8; ++r) x[r] = bp_[r * QP];
;     dft8(x);
; #pragma unroll
;     for (int q = 1; q < 8; ++q) x[q] = cmul(x[q], T[(q - 1) * Q + k]);
; #pragma unroll
;     for (int q = 0; q < 8; ++q) bp_[q * QP] = x[q];
; }
	ds_read2_b64 v[16:19], v117 offset1:72
	ds_read2_b64 v[20:23], v117 offset0:144 offset1:216
	ds_read2_b64 v[86:89], v56 offset0:32 offset1:104
	ds_read2_b64 v[90:93], v56 offset0:176 offset1:248
	s_waitcnt lgkmcnt(0)
	v_pk_add_f32 v[94:95], v[16:17], v[86:87]
	v_pk_add_f32 v[16:17], v[16:17], v[86:87] neg_lo:[0,1] neg_hi:[0,1]
	v_pk_add_f32 v[86:87], v[18:19], v[88:89]
	v_pk_add_f32 v[18:19], v[18:19], v[88:89] neg_lo:[0,1] neg_hi:[0,1]
	s_waitcnt lgkmcnt(0)
	v_pk_add_f32 v[88:89], v[20:21], v[90:91]
	v_pk_add_f32 v[20:21], v[20:21], v[90:91] neg_lo:[0,1] neg_hi:[0,1]
	v_pk_add_f32 v[90:91], v[22:23], v[92:93]
	v_pk_add_f32 v[22:23], v[22:23], v[92:93] neg_lo:[0,1] neg_hi:[0,1]
	v_pk_add_f32 v[92:93], v[18:19], v[18:19] op_sel:[1,0]
	v_pk_add_f32 v[18:19], v[18:19], v[18:19] op_sel_hi:[1,0] neg_lo:[0,1] neg_hi:[0,1]
	s_nop 0
	v_mov_b32_e32 v93, v19
	v_xor_b32_e32 v19, 0x80000000, v20
	v_mov_b32_e32 v18, v21
	v_pk_add_f32 v[20:21], v[22:23], v[22:23] op_sel:[1,0] neg_lo:[0,1] neg_hi:[0,1]
	v_pk_add_f32 v[22:23], v[22:23], v[22:23] op_sel_hi:[1,0]
	s_nop 0
	v_mov_b32_e32 v21, v23
	v_pk_add_f32 v[22:23], v[94:95], v[88:89]
	v_pk_add_f32 v[88:89], v[94:95], v[88:89] neg_lo:[0,1] neg_hi:[0,1]
	v_pk_add_f32 v[94:95], v[86:87], v[90:91]
	v_pk_add_f32 v[86:87], v[86:87], v[90:91] neg_lo:[0,1] neg_hi:[0,1]
	v_pk_mul_f32 v[20:21], v[20:21], s[20:21]
	v_xor_b32_e32 v91, 0x80000000, v86
	v_mov_b32_e32 v90, v87
	v_pk_add_f32 v[86:87], v[22:23], v[94:95]
	v_pk_add_f32 v[22:23], v[22:23], v[94:95] neg_lo:[0,1] neg_hi:[0,1]
	v_pk_add_f32 v[94:95], v[88:89], v[90:91]
	v_pk_add_f32 v[88:89], v[88:89], v[90:91] neg_lo:[0,1] neg_hi:[0,1]
	v_pk_add_f32 v[90:91], v[16:17], v[18:19]
	v_pk_add_f32 v[16:17], v[16:17], v[18:19] neg_lo:[0,1] neg_hi:[0,1]
	v_pk_fma_f32 v[18:19], v[92:93], s[20:21], v[20:21] op_sel_hi:[1,0,1]
	v_pk_fma_f32 v[20:21], v[92:93], s[20:21], v[20:21] op_sel_hi:[1,0,1] neg_lo:[0,0,1] neg_hi:[0,0,1]
	s_nop 0
	v_xor_b32_e32 v93, 0x80000000, v20
	v_mov_b32_e32 v92, v21
	v_pk_add_f32 v[20:21], v[90:91], v[18:19]
	v_pk_add_f32 v[18:19], v[90:91], v[18:19] neg_lo:[0,1] neg_hi:[0,1]
	v_pk_add_f32 v[90:91], v[16:17], v[92:93]
	v_pk_add_f32 v[16:17], v[16:17], v[92:93] neg_lo:[0,1] neg_hi:[0,1]
	s_waitcnt lgkmcnt(0)
	v_pk_mul_f32 v[96:97], v[224:225], v[20:21] op_sel:[1,1] op_sel_hi:[0,1]
	v_fma_f32 v98, v224, v20, -v96
	v_fma_f32 v99, v225, v20, v97
	s_nop 0
	s_waitcnt lgkmcnt(0)
	v_pk_mul_f32 v[92:93], v[226:227], v[94:95] op_sel:[1,1] op_sel_hi:[0,1]
	v_fma_f32 v96, v226, v94, -v92
	v_fma_f32 v97, v227, v94, v93
	s_nop 0
	s_waitcnt lgkmcnt(0)
	v_pk_mul_f32 v[92:93], v[228:229], v[90:91] op_sel:[1,1] op_sel_hi:[0,1]
	v_fma_f32 v94, v228, v90, -v92
	v_fma_f32 v95, v229, v90, v93
	s_nop 0
	s_waitcnt lgkmcnt(0)
	v_pk_mul_f32 v[90:91], v[22:23], v[230:231] op_sel:[1,1] op_sel_hi:[1,0]
	s_nop 0
	v_fma_f32 v92, v22, v230, -v90
	v_fma_f32 v93, v22, v231, v91
	s_waitcnt lgkmcnt(0)
	v_pk_mul_f32 v[22:23], v[232:233], v[18:19] op_sel:[1,1] op_sel_hi:[0,1]
	v_fma_f32 v90, v232, v18, -v22
	v_fma_f32 v91, v233, v18, v23
	s_nop 0
	s_waitcnt lgkmcnt(0)
	v_pk_mul_f32 v[20:21], v[88:89], v[234:235] op_sel:[1,1] op_sel_hi:[1,0]
	s_nop 0
	v_fma_f32 v22, v88, v234, -v20
	v_fma_f32 v23, v88, v235, v21
	v_mov_b64_e32 v[18:19], v[236:237]
	s_waitcnt lgkmcnt(0)
	v_pk_mul_f32 v[20:21], v[18:19], v[16:17] op_sel:[1,1] op_sel_hi:[0,1]
	v_fma_f32 v88, v18, v16, -v20
	v_fma_f32 v89, v19, v16, v21
	s_nop 0
	ds_write2_b64 v117, v[86:87], v[98:99] offset1:72
	ds_write2_b64 v117, v[96:97], v[94:95] offset0:144 offset1:216
	ds_write2_b64 v56, v[92:93], v[90:91] offset0:32 offset1:104
	ds_write2_b64 v56, v[22:23], v[88:89] offset0:176 offset1:248
	ds_read2_b64 v[16:19], v191 offset1:72
	ds_read2_b64 v[20:23], v191 offset0:144 offset1:216
	ds_read2_b64 v[86:89], v192 offset0:32 offset1:104
	ds_read2_b64 v[90:93], v192 offset0:176 offset1:248
	s_waitcnt lgkmcnt(0)
	v_pk_add_f32 v[94:95], v[16:17], v[86:87]
	v_pk_add_f32 v[16:17], v[16:17], v[86:87] neg_lo:[0,1] neg_hi:[0,1]
	v_pk_add_f32 v[86:87], v[18:19], v[88:89]
	v_pk_add_f32 v[18:19], v[18:19], v[88:89] neg_lo:[0,1] neg_hi:[0,1]
	s_waitcnt lgkmcnt(0)
	v_pk_add_f32 v[88:89], v[20:21], v[90:91]
	v_pk_add_f32 v[20:21], v[20:21], v[90:91] neg_lo:[0,1] neg_hi:[0,1]
	v_pk_add_f32 v[90:91], v[22:23], v[92:93]
	v_pk_add_f32 v[22:23], v[22:23], v[92:93] neg_lo:[0,1] neg_hi:[0,1]
	v_pk_add_f32 v[92:93], v[18:19], v[18:19] op_sel:[1,0]
	v_pk_add_f32 v[18:19], v[18:19], v[18:19] op_sel_hi:[1,0] neg_lo:[0,1] neg_hi:[0,1]
	s_nop 0
	v_mov_b32_e32 v93, v19
	v_xor_b32_e32 v19, 0x80000000, v20
	v_mov_b32_e32 v18, v21
	v_pk_add_f32 v[20:21], v[22:23], v[22:23] op_sel:[1,0] neg_lo:[0,1] neg_hi:[0,1]
	v_pk_add_f32 v[22:23], v[22:23], v[22:23] op_sel_hi:[1,0]
	s_nop 0
	v_mov_b32_e32 v21, v23
	v_pk_add_f32 v[22:23], v[94:95], v[88:89]
	v_pk_add_f32 v[88:89], v[94:95], v[88:89] neg_lo:[0,1] neg_hi:[0,1]
	v_pk_add_f32 v[94:95], v[86:87], v[90:91]
	v_pk_add_f32 v[86:87], v[86:87], v[90:91] neg_lo:[0,1] neg_hi:[0,1]
	v_pk_mul_f32 v[20:21], v[20:21], s[20:21]
	v_xor_b32_e32 v91, 0x80000000, v86
	v_mov_b32_e32 v90, v87
	v_pk_add_f32 v[86:87], v[22:23], v[94:95]
	v_pk_add_f32 v[22:23], v[22:23], v[94:95] neg_lo:[0,1] neg_hi:[0,1]
	v_pk_add_f32 v[94:95], v[88:89], v[90:91]
	v_pk_add_f32 v[88:89], v[88:89], v[90:91] neg_lo:[0,1] neg_hi:[0,1]
	v_pk_add_f32 v[90:91], v[16:17], v[18:19]
	v_pk_add_f32 v[16:17], v[16:17], v[18:19] neg_lo:[0,1] neg_hi:[0,1]
	v_pk_fma_f32 v[18:19], v[92:93], s[20:21], v[20:21] op_sel_hi:[1,0,1]
	v_pk_fma_f32 v[20:21], v[92:93], s[20:21], v[20:21] op_sel_hi:[1,0,1] neg_lo:[0,0,1] neg_hi:[0,0,1]
	s_nop 0
	v_xor_b32_e32 v93, 0x80000000, v20
	v_mov_b32_e32 v92, v21
	v_pk_add_f32 v[20:21], v[90:91], v[18:19]
	v_pk_add_f32 v[18:19], v[90:91], v[18:19] neg_lo:[0,1] neg_hi:[0,1]
	v_pk_add_f32 v[90:91], v[16:17], v[92:93]
	v_pk_add_f32 v[16:17], v[16:17], v[92:93] neg_lo:[0,1] neg_hi:[0,1]
	s_waitcnt lgkmcnt(0)
; __device__ __forceinline__ c2 cmul(c2 a, c2 b) { return (c2){a.x * b.x - a.y * b.y, a.x * b.y + a.y * b.x}; }
; __device__ __forceinline__ c2 mni(c2 a) { return (c2){a.y, -a.x}; }
; __device__ __forceinline__ void dft8(c2 (&x)[8]) {
;     const float s = 0.70710678118654752f;
;     const c2 a0 = x[0] + x[4], a4 = x[0] - x[4], a1 = x[1] + x[5], a5 = x[1] - x[5], a2 = x[2] + x[6], a6 = x[2] - x[6], a3 = x[3] + x[7], a7 = x[3] - x[7];
;     const c2 a5w = (c2){(a5.x + a5.y) * s, (a5.y - a5.x) * s};
;     const c2 a6w = mni(a6);
;     const c2 a7w = (c2){(a7.y - a7.x) * s, -(a7.x + a7.y) * s};
;     const c2 b0 = a0 + a2, b1 = a0 - a2, b2 = a1 + a3, b3 = mni(a1 - a3);
;     x[0] = b0 + b2; x[4] = b0 - b2; x[2] = b1 + b3; x[6] = b1 - b3;
;     const c2 c0 = a4 + a6w, c1 = a4 - a6w, c2_ = a5w + a7w, c3 = mni(a5w - a7w);
;     x[1] = c0 + c2_; x[5] = c0 - c2_; x[3] = c1 + c3; x[7] = c1 - c3;
; }
; template <int S> __device__ __forceinline__ void fwd_mid(c2* buf, const c2* tws, int tid) {
;     constexpr int lq = 9 - 3 * S, Q = 1 << lq; const c2* T = tws + (S == 1 ? 3584 : 4032);
;     const int k = tid & (Q - 1), base = ((tid >> lq) << (lq + 3)) + k;
;     c2 x[8];
;     c2* bp_ = buf + LP(base); constexpr int QP = Q + Q / 8;
; #pragma unroll
;     for (int r = 0; r < 8; ++r) x[r] = bp_[r * QP];
;     dft8(x);
; #pragma unroll
;     for (int q = 1; q < 8; ++q) x[q] = cmul(x[q], T[(q - 1) * Q + k]);
; #pragma unroll
;     for (int q = 0; q < 8; ++q) bp_[q * QP] = x[q];
; }
	v_pk_mul_f32 v[96:97], v[224:225], v[20:21] op_sel:[1,1] op_sel_hi:[0,1]
	v_fma_f32 v98, v224, v20, -v96
	v_fma_f32 v99, v225, v20, v97
	s_nop 0
	s_waitcnt lgkmcnt(0)
	v_pk_mul_f32 v[92:93], v[226:227], v[94:95] op_sel:[1,1] op_sel_hi:[0,1]
	v_fma_f32 v96, v226, v94, -v92
	v_fma_f32 v97, v227, v94, v93
	s_nop 0
	s_waitcnt lgkmcnt(0)
	v_pk_mul_f32 v[92:93], v[228:229], v[90:91] op_sel:[1,1] op_sel_hi:[0,1]
	v_fma_f32 v94, v228, v90, -v92
	v_fma_f32 v95, v229, v90, v93
	s_nop 0
	s_waitcnt lgkmcnt(0)
	v_pk_mul_f32 v[90:91], v[22:23], v[230:231] op_sel:[1,1] op_sel_hi:[1,0]
	s_nop 0
	v_fma_f32 v92, v22, v230, -v90
	v_fma_f32 v93, v22, v231, v91
	s_waitcnt lgkmcnt(0)
	v_pk_mul_f32 v[22:23], v[232:233], v[18:19] op_sel:[1,1] op_sel_hi:[0,1]
	v_fma_f32 v90, v232, v18, -v22
	v_fma_f32 v91, v233, v18, v23
	s_nop 0
	s_waitcnt lgkmcnt(0)
	v_pk_mul_f32 v[20:21], v[88:89], v[234:235] op_sel:[1,1] op_sel_hi:[1,0]
	s_nop 0
	v_fma_f32 v22, v88, v234, -v20
	v_fma_f32 v23, v88, v235, v21
	v_mov_b64_e32 v[18:19], v[236:237]
	s_waitcnt lgkmcnt(0)
	v_pk_mul_f32 v[20:21], v[18:19], v[16:17] op_sel:[1,1] op_sel_hi:[0,1]
	v_fma_f32 v88, v18, v16, -v20
	v_fma_f32 v89, v19, v16, v21
	s_nop 0
	ds_write2_b64 v191, v[86:87], v[98:99] offset1:72
	ds_write2_b64 v191, v[96:97], v[94:95] offset0:144 offset1:216
	ds_write2_b64 v192, v[92:93], v[90:91] offset0:32 offset1:104
	ds_write2_b64 v192, v[22:23], v[88:89] offset0:176 offset1:248
	s_waitcnt lgkmcnt(0)
	s_barrier
	ds_read2_b64 v[16:19], v119 offset1:9
	ds_read2_b64 v[20:23], v119 offset0:18 offset1:27
	ds_read2_b64 v[86:89], v119 offset0:36 offset1:45
	ds_read2_b64 v[90:93], v119 offset0:54 offset1:63
	s_waitcnt lgkmcnt(0)
	v_pk_add_f32 v[94:95], v[16:17], v[86:87]
	v_pk_add_f32 v[16:17], v[16:17], v[86:87] neg_lo:[0,1] neg_hi:[0,1]
	v_pk_add_f32 v[86:87], v[18:19], v[88:89]
	v_pk_add_f32 v[18:19], v[18:19], v[88:89] neg_lo:[0,1] neg_hi:[0,1]
	s_waitcnt lgkmcnt(0)
	v_pk_add_f32 v[88:89], v[20:21], v[90:91]
	v_pk_add_f32 v[20:21], v[20:21], v[90:91] neg_lo:[0,1] neg_hi:[0,1]
	v_pk_add_f32 v[90:91], v[22:23], v[92:93]
	v_pk_add_f32 v[22:23], v[22:23], v[92:93] neg_lo:[0,1] neg_hi:[0,1]
	v_pk_add_f32 v[92:93], v[18:19], v[18:19] op_sel:[1,0]
	v_pk_add_f32 v[18:19], v[18:19], v[18:19] op_sel_hi:[1,0] neg_lo:[0,1] neg_hi:[0,1]
	s_nop 0
	v_mov_b32_e32 v93, v19
	v_xor_b32_e32 v19, 0x80000000, v20
	v_mov_b32_e32 v18, v21
	v_pk_add_f32 v[20:21], v[22:23], v[22:23] op_sel:[1,0] neg_lo:[0,1] neg_hi:[0,1]
	v_pk_add_f32 v[22:23], v[22:23], v[22:23] op_sel_hi:[1,0]
	s_nop 0
	v_mov_b32_e32 v21, v23
	v_pk_add_f32 v[22:23], v[94:95], v[88:89]
	v_pk_add_f32 v[88:89], v[94:95], v[88:89] neg_lo:[0,1] neg_hi:[0,1]
	v_pk_add_f32 v[94:95], v[86:87], v[90:91]
	v_pk_add_f32 v[86:87], v[86:87], v[90:91] neg_lo:[0,1] neg_hi:[0,1]
	v_pk_mul_f32 v[20:21], v[20:21], s[20:21]
	v_xor_b32_e32 v91, 0x80000000, v86
	v_mov_b32_e32 v90, v87
	v_pk_add_f32 v[86:87], v[22:23], v[94:95]
	v_pk_add_f32 v[22:23], v[22:23], v[94:95] neg_lo:[0,1] neg_hi:[0,1]
	v_pk_add_f32 v[94:95], v[88:89], v[90:91]
	v_pk_add_f32 v[88:89], v[88:89], v[90:91] neg_lo:[0,1] neg_hi:[0,1]
	v_pk_add_f32 v[90:91], v[16:17], v[18:19]
	v_pk_add_f32 v[16:17], v[16:17], v[18:19] neg_lo:[0,1] neg_hi:[0,1]
	v_pk_fma_f32 v[18:19], v[92:93], s[20:21], v[20:21] op_sel_hi:[1,0,1]
	v_pk_fma_f32 v[20:21], v[92:93], s[20:21], v[20:21] op_sel_hi:[1,0,1] neg_lo:[0,0,1] neg_hi:[0,0,1]
	s_nop 0
	v_xor_b32_e32 v93, 0x80000000, v20
	v_mov_b32_e32 v92, v21
	v_pk_add_f32 v[20:21], v[90:91], v[18:19]
	v_pk_add_f32 v[18:19], v[90:91], v[18:19] neg_lo:[0,1] neg_hi:[0,1]
	v_pk_add_f32 v[90:91], v[16:17], v[92:93]
	v_pk_add_f32 v[16:17], v[16:17], v[92:93] neg_lo:[0,1] neg_hi:[0,1]
	s_waitcnt lgkmcnt(0)
	v_pk_mul_f32 v[96:97], v[238:239], v[20:21] op_sel:[1,1] op_sel_hi:[0,1]
	v_fma_f32 v98, v238, v20, -v96
	v_fma_f32 v99, v239, v20, v97
	s_nop 0
	s_waitcnt lgkmcnt(0)
	v_pk_mul_f32 v[92:93], v[240:241], v[94:95] op_sel:[1,1] op_sel_hi:[0,1]
	v_fma_f32 v96, v240, v94, -v92
	v_fma_f32 v97, v241, v94, v93
	s_nop 0
	s_waitcnt lgkmcnt(0)
	v_pk_mul_f32 v[92:93], v[242:243], v[90:91] op_sel:[1,1] op_sel_hi:[0,1]
	v_fma_f32 v94, v242, v90, -v92
	v_fma_f32 v95, v243, v90, v93
	s_nop 0
	s_waitcnt lgkmcnt(0)
	v_pk_mul_f32 v[90:91], v[22:23], v[244:245] op_sel:[1,1] op_sel_hi:[1,0]
	s_nop 0
	v_fma_f32 v92, v22, v244, -v90
	v_fma_f32 v93, v22, v245, v91
	s_waitcnt lgkmcnt(0)
	v_pk_mul_f32 v[22:23], v[246:247], v[18:19] op_sel:[1,1] op_sel_hi:[0,1]
	v_fma_f32 v90, v246, v18, -v22
	v_fma_f32 v91, v247, v18, v23
	s_nop 0
	s_waitcnt lgkmcnt(0)
	v_pk_mul_f32 v[20:21], v[88:89], v[248:249] op_sel:[1,1] op_sel_hi:[1,0]
	s_nop 0
	v_fma_f32 v22, v88, v248, -v20
	v_fma_f32 v23, v88, v249, v21
	v_mov_b64_e32 v[18:19], v[250:251]
	s_waitcnt lgkmcnt(0)
	v_pk_mul_f32 v[20:21], v[18:19], v[16:17] op_sel:[1,1] op_sel_hi:[0,1]
	v_fma_f32 v88, v18, v16, -v20
	v_fma_f32 v89, v19, v16, v21
	s_nop 0
	ds_write2_b64 v119, v[86:87], v[98:99] offset1:9
	ds_write2_b64 v119, v[96:97], v[94:95] offset0:18 offset1:27
	ds_write2_b64 v119, v[92:93], v[90:91] offset0:36 offset1:45
	ds_write2_b64 v119, v[22:23], v[88:89] offset0:54 offset1:63
	ds_read2_b64 v[16:19], v193 offset1:9
	ds_read2_b64 v[20:23], v193 offset0:18 offset1:27
	ds_read2_b64 v[86:89], v193 offset0:36 offset1:45
	ds_read2_b64 v[90:93], v193 offset0:54 offset1:63
	s_waitcnt lgkmcnt(0)
	v_pk_add_f32 v[94:95], v[16:17], v[86:87]
	v_pk_add_f32 v[16:17], v[16:17], v[86:87] neg_lo:[0,1] neg_hi:[0,1]
	v_pk_add_f32 v[86:87], v[18:19], v[88:89]
	v_pk_add_f32 v[18:19], v[18:19], v[88:89] neg_lo:[0,1] neg_hi:[0,1]
	s_waitcnt lgkmcnt(0)
; __device__ __forceinline__ c2 cmul(c2 a, c2 b) { return (c2){a.x * b.x - a.y * b.y, a.x * b.y + a.y * b.x}; }
; __device__ __forceinline__ c2 mni(c2 a) { return (c2){a.y, -a.x}; }
; __device__ __forceinline__ void dft8(c2 (&x)[8]) {
;     const float s = 0.70710678118654752f;
;     const c2 a0 = x[0] + x[4], a4 = x[0] - x[4], a1 = x[1] + x[5], a5 = x[1] - x[5], a2 = x[2] + x[6], a6 = x[2] - x[6], a3 = x[3] + x[7], a7 = x[3] - x[7];
;     const c2 a5w = (c2){(a5.x + a5.y) * s, (a5.y - a5.x) * s};
;     const c2 a6w = mni(a6);
;     const c2 a7w = (c2){(a7.y - a7.x) * s, -(a7.x + a7.y) * s};
;     const c2 b0 = a0 + a2, b1 = a0 - a2, b2 = a1 + a3, b3 = mni(a1 - a3);
;     x[0] = b0 + b2; x[4] = b0 - b2; x[2] = b1 + b3; x[6] = b1 - b3;
;     const c2 c0 = a4 + a6w, c1 = a4 - a6w, c2_ = a5w + a7w, c3 = mni(a5w - a7w);
;     x[1] = c0 + c2_; x[5] = c0 - c2_; x[3] = c1 + c3; x[7] = c1 - c3;
; }
; template <int S> __device__ __forceinline__ void fwd_mid(c2* buf, const c2* tws, int tid) {
;     constexpr int lq = 9 - 3 * S, Q = 1 << lq; const c2* T = tws + (S == 1 ? 3584 : 4032);
;     const int k = tid & (Q - 1), base = ((tid >> lq) << (lq + 3)) + k;
;     c2 x[8];
;     c2* bp_ = buf + LP(base); constexpr int QP = Q + Q / 8;
; #pragma unroll
;     for (int r = 0; r < 8; ++r) x[r] = bp_[r * QP];
;     dft8(x);
; #pragma unroll
;     for (int q = 1; q < 8; ++q) x[q] = cmul(x[q], T[(q - 1) * Q + k]);
; #pragma unroll
;     for (int q = 0; q < 8; ++q) bp_[q * QP] = x[q];
; }
; __device__ __forceinline__ void fwd_s3(c2 (&x)[8], const c2* buf, int tid) {
; #pragma unroll
;     for (int r = 0; r < 8; ++r) x[r] = buf[9 * tid + r];
;     dft8(x);
; }
	v_pk_add_f32 v[88:89], v[20:21], v[90:91]
	v_pk_add_f32 v[20:21], v[20:21], v[90:91] neg_lo:[0,1] neg_hi:[0,1]
	v_pk_add_f32 v[90:91], v[22:23], v[92:93]
	v_pk_add_f32 v[22:23], v[22:23], v[92:93] neg_lo:[0,1] neg_hi:[0,1]
	v_pk_add_f32 v[92:93], v[18:19], v[18:19] op_sel:[1,0]
	v_pk_add_f32 v[18:19], v[18:19], v[18:19] op_sel_hi:[1,0] neg_lo:[0,1] neg_hi:[0,1]
	s_nop 0
	v_mov_b32_e32 v93, v19
	v_xor_b32_e32 v19, 0x80000000, v20
	v_mov_b32_e32 v18, v21
	v_pk_add_f32 v[20:21], v[22:23], v[22:23] op_sel:[1,0] neg_lo:[0,1] neg_hi:[0,1]
	v_pk_add_f32 v[22:23], v[22:23], v[22:23] op_sel_hi:[1,0]
	s_nop 0
	v_mov_b32_e32 v21, v23
	v_pk_add_f32 v[22:23], v[94:95], v[88:89]
	v_pk_add_f32 v[88:89], v[94:95], v[88:89] neg_lo:[0,1] neg_hi:[0,1]
	v_pk_add_f32 v[94:95], v[86:87], v[90:91]
	v_pk_add_f32 v[86:87], v[86:87], v[90:91] neg_lo:[0,1] neg_hi:[0,1]
	v_pk_mul_f32 v[20:21], v[20:21], s[20:21]
	v_xor_b32_e32 v91, 0x80000000, v86
	v_mov_b32_e32 v90, v87
	v_pk_add_f32 v[86:87], v[22:23], v[94:95]
	v_pk_add_f32 v[22:23], v[22:23], v[94:95] neg_lo:[0,1] neg_hi:[0,1]
	v_pk_add_f32 v[94:95], v[88:89], v[90:91]
	v_pk_add_f32 v[88:89], v[88:89], v[90:91] neg_lo:[0,1] neg_hi:[0,1]
	v_pk_add_f32 v[90:91], v[16:17], v[18:19]
	v_pk_add_f32 v[16:17], v[16:17], v[18:19] neg_lo:[0,1] neg_hi:[0,1]
	v_pk_fma_f32 v[18:19], v[92:93], s[20:21], v[20:21] op_sel_hi:[1,0,1]
	v_pk_fma_f32 v[20:21], v[92:93], s[20:21], v[20:21] op_sel_hi:[1,0,1] neg_lo:[0,0,1] neg_hi:[0,0,1]
	s_nop 0
	v_xor_b32_e32 v93, 0x80000000, v20
	v_mov_b32_e32 v92, v21
	v_pk_add_f32 v[20:21], v[90:91], v[18:19]
	v_pk_add_f32 v[18:19], v[90:91], v[18:19] neg_lo:[0,1] neg_hi:[0,1]
	v_pk_add_f32 v[90:91], v[16:17], v[92:93]
	v_pk_add_f32 v[16:17], v[16:17], v[92:93] neg_lo:[0,1] neg_hi:[0,1]
	s_waitcnt lgkmcnt(0)
	v_pk_mul_f32 v[96:97], v[238:239], v[20:21] op_sel:[1,1] op_sel_hi:[0,1]
	v_fma_f32 v98, v238, v20, -v96
	v_fma_f32 v99, v239, v20, v97
	s_nop 0
	s_waitcnt lgkmcnt(0)
	v_pk_mul_f32 v[92:93], v[240:241], v[94:95] op_sel:[1,1] op_sel_hi:[0,1]
	v_fma_f32 v96, v240, v94, -v92
	v_fma_f32 v97, v241, v94, v93
	s_nop 0
	s_waitcnt lgkmcnt(0)
	v_pk_mul_f32 v[92:93], v[242:243], v[90:91] op_sel:[1,1] op_sel_hi:[0,1]
	v_fma_f32 v94, v242, v90, -v92
	v_fma_f32 v95, v243, v90, v93
	s_nop 0
	s_waitcnt lgkmcnt(0)
	v_pk_mul_f32 v[90:91], v[22:23], v[244:245] op_sel:[1,1] op_sel_hi:[1,0]
	s_nop 0
	v_fma_f32 v92, v22, v244, -v90
	v_fma_f32 v93, v22, v245, v91
	s_waitcnt lgkmcnt(0)
	v_pk_mul_f32 v[22:23], v[246:247], v[18:19] op_sel:[1,1] op_sel_hi:[0,1]
	v_fma_f32 v90, v246, v18, -v22
	v_fma_f32 v91, v247, v18, v23
	s_nop 0
	s_waitcnt lgkmcnt(0)
	v_pk_mul_f32 v[20:21], v[88:89], v[248:249] op_sel:[1,1] op_sel_hi:[1,0]
	s_nop 0
	v_fma_f32 v22, v88, v248, -v20
	v_fma_f32 v23, v88, v249, v21
	v_mov_b64_e32 v[18:19], v[250:251]
	s_waitcnt lgkmcnt(0)
	v_pk_mul_f32 v[20:21], v[18:19], v[16:17] op_sel:[1,1] op_sel_hi:[0,1]
	v_fma_f32 v88, v18, v16, -v20
	v_fma_f32 v89, v19, v16, v21
	s_nop 0
	ds_write2_b64 v193, v[86:87], v[98:99] offset1:9
	ds_write2_b64 v193, v[96:97], v[94:95] offset0:18 offset1:27
	ds_write2_b64 v193, v[92:93], v[90:91] offset0:36 offset1:45
	ds_write2_b64 v193, v[22:23], v[88:89] offset0:54 offset1:63
	s_waitcnt lgkmcnt(0)
	s_barrier
	ds_read2_b64 v[16:19], v121 offset1:1
	ds_read2_b64 v[20:23], v121 offset0:2 offset1:3
	ds_read2_b64 v[86:89], v121 offset0:4 offset1:5
	ds_read2_b64 v[90:93], v121 offset0:6 offset1:7
	s_waitcnt lgkmcnt(0)
	v_pk_add_f32 v[94:95], v[16:17], v[86:87]
	v_pk_add_f32 v[16:17], v[16:17], v[86:87] neg_lo:[0,1] neg_hi:[0,1]
	v_pk_add_f32 v[86:87], v[18:19], v[88:89]
	v_pk_add_f32 v[18:19], v[18:19], v[88:89] neg_lo:[0,1] neg_hi:[0,1]
	s_waitcnt lgkmcnt(0)
	v_pk_add_f32 v[88:89], v[20:21], v[90:91]
	v_pk_add_f32 v[20:21], v[20:21], v[90:91] neg_lo:[0,1] neg_hi:[0,1]
	v_pk_add_f32 v[90:91], v[22:23], v[92:93]
	v_pk_add_f32 v[22:23], v[22:23], v[92:93] neg_lo:[0,1] neg_hi:[0,1]
	v_pk_add_f32 v[92:93], v[18:19], v[18:19] op_sel:[1,0]
	v_pk_add_f32 v[18:19], v[18:19], v[18:19] op_sel_hi:[1,0] neg_lo:[0,1] neg_hi:[0,1]
	s_nop 0
	v_mov_b32_e32 v93, v19
	v_xor_b32_e32 v19, 0x80000000, v20
	v_mov_b32_e32 v18, v21
	v_pk_add_f32 v[20:21], v[22:23], v[22:23] op_sel:[1,0] neg_lo:[0,1] neg_hi:[0,1]
	v_pk_add_f32 v[22:23], v[22:23], v[22:23] op_sel_hi:[1,0]
	s_nop 0
	v_mov_b32_e32 v21, v23
	v_pk_mul_f32 v[20:21], v[20:21], s[20:21]
	v_pk_add_f32 v[22:23], v[94:95], v[88:89]
	v_pk_add_f32 v[88:89], v[94:95], v[88:89] neg_lo:[0,1] neg_hi:[0,1]
	v_pk_add_f32 v[94:95], v[86:87], v[90:91]
	v_pk_add_f32 v[86:87], v[86:87], v[90:91] neg_lo:[0,1] neg_hi:[0,1]
	v_pk_add_f32 v[96:97], v[22:23], v[94:95]
	v_pk_add_f32 v[94:95], v[22:23], v[94:95] neg_lo:[0,1] neg_hi:[0,1]
	v_pk_add_f32 v[22:23], v[16:17], v[18:19]
	v_pk_add_f32 v[16:17], v[16:17], v[18:19] neg_lo:[0,1] neg_hi:[0,1]
	v_pk_fma_f32 v[18:19], v[92:93], s[20:21], v[20:21] op_sel_hi:[1,0,1]
	v_pk_fma_f32 v[20:21], v[92:93], s[20:21], v[20:21] op_sel_hi:[1,0,1] neg_lo:[0,0,1] neg_hi:[0,0,1]
	v_xor_b32_e32 v91, 0x80000000, v86
	v_mov_b32_e32 v90, v87
	v_xor_b32_e32 v87, 0x80000000, v20
	v_mov_b32_e32 v86, v21
	v_pk_add_f32 v[98:99], v[88:89], v[90:91]
	v_pk_add_f32 v[100:101], v[88:89], v[90:91] neg_lo:[0,1] neg_hi:[0,1]
	v_pk_add_f32 v[102:103], v[22:23], v[18:19]
	v_pk_add_f32 v[194:195], v[22:23], v[18:19] neg_lo:[0,1] neg_hi:[0,1]
	v_pk_add_f32 v[196:197], v[16:17], v[86:87]
	v_pk_add_f32 v[198:199], v[16:17], v[86:87] neg_lo:[0,1] neg_hi:[0,1]
	ds_read2_b64 v[16:19], v63 offset1:1
	ds_read2_b64 v[20:23], v204 offset1:1
	ds_read2_b64 v[86:89], v205 offset1:1
	ds_read2_b64 v[90:93], v206 offset1:1
	s_waitcnt lgkmcnt(0)
; __device__ __forceinline__ c2 cmul(c2 a, c2 b) { return (c2){a.x * b.x - a.y * b.y, a.x * b.y + a.y * b.x}; }
; __device__ __forceinline__ c2 mni(c2 a) { return (c2){a.y, -a.x}; }
; __device__ __forceinline__ void dft8(c2 (&x)[8]) {
;     const float s = 0.70710678118654752f;
;     const c2 a0 = x[0] + x[4], a4 = x[0] - x[4], a1 = x[1] + x[5], a5 = x[1] - x[5], a2 = x[2] + x[6], a6 = x[2] - x[6], a3 = x[3] + x[7], a7 = x[3] - x[7];
;     const c2 a5w = (c2){(a5.x + a5.y) * s, (a5.y - a5.x) * s};
;     const c2 a6w = mni(a6);
;     const c2 a7w = (c2){(a7.y - a7.x) * s, -(a7.x + a7.y) * s};
;     const c2 b0 = a0 + a2, b1 = a0 - a2, b2 = a1 + a3, b3 = mni(a1 - a3);
;     x[0] = b0 + b2; x[4] = b0 - b2; x[2] = b1 + b3; x[6] = b1 - b3;
;     const c2 c0 = a4 + a6w, c1 = a4 - a6w, c2_ = a5w + a7w, c3 = mni(a5w - a7w);
;     x[1] = c0 + c2_; x[5] = c0 - c2_; x[3] = c1 + c3; x[7] = c1 - c3;
; }
; __device__ __forceinline__ c2 mpi(c2 a) { return (c2){-a.y, a.x}; }
; __device__ __forceinline__ void idft8(c2 (&x)[8]) {
;     const float s = 0.70710678118654752f;
;     const c2 a0 = x[0] + x[4], a4 = x[0] - x[4], a1 = x[1] + x[5], a5 = x[1] - x[5], a2 = x[2] + x[6], a6 = x[2] - x[6], a3 = x[3] + x[7], a7 = x[3] - x[7];
;     const c2 a5w = (c2){(a5.x - a5.y) * s, (a5.x + a5.y) * s};
;     const c2 a6w = mpi(a6);
;     const c2 a7w = (c2){-(a7.x + a7.y) * s, (a7.x - a7.y) * s};
;     const c2 b0 = a0 + a2, b1 = a0 - a2, b2 = a1 + a3, b3 = mpi(a1 - a3);
;     x[0] = b0 + b2; x[4] = b0 - b2; x[2] = b1 + b3; x[6] = b1 - b3;
;     const c2 c0 = a4 + a6w, c1 = a4 - a6w, c2_ = a5w + a7w, c3 = mpi(a5w - a7w);
;     x[1] = c0 + c2_; x[5] = c0 - c2_; x[3] = c1 + c3; x[7] = c1 - c3;
; __device__ __forceinline__ void phase_conv(const Params& p, int o, unsigned char* smem, int wave) {
;     ...
;                 for (int q = 0; q < 8; ++q) { x0[q] = cmul(x0[q], K[q]); x1[q] = cmul(x1[q], K[q]); }
	v_pk_add_f32 v[200:201], v[16:17], v[86:87]
	v_pk_add_f32 v[16:17], v[16:17], v[86:87] neg_lo:[0,1] neg_hi:[0,1]
	v_pk_add_f32 v[86:87], v[18:19], v[88:89]
	v_pk_add_f32 v[18:19], v[18:19], v[88:89] neg_lo:[0,1] neg_hi:[0,1]
	s_waitcnt lgkmcnt(0)
	v_pk_add_f32 v[88:89], v[20:21], v[90:91]
	v_pk_add_f32 v[20:21], v[20:21], v[90:91] neg_lo:[0,1] neg_hi:[0,1]
	v_pk_add_f32 v[90:91], v[22:23], v[92:93]
	v_pk_add_f32 v[22:23], v[22:23], v[92:93] neg_lo:[0,1] neg_hi:[0,1]
	v_pk_add_f32 v[92:93], v[18:19], v[18:19] op_sel:[1,0]
	v_pk_add_f32 v[18:19], v[18:19], v[18:19] op_sel_hi:[1,0] neg_lo:[0,1] neg_hi:[0,1]
	s_nop 0
	v_mov_b32_e32 v93, v19
	v_xor_b32_e32 v19, 0x80000000, v20
	v_mov_b32_e32 v18, v21
	v_pk_add_f32 v[20:21], v[22:23], v[22:23] op_sel:[1,0] neg_lo:[0,1] neg_hi:[0,1]
	v_pk_add_f32 v[22:23], v[22:23], v[22:23] op_sel_hi:[1,0]
	s_nop 0
	v_mov_b32_e32 v21, v23
	v_pk_add_f32 v[22:23], v[200:201], v[88:89]
	v_pk_add_f32 v[88:89], v[200:201], v[88:89] neg_lo:[0,1] neg_hi:[0,1]
	v_pk_add_f32 v[200:201], v[86:87], v[90:91]
	v_pk_add_f32 v[86:87], v[86:87], v[90:91] neg_lo:[0,1] neg_hi:[0,1]
	v_pk_mul_f32 v[20:21], v[20:21], s[20:21]
	v_xor_b32_e32 v91, 0x80000000, v86
	v_mov_b32_e32 v90, v87
	v_pk_add_f32 v[86:87], v[22:23], v[200:201]
	v_pk_add_f32 v[22:23], v[22:23], v[200:201] neg_lo:[0,1] neg_hi:[0,1]
	v_pk_add_f32 v[200:201], v[88:89], v[90:91]
	v_pk_add_f32 v[88:89], v[88:89], v[90:91] neg_lo:[0,1] neg_hi:[0,1]
	v_pk_add_f32 v[90:91], v[16:17], v[18:19]
	v_pk_add_f32 v[16:17], v[16:17], v[18:19] neg_lo:[0,1] neg_hi:[0,1]
	v_pk_fma_f32 v[18:19], v[92:93], s[20:21], v[20:21] op_sel_hi:[1,0,1]
	v_pk_fma_f32 v[20:21], v[92:93], s[20:21], v[20:21] op_sel_hi:[1,0,1] neg_lo:[0,0,1] neg_hi:[0,0,1]
	s_nop 0
	v_xor_b32_e32 v93, 0x80000000, v20
	v_mov_b32_e32 v92, v21
	v_pk_add_f32 v[20:21], v[90:91], v[18:19]
	v_pk_add_f32 v[18:19], v[90:91], v[18:19] neg_lo:[0,1] neg_hi:[0,1]
	v_pk_add_f32 v[90:91], v[16:17], v[92:93]
	v_pk_add_f32 v[16:17], v[16:17], v[92:93] neg_lo:[0,1] neg_hi:[0,1]
	v_pk_mul_f32 v[92:93], v[40:41], v[96:97] op_sel:[0,1]
	s_nop 0
	v_fma_f32 v202, v24, v96, -v92
	v_fma_f32 v203, v25, v96, v93
	s_nop 0
	v_pk_mul_f32 v[92:93], v[40:41], v[86:87] op_sel:[0,1]
	s_nop 0
	v_fma_f32 v96, v24, v86, -v92
	v_fma_f32 v97, v25, v86, v93
	s_nop 0
	v_pk_mul_f32 v[86:87], v[42:43], v[102:103] op_sel:[0,1]
	s_nop 0
	v_fma_f32 v92, v32, v102, -v86
	v_fma_f32 v93, v33, v102, v87
	s_nop 0
	v_pk_mul_f32 v[86:87], v[42:43], v[20:21] op_sel:[0,1]
	s_nop 0
	v_fma_f32 v102, v32, v20, -v86
	v_fma_f32 v103, v33, v20, v87
	s_nop 0
	v_pk_mul_f32 v[20:21], v[44:45], v[98:99] op_sel:[0,1]
	s_nop 0
	v_fma_f32 v86, v28, v98, -v20
	v_fma_f32 v87, v29, v98, v21
	s_nop 0
	v_pk_mul_f32 v[20:21], v[44:45], v[200:201] op_sel:[0,1]
	s_nop 0
	v_fma_f32 v98, v28, v200, -v20
	v_fma_f32 v99, v29, v200, v21
	s_nop 0
	v_pk_mul_f32 v[20:21], v[46:47], v[196:197] op_sel:[0,1]
	s_nop 0
	v_fma_f32 v200, v36, v196, -v20
	v_fma_f32 v201, v37, v196, v21
	s_nop 0
	v_pk_mul_f32 v[20:21], v[46:47], v[90:91] op_sel:[0,1]
	s_nop 0
	v_fma_f32 v196, v36, v90, -v20
	v_fma_f32 v197, v37, v90, v21
	s_nop 0
	v_pk_mul_f32 v[20:21], v[48:49], v[94:95] op_sel:[0,1]
	s_nop 0
	v_fma_f32 v90, v26, v94, -v20
	v_fma_f32 v91, v27, v94, v21
	s_nop 0
	v_pk_mul_f32 v[20:21], v[48:49], v[22:23] op_sel:[0,1]
	s_nop 0
	v_fma_f32 v94, v26, v22, -v20
	v_fma_f32 v95, v27, v22, v21
	s_nop 0
	v_pk_mul_f32 v[20:21], v[50:51], v[194:195] op_sel:[0,1]
	s_nop 0
	v_fma_f32 v22, v34, v194, -v20
	v_fma_f32 v23, v35, v194, v21
	s_nop 0
	v_pk_mul_f32 v[20:21], v[50:51], v[18:19] op_sel:[0,1]
	s_nop 0
	v_fma_f32 v194, v34, v18, -v20
	v_fma_f32 v195, v35, v18, v21
	s_nop 0
	v_pk_mul_f32 v[18:19], v[52:53], v[100:101] op_sel:[0,1]
	s_nop 0
	v_fma_f32 v20, v30, v100, -v18
	v_fma_f32 v21, v31, v100, v19
	s_nop 0
	v_pk_mul_f32 v[18:19], v[52:53], v[88:89] op_sel:[0,1]
	s_nop 0
	v_fma_f32 v100, v30, v88, -v18
	v_fma_f32 v101, v31, v88, v19
	s_nop 0
	v_pk_mul_f32 v[18:19], v[54:55], v[198:199] op_sel:[0,1]
	s_nop 0
	v_fma_f32 v88, v38, v198, -v18
	v_fma_f32 v89, v39, v198, v19
	s_nop 0
	v_pk_mul_f32 v[18:19], v[54:55], v[16:17] op_sel:[0,1]
	s_nop 0
	v_fma_f32 v198, v38, v16, -v18
	v_fma_f32 v199, v39, v16, v19
	v_pk_add_f32 v[18:19], v[202:203], v[90:91] neg_lo:[0,1] neg_hi:[0,1]
	v_pk_add_f32 v[16:17], v[202:203], v[90:91]
	v_pk_add_f32 v[90:91], v[92:93], v[22:23]
	v_pk_add_f32 v[22:23], v[92:93], v[22:23] neg_lo:[0,1] neg_hi:[0,1]
	v_pk_add_f32 v[92:93], v[86:87], v[20:21]
	v_pk_add_f32 v[20:21], v[86:87], v[20:21] neg_lo:[0,1] neg_hi:[0,1]
	v_pk_add_f32 v[86:87], v[200:201], v[88:89]
	v_pk_add_f32 v[88:89], v[200:201], v[88:89] neg_lo:[0,1] neg_hi:[0,1]
	v_pk_add_f32 v[200:201], v[22:23], v[22:23] op_sel:[0,1] neg_lo:[0,1] neg_hi:[0,1]
	v_pk_add_f32 v[22:23], v[22:23], v[22:23] op_sel_hi:[0,1]
	v_mov_b32_e32 v201, v23
	v_xor_b32_e32 v22, 0x80000000, v21
	v_mov_b32_e32 v23, v20
	v_pk_add_f32 v[20:21], v[88:89], v[88:89] op_sel:[0,1]
	v_pk_add_f32 v[88:89], v[88:89], v[88:89] op_sel_hi:[0,1] neg_lo:[0,1] neg_hi:[0,1]
	v_mov_b32_e32 v21, v89
	v_pk_add_f32 v[88:89], v[16:17], v[92:93]
	v_pk_add_f32 v[16:17], v[16:17], v[92:93] neg_lo:[0,1] neg_hi:[0,1]
	v_pk_add_f32 v[92:93], v[90:91], v[86:87]
	v_pk_add_f32 v[86:87], v[90:91], v[86:87] neg_lo:[0,1] neg_hi:[0,1]
	v_pk_mul_f32 v[20:21], v[20:21], s[84:85]
	v_xor_b32_e32 v90, 0x80000000, v87
	v_mov_b32_e32 v91, v86
	v_pk_add_f32 v[86:87], v[88:89], v[92:93]
	v_pk_add_f32 v[88:89], v[88:89], v[92:93] neg_lo:[0,1] neg_hi:[0,1]
	v_pk_add_f32 v[92:93], v[16:17], v[90:91]
	v_pk_add_f32 v[16:17], v[16:17], v[90:91] neg_lo:[0,1] neg_hi:[0,1]
	v_pk_add_f32 v[90:91], v[18:19], v[22:23]
; __device__ __forceinline__ c2 cmulc(c2 a, c2 b) { return (c2){a.x * b.x + a.y * b.y, a.y * b.x - a.x * b.y}; }
; __device__ __forceinline__ void inv_s3(c2 (&x)[8], c2* buf, int tid) {
;     idft8(x);
; #pragma unroll
;     for (int q = 0; q < 8; ++q) buf[9 * tid + q] = x[q];
; }
; template <int S> __device__ __forceinline__ void inv_mid(c2* buf, const c2* tws, int tid) {
;     constexpr int lq = 9 - 3 * S, Q = 1 << lq; const c2* T = tws + (S == 1 ? 3584 : 4032);
;     const int k = tid & (Q - 1), base = ((tid >> lq) << (lq + 3)) + k;
;     c2 x[8];
;     c2* bp_ = buf + LP(base); constexpr int QP = Q + Q / 8;
; #pragma unroll
;     for (int r = 0; r < 8; ++r) { c2 v = bp_[r * QP]; if (r) v = cmulc(v, T[(r - 1) * Q + k]); x[r] = v; }
;     idft8(x);
; #pragma unroll
;     for (int q = 0; q < 8; ++q) bp_[q * QP] = x[q];
; }
	v_pk_add_f32 v[18:19], v[18:19], v[22:23] neg_lo:[0,1] neg_hi:[0,1]
	v_pk_fma_f32 v[22:23], v[200:201], s[20:21], v[20:21] op_sel_hi:[1,0,1]
	v_pk_fma_f32 v[20:21], v[200:201], s[20:21], v[20:21] op_sel_hi:[1,0,1] neg_lo:[0,0,1] neg_hi:[0,0,1]
	s_nop 0
	v_xor_b32_e32 v200, 0x80000000, v21
	v_mov_b32_e32 v201, v20
	v_pk_add_f32 v[20:21], v[90:91], v[22:23]
	v_pk_add_f32 v[22:23], v[90:91], v[22:23] neg_lo:[0,1] neg_hi:[0,1]
	v_pk_add_f32 v[90:91], v[18:19], v[200:201]
	v_pk_add_f32 v[18:19], v[18:19], v[200:201] neg_lo:[0,1] neg_hi:[0,1]
	ds_write2_b64 v121, v[86:87], v[20:21] offset1:1
	ds_write2_b64 v121, v[92:93], v[90:91] offset0:2 offset1:3
	ds_write2_b64 v121, v[88:89], v[22:23] offset0:4 offset1:5
	ds_write2_b64 v121, v[16:17], v[18:19] offset0:6 offset1:7
	v_pk_add_f32 v[22:23], v[102:103], v[194:195] neg_lo:[0,1] neg_hi:[0,1]
	v_pk_add_f32 v[16:17], v[96:97], v[94:95]
	v_pk_add_f32 v[18:19], v[96:97], v[94:95] neg_lo:[0,1] neg_hi:[0,1]
	v_pk_add_f32 v[88:89], v[98:99], v[100:101] neg_lo:[0,1] neg_hi:[0,1]
	v_pk_add_f32 v[92:93], v[196:197], v[198:199] neg_lo:[0,1] neg_hi:[0,1]
	v_pk_add_f32 v[94:95], v[22:23], v[22:23] op_sel:[0,1] neg_lo:[0,1] neg_hi:[0,1]
	v_pk_add_f32 v[22:23], v[22:23], v[22:23] op_sel_hi:[0,1]
	v_pk_add_f32 v[20:21], v[102:103], v[194:195]
	v_pk_add_f32 v[86:87], v[98:99], v[100:101]
	v_pk_add_f32 v[90:91], v[196:197], v[198:199]
	v_mov_b32_e32 v95, v23
	v_xor_b32_e32 v22, 0x80000000, v89
	v_mov_b32_e32 v23, v88
	v_pk_add_f32 v[88:89], v[92:93], v[92:93] op_sel:[0,1]
	v_pk_add_f32 v[92:93], v[92:93], v[92:93] op_sel_hi:[0,1] neg_lo:[0,1] neg_hi:[0,1]
	v_mov_b32_e32 v89, v93
	v_pk_add_f32 v[92:93], v[16:17], v[86:87]
	v_pk_add_f32 v[16:17], v[16:17], v[86:87] neg_lo:[0,1] neg_hi:[0,1]
	v_pk_add_f32 v[86:87], v[20:21], v[90:91]
	v_pk_add_f32 v[20:21], v[20:21], v[90:91] neg_lo:[0,1] neg_hi:[0,1]
	v_pk_mul_f32 v[88:89], v[88:89], s[84:85]
	v_xor_b32_e32 v90, 0x80000000, v21
	v_mov_b32_e32 v91, v20
	v_pk_add_f32 v[20:21], v[92:93], v[86:87]
	v_pk_add_f32 v[86:87], v[92:93], v[86:87] neg_lo:[0,1] neg_hi:[0,1]
	v_pk_add_f32 v[92:93], v[16:17], v[90:91]
	v_pk_add_f32 v[16:17], v[16:17], v[90:91] neg_lo:[0,1] neg_hi:[0,1]
	v_pk_add_f32 v[90:91], v[18:19], v[22:23]
	v_pk_add_f32 v[18:19], v[18:19], v[22:23] neg_lo:[0,1] neg_hi:[0,1]
	v_pk_fma_f32 v[22:23], v[94:95], s[20:21], v[88:89] op_sel_hi:[1,0,1]
	v_pk_fma_f32 v[88:89], v[94:95], s[20:21], v[88:89] op_sel_hi:[1,0,1] neg_lo:[0,0,1] neg_hi:[0,0,1]
	s_nop 0
	v_xor_b32_e32 v94, 0x80000000, v89
	v_mov_b32_e32 v95, v88
	v_pk_add_f32 v[88:89], v[90:91], v[22:23]
	v_pk_add_f32 v[22:23], v[90:91], v[22:23] neg_lo:[0,1] neg_hi:[0,1]
	v_pk_add_f32 v[90:91], v[18:19], v[94:95]
	v_pk_add_f32 v[18:19], v[18:19], v[94:95] neg_lo:[0,1] neg_hi:[0,1]
	ds_write2_b64 v63, v[20:21], v[88:89] offset1:1
	ds_write2_b64 v204, v[92:93], v[90:91] offset1:1
	ds_write2_b64 v205, v[86:87], v[22:23] offset1:1
	ds_write2_b64 v206, v[16:17], v[18:19] offset1:1
	s_waitcnt lgkmcnt(0)
	s_barrier
	ds_read2_b64 v[16:19], v119 offset1:9
	v_mov_b64_e32 v[94:95], v[238:239]
	ds_read2_b64 v[20:23], v119 offset0:18 offset1:27
	v_mov_b64_e32 v[96:97], v[240:241]
	v_mov_b64_e32 v[98:99], v[242:243]
	ds_read2_b64 v[86:89], v119 offset0:36 offset1:45
	v_mov_b64_e32 v[100:101], v[244:245]
	v_mov_b64_e32 v[102:103], v[246:247]
	ds_read2_b64 v[90:93], v119 offset0:54 offset1:63
	v_mov_b64_e32 v[194:195], v[248:249]
	s_waitcnt lgkmcnt(0)
	v_pk_mul_f32 v[198:199], v[92:93], v[250:251] op_sel:[1,1] op_sel_hi:[0,1]
	v_fma_f32 v200, v92, v250, v198
	v_fma_f32 v201, v93, v250, -v199
	s_nop 0
	v_pk_mul_f32 v[92:93], v[18:19], v[94:95] op_sel:[1,1] op_sel_hi:[0,1]
	v_fma_f32 v196, v18, v94, v92
	v_fma_f32 v197, v19, v94, -v93
	s_nop 0
	v_pk_mul_f32 v[18:19], v[20:21], v[96:97] op_sel:[1,1] op_sel_hi:[0,1]
	v_fma_f32 v92, v20, v96, v18
	v_fma_f32 v93, v21, v96, -v19
	s_nop 0
	v_pk_mul_f32 v[18:19], v[22:23], v[98:99] op_sel:[1,1] op_sel_hi:[0,1]
	v_fma_f32 v20, v22, v98, v18
	v_fma_f32 v21, v23, v98, -v19
	s_nop 0
	v_pk_mul_f32 v[18:19], v[86:87], v[100:101] op_sel:[1,1] op_sel_hi:[0,1]
	v_fma_f32 v22, v86, v100, v18
	v_fma_f32 v23, v87, v100, -v19
	s_nop 0
	v_pk_mul_f32 v[18:19], v[88:89], v[102:103] op_sel:[1,1] op_sel_hi:[0,1]
	v_fma_f32 v86, v88, v102, v18
	v_fma_f32 v87, v89, v102, -v19
	s_nop 0
	v_pk_mul_f32 v[18:19], v[90:91], v[194:195] op_sel:[1,1] op_sel_hi:[0,1]
	v_fma_f32 v88, v90, v194, v18
	v_fma_f32 v89, v91, v194, -v19
	s_nop 0
	v_pk_add_f32 v[18:19], v[16:17], v[22:23]
	v_pk_add_f32 v[16:17], v[16:17], v[22:23] neg_lo:[0,1] neg_hi:[0,1]
	v_pk_add_f32 v[22:23], v[196:197], v[86:87]
	v_pk_add_f32 v[86:87], v[196:197], v[86:87] neg_lo:[0,1] neg_hi:[0,1]
	v_pk_add_f32 v[90:91], v[92:93], v[88:89]
	v_pk_add_f32 v[88:89], v[92:93], v[88:89] neg_lo:[0,1] neg_hi:[0,1]
	v_pk_add_f32 v[92:93], v[20:21], v[200:201]
	v_pk_add_f32 v[20:21], v[20:21], v[200:201] neg_lo:[0,1] neg_hi:[0,1]
	v_pk_add_f32 v[94:95], v[86:87], v[86:87] op_sel:[0,1] neg_lo:[0,1] neg_hi:[0,1]
	v_pk_add_f32 v[86:87], v[86:87], v[86:87] op_sel_hi:[0,1]
	v_mov_b32_e32 v95, v87
	v_xor_b32_e32 v86, 0x80000000, v89
	v_mov_b32_e32 v87, v88
	v_pk_add_f32 v[88:89], v[20:21], v[20:21] op_sel:[0,1]
	v_pk_add_f32 v[20:21], v[20:21], v[20:21] op_sel_hi:[0,1] neg_lo:[0,1] neg_hi:[0,1]
	v_mov_b32_e32 v89, v21
	v_pk_mul_f32 v[20:21], v[88:89], s[84:85]
	v_pk_add_f32 v[88:89], v[18:19], v[90:91]
	v_pk_add_f32 v[18:19], v[18:19], v[90:91] neg_lo:[0,1] neg_hi:[0,1]
	v_pk_add_f32 v[90:91], v[22:23], v[92:93]
	v_pk_add_f32 v[22:23], v[22:23], v[92:93] neg_lo:[0,1] neg_hi:[0,1]
	s_nop 0
	v_xor_b32_e32 v92, 0x80000000, v23
	v_mov_b32_e32 v93, v22
; __device__ __forceinline__ c2 cmulc(c2 a, c2 b) { return (c2){a.x * b.x + a.y * b.y, a.y * b.x - a.x * b.y}; }
; template <int S> __device__ __forceinline__ void inv_mid(c2* buf, const c2* tws, int tid) {
;     constexpr int lq = 9 - 3 * S, Q = 1 << lq; const c2* T = tws + (S == 1 ? 3584 : 4032);
;     const int k = tid & (Q - 1), base = ((tid >> lq) << (lq + 3)) + k;
;     c2 x[8];
;     c2* bp_ = buf + LP(base); constexpr int QP = Q + Q / 8;
; #pragma unroll
;     for (int r = 0; r < 8; ++r) { c2 v = bp_[r * QP]; if (r) v = cmulc(v, T[(r - 1) * Q + k]); x[r] = v; }
;     idft8(x);
; #pragma unroll
;     for (int q = 0; q < 8; ++q) bp_[q * QP] = x[q];
; }
	v_pk_add_f32 v[22:23], v[88:89], v[90:91]
	v_pk_add_f32 v[88:89], v[88:89], v[90:91] neg_lo:[0,1] neg_hi:[0,1]
	v_pk_add_f32 v[90:91], v[18:19], v[92:93]
	v_pk_add_f32 v[18:19], v[18:19], v[92:93] neg_lo:[0,1] neg_hi:[0,1]
	v_pk_add_f32 v[92:93], v[16:17], v[86:87]
	v_pk_add_f32 v[16:17], v[16:17], v[86:87] neg_lo:[0,1] neg_hi:[0,1]
	v_pk_fma_f32 v[86:87], v[94:95], s[20:21], v[20:21] op_sel_hi:[1,0,1]
	v_pk_fma_f32 v[20:21], v[94:95], s[20:21], v[20:21] op_sel_hi:[1,0,1] neg_lo:[0,0,1] neg_hi:[0,0,1]
	s_nop 0
	v_xor_b32_e32 v94, 0x80000000, v21
	v_mov_b32_e32 v95, v20
	v_pk_add_f32 v[20:21], v[92:93], v[86:87]
	v_pk_add_f32 v[86:87], v[92:93], v[86:87] neg_lo:[0,1] neg_hi:[0,1]
	v_pk_add_f32 v[92:93], v[16:17], v[94:95]
	v_pk_add_f32 v[16:17], v[16:17], v[94:95] neg_lo:[0,1] neg_hi:[0,1]
	ds_write2_b64 v119, v[22:23], v[20:21] offset1:9
	ds_write2_b64 v119, v[90:91], v[92:93] offset0:18 offset1:27
	ds_write2_b64 v119, v[88:89], v[86:87] offset0:36 offset1:45
	ds_write2_b64 v119, v[18:19], v[16:17] offset0:54 offset1:63
	ds_read2_b64 v[16:19], v193 offset1:9
	v_mov_b64_e32 v[94:95], v[238:239]
	ds_read2_b64 v[20:23], v193 offset0:18 offset1:27
	v_mov_b64_e32 v[96:97], v[240:241]
	v_mov_b64_e32 v[98:99], v[242:243]
	ds_read2_b64 v[86:89], v193 offset0:36 offset1:45
	v_mov_b64_e32 v[100:101], v[244:245]
	v_mov_b64_e32 v[102:103], v[246:247]
	ds_read2_b64 v[90:93], v193 offset0:54 offset1:63
	v_mov_b64_e32 v[194:195], v[248:249]
	s_waitcnt lgkmcnt(0)
	v_pk_mul_f32 v[198:199], v[92:93], v[250:251] op_sel:[1,1] op_sel_hi:[0,1]
	v_fma_f32 v200, v92, v250, v198
	v_fma_f32 v201, v93, v250, -v199
	s_nop 0
	v_pk_mul_f32 v[92:93], v[18:19], v[94:95] op_sel:[1,1] op_sel_hi:[0,1]
	v_fma_f32 v196, v18, v94, v92
	v_fma_f32 v197, v19, v94, -v93
	s_nop 0
	v_pk_mul_f32 v[18:19], v[20:21], v[96:97] op_sel:[1,1] op_sel_hi:[0,1]
	v_fma_f32 v92, v20, v96, v18
	v_fma_f32 v93, v21, v96, -v19
	s_nop 0
	v_pk_mul_f32 v[18:19], v[22:23], v[98:99] op_sel:[1,1] op_sel_hi:[0,1]
	v_fma_f32 v20, v22, v98, v18
	v_fma_f32 v21, v23, v98, -v19
	s_nop 0
	v_pk_mul_f32 v[18:19], v[86:87], v[100:101] op_sel:[1,1] op_sel_hi:[0,1]
	v_fma_f32 v22, v86, v100, v18
	v_fma_f32 v23, v87, v100, -v19
	s_nop 0
	v_pk_mul_f32 v[18:19], v[88:89], v[102:103] op_sel:[1,1] op_sel_hi:[0,1]
	v_fma_f32 v86, v88, v102, v18
	v_fma_f32 v87, v89, v102, -v19
	s_nop 0
	v_pk_mul_f32 v[18:19], v[90:91], v[194:195] op_sel:[1,1] op_sel_hi:[0,1]
	v_fma_f32 v88, v90, v194, v18
	v_fma_f32 v89, v91, v194, -v19
	s_nop 0
	v_pk_add_f32 v[18:19], v[16:17], v[22:23]
	v_pk_add_f32 v[16:17], v[16:17], v[22:23] neg_lo:[0,1] neg_hi:[0,1]
	v_pk_add_f32 v[22:23], v[196:197], v[86:87]
	v_pk_add_f32 v[86:87], v[196:197], v[86:87] neg_lo:[0,1] neg_hi:[0,1]
	v_pk_add_f32 v[90:91], v[92:93], v[88:89]
	v_pk_add_f32 v[88:89], v[92:93], v[88:89] neg_lo:[0,1] neg_hi:[0,1]
	v_pk_add_f32 v[92:93], v[20:21], v[200:201]
	v_pk_add_f32 v[20:21], v[20:21], v[200:201] neg_lo:[0,1] neg_hi:[0,1]
	v_pk_add_f32 v[94:95], v[86:87], v[86:87] op_sel:[0,1] neg_lo:[0,1] neg_hi:[0,1]
	v_pk_add_f32 v[86:87], v[86:87], v[86:87] op_sel_hi:[0,1]
	v_mov_b32_e32 v95, v87
	v_xor_b32_e32 v86, 0x80000000, v89
	v_mov_b32_e32 v87, v88
	v_pk_add_f32 v[88:89], v[20:21], v[20:21] op_sel:[0,1]
	v_pk_add_f32 v[20:21], v[20:21], v[20:21] op_sel_hi:[0,1] neg_lo:[0,1] neg_hi:[0,1]
	v_mov_b32_e32 v89, v21
	v_pk_mul_f32 v[20:21], v[88:89], s[84:85]
	v_pk_add_f32 v[88:89], v[18:19], v[90:91]
	v_pk_add_f32 v[18:19], v[18:19], v[90:91] neg_lo:[0,1] neg_hi:[0,1]
	v_pk_add_f32 v[90:91], v[22:23], v[92:93]
	v_pk_add_f32 v[22:23], v[22:23], v[92:93] neg_lo:[0,1] neg_hi:[0,1]
	s_nop 0
	v_xor_b32_e32 v92, 0x80000000, v23
	v_mov_b32_e32 v93, v22
	v_pk_add_f32 v[22:23], v[88:89], v[90:91]
	v_pk_add_f32 v[88:89], v[88:89], v[90:91] neg_lo:[0,1] neg_hi:[0,1]
	v_pk_add_f32 v[90:91], v[18:19], v[92:93]
	v_pk_add_f32 v[18:19], v[18:19], v[92:93] neg_lo:[0,1] neg_hi:[0,1]
	v_pk_add_f32 v[92:93], v[16:17], v[86:87]
	v_pk_add_f32 v[16:17], v[16:17], v[86:87] neg_lo:[0,1] neg_hi:[0,1]
	v_pk_fma_f32 v[86:87], v[94:95], s[20:21], v[20:21] op_sel_hi:[1,0,1]
	v_pk_fma_f32 v[20:21], v[94:95], s[20:21], v[20:21] op_sel_hi:[1,0,1] neg_lo:[0,0,1] neg_hi:[0,0,1]
	s_nop 0
	v_xor_b32_e32 v94, 0x80000000, v21
	v_mov_b32_e32 v95, v20
	v_pk_add_f32 v[20:21], v[92:93], v[86:87]
	v_pk_add_f32 v[86:87], v[92:93], v[86:87] neg_lo:[0,1] neg_hi:[0,1]
	v_pk_add_f32 v[92:93], v[16:17], v[94:95]
	v_pk_add_f32 v[16:17], v[16:17], v[94:95] neg_lo:[0,1] neg_hi:[0,1]
	ds_write2_b64 v193, v[22:23], v[20:21] offset1:9
	ds_write2_b64 v193, v[90:91], v[92:93] offset0:18 offset1:27
	ds_write2_b64 v193, v[88:89], v[86:87] offset0:36 offset1:45
	ds_write2_b64 v193, v[18:19], v[16:17] offset0:54 offset1:63
	s_waitcnt lgkmcnt(0)
	s_barrier
; __device__ __forceinline__ c2 cmulc(c2 a, c2 b) { return (c2){a.x * b.x + a.y * b.y, a.y * b.x - a.x * b.y}; }
; template <int S> __device__ __forceinline__ void inv_mid(c2* buf, const c2* tws, int tid) {
;     constexpr int lq = 9 - 3 * S, Q = 1 << lq; const c2* T = tws + (S == 1 ? 3584 : 4032);
;     const int k = tid & (Q - 1), base = ((tid >> lq) << (lq + 3)) + k;
;     c2 x[8];
;     c2* bp_ = buf + LP(base); constexpr int QP = Q + Q / 8;
; #pragma unroll
;     for (int r = 0; r < 8; ++r) { c2 v = bp_[r * QP]; if (r) v = cmulc(v, T[(r - 1) * Q + k]); x[r] = v; }
;     idft8(x);
; #pragma unroll
;     for (int q = 0; q < 8; ++q) bp_[q * QP] = x[q];
; }
	ds_read2_b64 v[16:19], v117 offset1:72
	v_mov_b64_e32 v[94:95], v[224:225]
	ds_read2_b64 v[20:23], v117 offset0:144 offset1:216
	v_mov_b64_e32 v[96:97], v[226:227]
	v_mov_b64_e32 v[98:99], v[228:229]
	ds_read2_b64 v[86:89], v56 offset0:32 offset1:104
	v_mov_b64_e32 v[100:101], v[230:231]
	v_mov_b64_e32 v[102:103], v[232:233]
	ds_read2_b64 v[90:93], v56 offset0:176 offset1:248
	v_mov_b64_e32 v[194:195], v[234:235]
	s_waitcnt lgkmcnt(0)
	v_pk_mul_f32 v[198:199], v[92:93], v[236:237] op_sel:[1,1] op_sel_hi:[0,1]
	v_fma_f32 v200, v92, v236, v198
	v_fma_f32 v201, v93, v236, -v199
	s_nop 0
	v_pk_mul_f32 v[92:93], v[18:19], v[94:95] op_sel:[1,1] op_sel_hi:[0,1]
	v_fma_f32 v196, v18, v94, v92
	v_fma_f32 v197, v19, v94, -v93
	s_nop 0
	v_pk_mul_f32 v[18:19], v[20:21], v[96:97] op_sel:[1,1] op_sel_hi:[0,1]
	v_fma_f32 v92, v20, v96, v18
	v_fma_f32 v93, v21, v96, -v19
	s_nop 0
	v_pk_mul_f32 v[18:19], v[22:23], v[98:99] op_sel:[1,1] op_sel_hi:[0,1]
	v_fma_f32 v20, v22, v98, v18
	v_fma_f32 v21, v23, v98, -v19
	s_nop 0
	v_pk_mul_f32 v[18:19], v[86:87], v[100:101] op_sel:[1,1] op_sel_hi:[0,1]
	v_fma_f32 v22, v86, v100, v18
	v_fma_f32 v23, v87, v100, -v19
	s_nop 0
	v_pk_mul_f32 v[18:19], v[88:89], v[102:103] op_sel:[1,1] op_sel_hi:[0,1]
	v_fma_f32 v86, v88, v102, v18
	v_fma_f32 v87, v89, v102, -v19
	s_nop 0
	v_pk_mul_f32 v[18:19], v[90:91], v[194:195] op_sel:[1,1] op_sel_hi:[0,1]
	v_fma_f32 v88, v90, v194, v18
	v_fma_f32 v89, v91, v194, -v19
	s_nop 0
	v_pk_add_f32 v[18:19], v[16:17], v[22:23]
	v_pk_add_f32 v[16:17], v[16:17], v[22:23] neg_lo:[0,1] neg_hi:[0,1]
	v_pk_add_f32 v[22:23], v[196:197], v[86:87]
	v_pk_add_f32 v[86:87], v[196:197], v[86:87] neg_lo:[0,1] neg_hi:[0,1]
	v_pk_add_f32 v[90:91], v[92:93], v[88:89]
	v_pk_add_f32 v[88:89], v[92:93], v[88:89] neg_lo:[0,1] neg_hi:[0,1]
	v_pk_add_f32 v[92:93], v[20:21], v[200:201]
	v_pk_add_f32 v[20:21], v[20:21], v[200:201] neg_lo:[0,1] neg_hi:[0,1]
	v_pk_add_f32 v[94:95], v[86:87], v[86:87] op_sel:[0,1] neg_lo:[0,1] neg_hi:[0,1]
	v_pk_add_f32 v[86:87], v[86:87], v[86:87] op_sel_hi:[0,1]
	v_mov_b32_e32 v95, v87
	v_xor_b32_e32 v86, 0x80000000, v89
	v_mov_b32_e32 v87, v88
	v_pk_add_f32 v[88:89], v[20:21], v[20:21] op_sel:[0,1]
	v_pk_add_f32 v[20:21], v[20:21], v[20:21] op_sel_hi:[0,1] neg_lo:[0,1] neg_hi:[0,1]
	v_mov_b32_e32 v89, v21
	v_pk_mul_f32 v[20:21], v[88:89], s[84:85]
	v_pk_add_f32 v[88:89], v[18:19], v[90:91]
	v_pk_add_f32 v[18:19], v[18:19], v[90:91] neg_lo:[0,1] neg_hi:[0,1]
	v_pk_add_f32 v[90:91], v[22:23], v[92:93]
	v_pk_add_f32 v[22:23], v[22:23], v[92:93] neg_lo:[0,1] neg_hi:[0,1]
	s_nop 0
	v_xor_b32_e32 v92, 0x80000000, v23
	v_mov_b32_e32 v93, v22
	v_pk_add_f32 v[22:23], v[88:89], v[90:91]
	v_pk_add_f32 v[88:89], v[88:89], v[90:91] neg_lo:[0,1] neg_hi:[0,1]
	v_pk_add_f32 v[90:91], v[18:19], v[92:93]
	v_pk_add_f32 v[18:19], v[18:19], v[92:93] neg_lo:[0,1] neg_hi:[0,1]
	v_pk_add_f32 v[92:93], v[16:17], v[86:87]
	v_pk_add_f32 v[16:17], v[16:17], v[86:87] neg_lo:[0,1] neg_hi:[0,1]
	v_pk_fma_f32 v[86:87], v[94:95], s[20:21], v[20:21] op_sel_hi:[1,0,1]
	v_pk_fma_f32 v[20:21], v[94:95], s[20:21], v[20:21] op_sel_hi:[1,0,1] neg_lo:[0,0,1] neg_hi:[0,0,1]
	s_nop 0
	v_xor_b32_e32 v94, 0x80000000, v21
	v_mov_b32_e32 v95, v20
	v_pk_add_f32 v[20:21], v[92:93], v[86:87]
	v_pk_add_f32 v[86:87], v[92:93], v[86:87] neg_lo:[0,1] neg_hi:[0,1]
	v_pk_add_f32 v[92:93], v[16:17], v[94:95]
	v_pk_add_f32 v[16:17], v[16:17], v[94:95] neg_lo:[0,1] neg_hi:[0,1]
	ds_write2_b64 v117, v[22:23], v[20:21] offset1:72
	ds_write2_b64 v117, v[90:91], v[92:93] offset0:144 offset1:216
	ds_write2_b64 v56, v[88:89], v[86:87] offset0:32 offset1:104
	ds_write2_b64 v56, v[18:19], v[16:17] offset0:176 offset1:248
	ds_read2_b64 v[16:19], v191 offset1:72
	v_mov_b64_e32 v[94:95], v[224:225]
	ds_read2_b64 v[20:23], v191 offset0:144 offset1:216
	v_mov_b64_e32 v[96:97], v[226:227]
	v_mov_b64_e32 v[98:99], v[228:229]
	ds_read2_b64 v[86:89], v192 offset0:32 offset1:104
	v_mov_b64_e32 v[100:101], v[230:231]
	v_mov_b64_e32 v[102:103], v[232:233]
	ds_read2_b64 v[90:93], v192 offset0:176 offset1:248
	v_mov_b64_e32 v[194:195], v[234:235]
	s_waitcnt lgkmcnt(0)
	v_pk_mul_f32 v[198:199], v[92:93], v[236:237] op_sel:[1,1] op_sel_hi:[0,1]
	v_fma_f32 v200, v92, v236, v198
	v_fma_f32 v201, v93, v236, -v199
	s_nop 0
	v_pk_mul_f32 v[92:93], v[18:19], v[94:95] op_sel:[1,1] op_sel_hi:[0,1]
	v_fma_f32 v196, v18, v94, v92
	v_fma_f32 v197, v19, v94, -v93
	s_nop 0
	v_pk_mul_f32 v[18:19], v[20:21], v[96:97] op_sel:[1,1] op_sel_hi:[0,1]
	v_fma_f32 v92, v20, v96, v18
	v_fma_f32 v93, v21, v96, -v19
	s_nop 0
	v_pk_mul_f32 v[18:19], v[22:23], v[98:99] op_sel:[1,1] op_sel_hi:[0,1]
	v_fma_f32 v20, v22, v98, v18
	v_fma_f32 v21, v23, v98, -v19
	s_nop 0
	v_pk_mul_f32 v[18:19], v[86:87], v[100:101] op_sel:[1,1] op_sel_hi:[0,1]
	v_fma_f32 v22, v86, v100, v18
	v_fma_f32 v23, v87, v100, -v19
	s_nop 0
	v_pk_mul_f32 v[18:19], v[88:89], v[102:103] op_sel:[1,1] op_sel_hi:[0,1]
	v_fma_f32 v86, v88, v102, v18
	v_fma_f32 v87, v89, v102, -v19
	s_nop 0
	v_pk_mul_f32 v[18:19], v[90:91], v[194:195] op_sel:[1,1] op_sel_hi:[0,1]
	v_fma_f32 v88, v90, v194, v18
	v_fma_f32 v89, v91, v194, -v19
	s_nop 0
	v_pk_add_f32 v[18:19], v[16:17], v[22:23]
	v_pk_add_f32 v[16:17], v[16:17], v[22:23] neg_lo:[0,1] neg_hi:[0,1]
	v_pk_add_f32 v[22:23], v[196:197], v[86:87]
	v_pk_add_f32 v[86:87], v[196:197], v[86:87] neg_lo:[0,1] neg_hi:[0,1]
	v_pk_add_f32 v[90:91], v[92:93], v[88:89]
	v_pk_add_f32 v[88:89], v[92:93], v[88:89] neg_lo:[0,1] neg_hi:[0,1]
	v_pk_add_f32 v[92:93], v[20:21], v[200:201]
	v_pk_add_f32 v[20:21], v[20:21], v[200:201] neg_lo:[0,1] neg_hi:[0,1]
	v_pk_add_f32 v[94:95], v[86:87], v[86:87] op_sel:[0,1] neg_lo:[0,1] neg_hi:[0,1]
; __device__ __forceinline__ c2 cmulc(c2 a, c2 b) { return (c2){a.x * b.x + a.y * b.y, a.y * b.x - a.x * b.y}; }
; template <int S> __device__ __forceinline__ void inv_mid(c2* buf, const c2* tws, int tid) {
;     constexpr int lq = 9 - 3 * S, Q = 1 << lq; const c2* T = tws + (S == 1 ? 3584 : 4032);
;     const int k = tid & (Q - 1), base = ((tid >> lq) << (lq + 3)) + k;
;     c2 x[8];
;     c2* bp_ = buf + LP(base); constexpr int QP = Q + Q / 8;
; #pragma unroll
;     for (int r = 0; r < 8; ++r) { c2 v = bp_[r * QP]; if (r) v = cmulc(v, T[(r - 1) * Q + k]); x[r] = v; }
;     idft8(x);
; #pragma unroll
;     for (int q = 0; q < 8; ++q) bp_[q * QP] = x[q];
; }
; __device__ __forceinline__ void inv_s0(c2 (&x)[8], const c2* buf, const c2* tws, int tid) {
;     const c2* bp_ = buf + LP(tid);
; #pragma unroll
;     for (int r = 0; r < 8; ++r) { c2 v = bp_[576 * r]; if (r) v = cmulc(v, tws[(r - 1) * 512 + tid]); x[r] = v; }
;     idft8(x);
; }
	v_pk_add_f32 v[86:87], v[86:87], v[86:87] op_sel_hi:[0,1]
	v_mov_b32_e32 v95, v87
	v_xor_b32_e32 v86, 0x80000000, v89
	v_mov_b32_e32 v87, v88
	v_pk_add_f32 v[88:89], v[20:21], v[20:21] op_sel:[0,1]
	v_pk_add_f32 v[20:21], v[20:21], v[20:21] op_sel_hi:[0,1] neg_lo:[0,1] neg_hi:[0,1]
	v_mov_b32_e32 v89, v21
	v_pk_mul_f32 v[20:21], v[88:89], s[84:85]
	v_pk_add_f32 v[88:89], v[18:19], v[90:91]
	v_pk_add_f32 v[18:19], v[18:19], v[90:91] neg_lo:[0,1] neg_hi:[0,1]
	v_pk_add_f32 v[90:91], v[22:23], v[92:93]
	v_pk_add_f32 v[22:23], v[22:23], v[92:93] neg_lo:[0,1] neg_hi:[0,1]
	s_nop 0
	v_xor_b32_e32 v92, 0x80000000, v23
	v_mov_b32_e32 v93, v22
	v_pk_add_f32 v[22:23], v[88:89], v[90:91]
	v_pk_add_f32 v[88:89], v[88:89], v[90:91] neg_lo:[0,1] neg_hi:[0,1]
	v_pk_add_f32 v[90:91], v[18:19], v[92:93]
	v_pk_add_f32 v[18:19], v[18:19], v[92:93] neg_lo:[0,1] neg_hi:[0,1]
	v_pk_add_f32 v[92:93], v[16:17], v[86:87]
	v_pk_add_f32 v[16:17], v[16:17], v[86:87] neg_lo:[0,1] neg_hi:[0,1]
	v_pk_fma_f32 v[86:87], v[94:95], s[20:21], v[20:21] op_sel_hi:[1,0,1]
	v_pk_fma_f32 v[20:21], v[94:95], s[20:21], v[20:21] op_sel_hi:[1,0,1] neg_lo:[0,0,1] neg_hi:[0,0,1]
	s_nop 0
	v_xor_b32_e32 v94, 0x80000000, v21
	v_mov_b32_e32 v95, v20
	v_pk_add_f32 v[20:21], v[92:93], v[86:87]
	v_pk_add_f32 v[86:87], v[92:93], v[86:87] neg_lo:[0,1] neg_hi:[0,1]
	v_pk_add_f32 v[92:93], v[16:17], v[94:95]
	v_pk_add_f32 v[16:17], v[16:17], v[94:95] neg_lo:[0,1] neg_hi:[0,1]
	ds_write2_b64 v191, v[22:23], v[20:21] offset1:72
	ds_write2_b64 v191, v[90:91], v[92:93] offset0:144 offset1:216
	ds_write2_b64 v192, v[88:89], v[86:87] offset0:32 offset1:104
	ds_write2_b64 v192, v[18:19], v[16:17] offset0:176 offset1:248
	s_waitcnt lgkmcnt(0)
	s_barrier
	ds_read2st64_b64 v[20:23], v115 offset1:9
	v_mov_b64_e32 v[98:99], v[210:211]
	v_mov_b64_e32 v[100:101], v[212:213]
	v_mov_b64_e32 v[194:195], v[214:215]
	v_mov_b64_e32 v[196:197], v[216:217]
	ds_read2st64_b64 v[86:89], v115 offset0:36 offset1:45
	s_waitcnt lgkmcnt(0)
	v_pk_mul_f32 v[16:17], v[22:23], v[98:99] op_sel:[0,1]
	s_nop 0
	v_fma_f32 v92, v22, v98, v17
	v_fma_f32 v93, v23, v98, -v16
	s_nop 0
	ds_read2st64_b64 v[16:19], v115 offset0:18 offset1:27
	s_waitcnt lgkmcnt(0)
	v_pk_mul_f32 v[22:23], v[16:17], v[100:101] op_sel:[0,1]
	s_nop 0
	v_fma_f32 v94, v16, v100, v23
	v_fma_f32 v95, v17, v100, -v22
	s_nop 0
	v_pk_mul_f32 v[16:17], v[18:19], v[194:195] op_sel:[0,1]
	s_nop 0
	v_fma_f32 v22, v18, v194, v17
	v_fma_f32 v23, v19, v194, -v16
	s_nop 0
	v_pk_mul_f32 v[16:17], v[86:87], v[196:197] op_sel:[0,1]
	s_nop 0
	v_fma_f32 v96, v86, v196, v17
	v_fma_f32 v97, v87, v196, -v16
	s_nop 0
	v_mov_b64_e32 v[16:17], v[218:219]
	v_mov_b64_e32 v[18:19], v[220:221]
	s_waitcnt lgkmcnt(0)
	v_pk_mul_f32 v[86:87], v[88:89], v[16:17] op_sel:[0,1]
	s_nop 0
	v_fma_f32 v102, v88, v16, v87
	v_fma_f32 v103, v89, v16, -v86
	ds_read2st64_b64 v[88:91], v115 offset0:54 offset1:63
	s_waitcnt lgkmcnt(0)
	v_pk_mul_f32 v[86:87], v[88:89], v[18:19] op_sel:[0,1]
	s_nop 0
	v_fma_f32 v198, v88, v18, v87
	v_fma_f32 v199, v89, v18, -v86
	v_mov_b64_e32 v[88:89], v[222:223]
	s_waitcnt lgkmcnt(0)
	v_pk_mul_f32 v[86:87], v[90:91], v[88:89] op_sel:[0,1]
	s_nop 0
	v_fma_f32 v200, v90, v88, v87
	v_fma_f32 v201, v91, v88, -v86
	v_pk_add_f32 v[90:91], v[92:93], v[102:103]
	v_pk_add_f32 v[92:93], v[92:93], v[102:103] neg_lo:[0,1] neg_hi:[0,1]
	v_pk_add_f32 v[86:87], v[20:21], v[96:97]
	v_pk_add_f32 v[20:21], v[20:21], v[96:97] neg_lo:[0,1] neg_hi:[0,1]
	v_pk_add_f32 v[96:97], v[94:95], v[198:199]
	v_pk_add_f32 v[94:95], v[94:95], v[198:199] neg_lo:[0,1] neg_hi:[0,1]
	v_pk_add_f32 v[102:103], v[22:23], v[200:201]
	v_pk_add_f32 v[22:23], v[22:23], v[200:201] neg_lo:[0,1] neg_hi:[0,1]
	v_pk_add_f32 v[198:199], v[92:93], v[92:93] op_sel:[0,1] neg_lo:[0,1] neg_hi:[0,1]
	v_pk_add_f32 v[92:93], v[92:93], v[92:93] op_sel_hi:[0,1]
	v_mov_b32_e32 v199, v93
	v_xor_b32_e32 v92, 0x80000000, v95
	v_mov_b32_e32 v93, v94
	v_pk_add_f32 v[94:95], v[22:23], v[22:23] op_sel:[0,1]
	v_pk_add_f32 v[22:23], v[22:23], v[22:23] op_sel_hi:[0,1] neg_lo:[0,1] neg_hi:[0,1]
	v_mov_b32_e32 v95, v23
	v_pk_mul_f32 v[22:23], v[94:95], s[84:85]
	v_pk_add_f32 v[94:95], v[86:87], v[96:97]
	v_pk_add_f32 v[86:87], v[86:87], v[96:97] neg_lo:[0,1] neg_hi:[0,1]
	v_pk_add_f32 v[96:97], v[90:91], v[102:103]
	v_pk_add_f32 v[90:91], v[90:91], v[102:103] neg_lo:[0,1] neg_hi:[0,1]
	v_pk_add_f32 v[94:95], v[94:95], v[96:97]
	v_xor_b32_e32 v102, 0x80000000, v91
	v_mov_b32_e32 v103, v90
	v_pk_add_f32 v[90:91], v[86:87], v[102:103]
	v_pk_add_f32 v[86:87], v[20:21], v[92:93]
	v_pk_add_f32 v[20:21], v[20:21], v[92:93] neg_lo:[0,1] neg_hi:[0,1]
	v_pk_fma_f32 v[92:93], v[198:199], s[20:21], v[22:23] op_sel_hi:[1,0,1]
	v_pk_fma_f32 v[22:23], v[198:199], s[20:21], v[22:23] op_sel_hi:[1,0,1] neg_lo:[0,0,1] neg_hi:[0,0,1]
	v_pk_add_f32 v[92:93], v[86:87], v[92:93]
	v_xor_b32_e32 v96, 0x80000000, v23
	v_mov_b32_e32 v97, v22
	v_pk_add_f32 v[86:87], v[20:21], v[96:97]
	ds_read2st64_b64 v[20:23], v115 offset0:72 offset1:81
	ds_read2st64_b64 v[198:201], v115 offset0:90 offset1:99
	s_waitcnt lgkmcnt(0)
	v_pk_mul_f32 v[102:103], v[98:99], v[22:23] op_sel:[1,0]
	s_nop 0
	v_fma_f32 v96, v98, v22, v103
	v_fma_f32 v97, v98, v23, -v102
	s_waitcnt lgkmcnt(0)
	v_pk_mul_f32 v[98:99], v[100:101], v[198:199] op_sel:[1,0]
	v_fma_f32 v22, v100, v198, v99
	v_fma_f32 v23, v100, v199, -v98
	v_pk_mul_f32 v[100:101], v[194:195], v[200:201] op_sel:[1,0]
	v_fma_f32 v98, v194, v200, v101
	v_fma_f32 v99, v194, v201, -v100
	ds_read2st64_b64 v[198:201], v115 offset0:108 offset1:117
	s_waitcnt lgkmcnt(0)
; __device__ __forceinline__ c2 cmulc(c2 a, c2 b) { return (c2){a.x * b.x + a.y * b.y, a.y * b.x - a.x * b.y}; }
; __device__ __forceinline__ void inv_s0(c2 (&x)[8], const c2* buf, const c2* tws, int tid) {
;     const c2* bp_ = buf + LP(tid);
; #pragma unroll
;     for (int r = 0; r < 8; ++r) { c2 v = bp_[576 * r]; if (r) v = cmulc(v, tws[(r - 1) * 512 + tid]); x[r] = v; }
;     idft8(x);
; }
	v_pk_mul_f32 v[102:103], v[196:197], v[198:199] op_sel:[1,0]
	s_nop 0
	v_fma_f32 v100, v196, v198, v103
	v_fma_f32 v101, v196, v199, -v102
	v_pk_mul_f32 v[194:195], v[16:17], v[200:201] op_sel:[1,0]
	v_fma_f32 v102, v16, v200, v195
	v_fma_f32 v103, v16, v201, -v194
	ds_read_b64 v[16:17], v115 offset:64512
	s_waitcnt lgkmcnt(0)
	v_pk_mul_f32 v[194:195], v[18:19], v[16:17] op_sel:[1,0]
	s_nop 0
	v_fma_f32 v196, v18, v16, v195
	v_fma_f32 v197, v18, v17, -v194
	ds_read_b64 v[16:17], v116 offset:32256
	s_waitcnt lgkmcnt(0)
	v_pk_mul_f32 v[18:19], v[88:89], v[16:17] op_sel:[1,0]
	s_nop 0
	v_fma_f32 v194, v88, v16, v19
	v_fma_f32 v195, v88, v17, -v18
	v_pk_add_f32 v[88:89], v[96:97], v[102:103] neg_lo:[0,1] neg_hi:[0,1]
	v_pk_add_f32 v[16:17], v[20:21], v[100:101]
	v_pk_add_f32 v[20:21], v[20:21], v[100:101] neg_lo:[0,1] neg_hi:[0,1]
	v_pk_add_f32 v[18:19], v[96:97], v[102:103]
	v_pk_add_f32 v[96:97], v[22:23], v[196:197]
	v_pk_add_f32 v[22:23], v[22:23], v[196:197] neg_lo:[0,1] neg_hi:[0,1]
	v_pk_add_f32 v[100:101], v[98:99], v[194:195]
	v_pk_add_f32 v[98:99], v[98:99], v[194:195] neg_lo:[0,1] neg_hi:[0,1]
	v_pk_add_f32 v[102:103], v[88:89], v[88:89] op_sel:[0,1] neg_lo:[0,1] neg_hi:[0,1]
	v_pk_add_f32 v[88:89], v[88:89], v[88:89] op_sel_hi:[0,1]
	v_mov_b32_e32 v103, v89
	v_xor_b32_e32 v194, 0x80000000, v23
	v_mov_b32_e32 v195, v22
	v_pk_add_f32 v[22:23], v[98:99], v[98:99] op_sel:[0,1]
	v_pk_add_f32 v[88:89], v[98:99], v[98:99] op_sel_hi:[0,1] neg_lo:[0,1] neg_hi:[0,1]
	v_mov_b32_e32 v23, v89
	v_pk_mul_f32 v[22:23], v[22:23], s[84:85]
	v_pk_add_f32 v[88:89], v[16:17], v[96:97]
	v_pk_add_f32 v[16:17], v[16:17], v[96:97] neg_lo:[0,1] neg_hi:[0,1]
	v_pk_add_f32 v[96:97], v[18:19], v[100:101]
	v_pk_add_f32 v[18:19], v[18:19], v[100:101] neg_lo:[0,1] neg_hi:[0,1]
	v_pk_add_f32 v[88:89], v[88:89], v[96:97]
	v_xor_b32_e32 v98, 0x80000000, v19
	v_mov_b32_e32 v99, v18
	v_pk_fma_f32 v[96:97], v[102:103], s[20:21], v[22:23] op_sel_hi:[1,0,1]
	v_pk_fma_f32 v[22:23], v[102:103], s[20:21], v[22:23] op_sel_hi:[1,0,1] neg_lo:[0,0,1] neg_hi:[0,0,1]
	v_pk_add_f32 v[18:19], v[16:17], v[98:99]
	v_pk_add_f32 v[16:17], v[20:21], v[194:195]
	v_pk_add_f32 v[20:21], v[20:21], v[194:195] neg_lo:[0,1] neg_hi:[0,1]
	v_xor_b32_e32 v98, 0x80000000, v23
	v_mov_b32_e32 v99, v22
	v_pk_add_f32 v[22:23], v[16:17], v[96:97]
	v_pk_add_f32 v[16:17], v[20:21], v[98:99]
	ds_read_u16 v20, v160 offset:14
	ds_read_u16 v21, v160 offset:16
	ds_read_u16 v63, v160 offset:18
	v_pk_mul_f32 v[96:97], v[66:67], v[94:95]
	v_pk_mul_f32 v[22:23], v[66:67], v[22:23]
	s_waitcnt lgkmcnt(0)
	v_lshlrev_b32_e32 v20, 16, v20
	s_waitcnt lgkmcnt(0)
	v_lshlrev_b32_e32 v21, 16, v21
	v_mul_f32_e32 v21, v190, v21
	v_fmac_f32_e32 v21, v187, v20
	s_waitcnt lgkmcnt(0)
	v_lshlrev_b32_e32 v20, 16, v63
	v_fmac_f32_e32 v21, v189, v20
	v_add_f32_e32 v20, v188, v21
	ds_read_u16 v21, v161 offset:14
	ds_read_u16 v63, v161 offset:16
	ds_read_u16 v94, v161 offset:18
	v_fmac_f32_e32 v97, v184, v85
	v_fma_f32 v22, v184, v74, v22
	s_waitcnt lgkmcnt(0)
	v_lshlrev_b32_e32 v21, 16, v21
	s_waitcnt lgkmcnt(0)
	v_lshlrev_b32_e32 v63, 16, v63
	v_mul_f32_e32 v63, v190, v63
	v_fmac_f32_e32 v63, v187, v21
	s_waitcnt lgkmcnt(0)
	v_lshlrev_b32_e32 v21, 16, v94
	v_fmac_f32_e32 v63, v189, v21
	v_fma_f32 v21, v184, v84, v96
	v_mul_f32_e32 v20, v21, v20
	v_cvt_pk_bf16_f32 v84, v20, s0
	v_add_u32_e32 v20, s92, v113
	v_ashrrev_i32_e32 v21, 31, v20
	v_lshl_add_u64 v[94:95], v[20:21], 1, s[50:51]
	v_add_f32_e32 v63, v188, v63
	global_store_short v[94:95], v84, off
	v_add_u32_e32 v84, 0x800, v20
	v_mul_f32_e32 v21, v97, v63
	v_ashrrev_i32_e32 v85, 31, v84
	v_cvt_pk_bf16_f32 v21, v21, s0
	v_lshl_add_u64 v[84:85], v[84:85], 1, s[50:51]
	global_store_short v[84:85], v21, off
	v_pk_mul_f32 v[84:85], v[66:67], v[92:93]
	ds_read_u16 v21, v162 offset:14
	ds_read_u16 v63, v162 offset:16
	ds_read_u16 v92, v162 offset:18
	v_fma_f32 v82, v184, v82, v84
	v_fmac_f32_e32 v85, v184, v83
	s_waitcnt lgkmcnt(0)
	v_lshlrev_b32_e32 v21, 16, v21
	s_waitcnt lgkmcnt(0)
	v_lshlrev_b32_e32 v63, 16, v63
	v_mul_f32_e32 v63, v190, v63
	v_fmac_f32_e32 v63, v187, v21
	s_waitcnt lgkmcnt(0)
	v_lshlrev_b32_e32 v21, 16, v92
	v_fmac_f32_e32 v63, v189, v21
	v_add_f32_e32 v21, v188, v63
	ds_read_u16 v63, v163 offset:14
	ds_read_u16 v92, v163 offset:16
	ds_read_u16 v93, v163 offset:18
	v_mul_f32_e32 v21, v82, v21
	v_cvt_pk_bf16_f32 v21, v21, s0
	s_waitcnt lgkmcnt(0)
	v_lshlrev_b32_e32 v63, 16, v63
	s_waitcnt lgkmcnt(0)
	v_lshlrev_b32_e32 v92, 16, v92
	v_mul_f32_e32 v92, v190, v92
	v_fmac_f32_e32 v92, v187, v63
	s_waitcnt lgkmcnt(0)
	v_lshlrev_b32_e32 v63, 16, v93
	v_fmac_f32_e32 v92, v189, v63
	v_add_f32_e32 v63, v188, v92
	v_add_u32_e32 v82, 0xa00, v20
	global_store_short v[94:95], v21, off offset:1024
	v_mul_f32_e32 v21, v85, v63
	v_ashrrev_i32_e32 v83, 31, v82
	v_cvt_pk_bf16_f32 v21, v21, s0
	v_lshl_add_u64 v[82:83], v[82:83], 1, s[50:51]
	global_store_short v[82:83], v21, off
	ds_read_u16 v21, v164 offset:14
	ds_read_u16 v63, v164 offset:16
	ds_read_u16 v84, v164 offset:18
	v_pk_mul_f32 v[82:83], v[66:67], v[90:91]
	v_fmac_f32_e32 v23, v184, v75
	s_waitcnt lgkmcnt(0)
	v_lshlrev_b32_e32 v21, 16, v21
	s_waitcnt lgkmcnt(0)
	v_lshlrev_b32_e32 v63, 16, v63
	v_mul_f32_e32 v63, v190, v63
	v_fmac_f32_e32 v63, v187, v21
	s_waitcnt lgkmcnt(0)
	v_lshlrev_b32_e32 v21, 16, v84
	v_fmac_f32_e32 v63, v189, v21
	v_add_f32_e32 v21, v188, v63
	ds_read_u16 v63, v165 offset:14
	ds_read_u16 v84, v165 offset:16
	ds_read_u16 v85, v165 offset:18
	v_fma_f32 v78, v184, v78, v82
	v_mul_f32_e32 v21, v78, v21
	s_waitcnt lgkmcnt(0)
	v_lshlrev_b32_e32 v63, 16, v63
	s_waitcnt lgkmcnt(0)
; __device__ __forceinline__ c2 cmul(c2 a, c2 b) { return (c2){a.x * b.x - a.y * b.y, a.x * b.y + a.y * b.x}; }
; #define ZVAL(r, t) ((o == 0) ? dwl((r), (t), zw0, zw1, zw2, zb) : bf2f((r)[8 + (t)]))
; __device__ __forceinline__ void phase_conv(const Params& p, int o, unsigned char* smem, int wave) {
;     ...
;             for (int i = 0; i < 8; ++i) {
;                 const int gq = i * 8192;
;                 __syncthreads();
;                 quad_store(R, raw, tid);
;                 __syncthreads();
;                 if (i < 7) R = quad_load(zrow, grow, gq + 8192, false, true, true, tid);
;                 c2 x0[8], x1[8], zk0[4], zk1[4];
; #pragma unroll
;                 for (int r = 0; r < 4; ++r) { const int t = tid + 512 * r;
;                     x0[r] = (c2){ZVAL(raw, t), ZVAL(raw + RAWROW, t)}; x1[r] = (c2){ZVAL(raw + 2 * RAWROW, t), ZVAL(raw + 3 * RAWROW, t)}; zk0[r] = x0[r]; zk1[r] = x1[r];
;                     x0[4 + r] = (c2){0.f, 0.f}; x1[4 + r] = (c2){0.f, 0.f}; }
;                 fft_fwd_regs2(x0, x1, buf0, buf1, tws, tid);
; #pragma unroll
;                 for (int q = 0; q < 8; ++q) { x0[q] = cmul(x0[q], K[q]); x1[q] = cmul(x1[q], K[q]); }
;                 fft_inv_regs2(x0, x1, buf0, buf1, tws, tid);
;                 EPIZ(x0, zk0, 0, gq); EPIZ(x1, zk1, 2, gq);
;             }
	v_lshlrev_b32_e32 v84, 16, v84
	v_mul_f32_e32 v84, v190, v84
	v_fmac_f32_e32 v84, v187, v63
	s_waitcnt lgkmcnt(0)
	v_lshlrev_b32_e32 v63, 16, v85
	v_fmac_f32_e32 v84, v189, v63
	v_add_f32_e32 v63, v188, v84
	v_cvt_pk_bf16_f32 v21, v21, s0
	v_fmac_f32_e32 v83, v184, v79
	v_add_u32_e32 v78, 0xc00, v20
	global_store_short v[94:95], v21, off offset:2048
	v_mul_f32_e32 v21, v83, v63
	v_ashrrev_i32_e32 v79, 31, v78
	v_cvt_pk_bf16_f32 v21, v21, s0
	v_lshl_add_u64 v[78:79], v[78:79], 1, s[50:51]
	global_store_short v[78:79], v21, off
	ds_read_u16 v21, v166 offset:14
	ds_read_u16 v63, v166 offset:16
	ds_read_u16 v82, v166 offset:18
	v_pk_mul_f32 v[78:79], v[66:67], v[86:87]
	v_pk_mul_f32 v[18:19], v[66:67], v[18:19]
	s_waitcnt lgkmcnt(0)
	v_lshlrev_b32_e32 v21, 16, v21
	s_waitcnt lgkmcnt(0)
	v_lshlrev_b32_e32 v63, 16, v63
	v_mul_f32_e32 v63, v190, v63
	v_fmac_f32_e32 v63, v187, v21
	s_waitcnt lgkmcnt(0)
	v_lshlrev_b32_e32 v21, 16, v82
	v_fmac_f32_e32 v63, v189, v21
	v_add_f32_e32 v21, v188, v63
	ds_read_u16 v63, v167 offset:14
	ds_read_u16 v82, v167 offset:16
	ds_read_u16 v83, v167 offset:18
	v_fma_f32 v78, v184, v80, v78
	v_mul_f32_e32 v21, v78, v21
	s_waitcnt lgkmcnt(0)
	v_lshlrev_b32_e32 v63, 16, v63
	s_waitcnt lgkmcnt(0)
	v_lshlrev_b32_e32 v82, 16, v82
	v_mul_f32_e32 v82, v190, v82
	v_fmac_f32_e32 v82, v187, v63
	s_waitcnt lgkmcnt(0)
	v_lshlrev_b32_e32 v63, 16, v83
	v_fmac_f32_e32 v82, v189, v63
	v_add_f32_e32 v63, v188, v82
	v_cvt_pk_bf16_f32 v21, v21, s0
	v_fmac_f32_e32 v79, v184, v81
	v_add_u32_e32 v78, 0xe00, v20
	global_store_short v[94:95], v21, off offset:3072
	v_mul_f32_e32 v21, v79, v63
	v_ashrrev_i32_e32 v79, 31, v78
	v_cvt_pk_bf16_f32 v21, v21, s0
	v_lshl_add_u64 v[78:79], v[78:79], 1, s[50:51]
	global_store_short v[78:79], v21, off
	ds_read_u16 v21, v168 offset:14
	ds_read_u16 v63, v168 offset:16
	ds_read_u16 v80, v168 offset:18
	v_pk_mul_f32 v[78:79], v[66:67], v[88:89]
	v_fma_f32 v18, v184, v72, v18
	s_waitcnt lgkmcnt(0)
	v_lshlrev_b32_e32 v21, 16, v21
	s_waitcnt lgkmcnt(0)
	v_lshlrev_b32_e32 v63, 16, v63
	v_mul_f32_e32 v63, v190, v63
	v_fmac_f32_e32 v63, v187, v21
	s_waitcnt lgkmcnt(0)
	v_lshlrev_b32_e32 v21, 16, v80
	v_fmac_f32_e32 v63, v189, v21
	v_add_f32_e32 v21, v188, v63
	ds_read_u16 v63, v169 offset:14
	ds_read_u16 v80, v169 offset:16
	ds_read_u16 v81, v169 offset:18
	v_fma_f32 v76, v184, v76, v78
	v_mul_f32_e32 v21, v76, v21
	s_waitcnt lgkmcnt(0)
	v_lshlrev_b32_e32 v63, 16, v63
	s_waitcnt lgkmcnt(0)
	v_lshlrev_b32_e32 v80, 16, v80
	v_mul_f32_e32 v80, v190, v80
	v_fmac_f32_e32 v80, v187, v63
	s_waitcnt lgkmcnt(0)
	v_lshlrev_b32_e32 v63, 16, v81
	v_fmac_f32_e32 v80, v189, v63
	v_add_f32_e32 v63, v188, v80
	v_add_u32_e32 v80, 0x1000, v20
	v_ashrrev_i32_e32 v81, 31, v80
	v_cvt_pk_bf16_f32 v21, v21, s0
	v_lshl_add_u64 v[80:81], v[80:81], 1, s[50:51]
	v_fmac_f32_e32 v79, v184, v77
	v_add_u32_e32 v76, 0x1800, v20
	global_store_short v[80:81], v21, off
	v_mul_f32_e32 v21, v79, v63
	v_ashrrev_i32_e32 v77, 31, v76
	v_cvt_pk_bf16_f32 v21, v21, s0
	v_lshl_add_u64 v[76:77], v[76:77], 1, s[50:51]
	global_store_short v[76:77], v21, off
	ds_read_u16 v21, v170 offset:14
	ds_read_u16 v63, v170 offset:16
	ds_read_u16 v76, v170 offset:18
	v_fmac_f32_e32 v19, v184, v73
	v_pk_mul_f32 v[16:17], v[66:67], v[16:17]
	s_waitcnt lgkmcnt(0)
	v_lshlrev_b32_e32 v21, 16, v21
	s_waitcnt lgkmcnt(0)
	v_lshlrev_b32_e32 v63, 16, v63
	v_mul_f32_e32 v63, v190, v63
	v_fmac_f32_e32 v63, v187, v21
	s_waitcnt lgkmcnt(0)
	v_lshlrev_b32_e32 v21, 16, v76
	v_fmac_f32_e32 v63, v189, v21
	v_add_f32_e32 v21, v188, v63
	ds_read_u16 v63, v171 offset:14
	ds_read_u16 v76, v171 offset:16
	ds_read_u16 v77, v171 offset:18
	v_mul_f32_e32 v21, v22, v21
	v_cvt_pk_bf16_f32 v21, v21, s0
	s_waitcnt lgkmcnt(0)
	v_lshlrev_b32_e32 v63, 16, v63
	s_waitcnt lgkmcnt(0)
	v_lshlrev_b32_e32 v76, 16, v76
	v_mul_f32_e32 v76, v190, v76
	v_fmac_f32_e32 v76, v187, v63
	s_waitcnt lgkmcnt(0)
	v_lshlrev_b32_e32 v63, 16, v77
	v_fmac_f32_e32 v76, v189, v63
	v_add_f32_e32 v63, v188, v76
	v_add_u32_e32 v76, 0x1200, v20
	v_ashrrev_i32_e32 v77, 31, v76
	v_lshl_add_u64 v[76:77], v[76:77], 1, s[50:51]
	v_add_u32_e32 v22, 0x1a00, v20
	global_store_short v[76:77], v21, off
	v_mul_f32_e32 v21, v23, v63
	v_ashrrev_i32_e32 v23, 31, v22
	v_cvt_pk_bf16_f32 v21, v21, s0
	v_lshl_add_u64 v[22:23], v[22:23], 1, s[50:51]
	global_store_short v[22:23], v21, off
	ds_read_u16 v21, v172 offset:14
	ds_read_u16 v22, v172 offset:16
	ds_read_u16 v23, v172 offset:18
	v_fma_f32 v16, v184, v70, v16
	v_fmac_f32_e32 v17, v184, v71
	s_waitcnt lgkmcnt(0)
	v_lshlrev_b32_e32 v21, 16, v21
	s_waitcnt lgkmcnt(0)
	v_lshlrev_b32_e32 v22, 16, v22
	v_mul_f32_e32 v22, v190, v22
	v_fmac_f32_e32 v22, v187, v21
	s_waitcnt lgkmcnt(0)
	v_lshlrev_b32_e32 v21, 16, v23
	v_fmac_f32_e32 v22, v189, v21
	v_add_f32_e32 v21, v188, v22
	ds_read_u16 v22, v173 offset:14
	ds_read_u16 v23, v173 offset:16
	ds_read_u16 v63, v173 offset:18
	v_mul_f32_e32 v18, v18, v21
	v_cvt_pk_bf16_f32 v18, v18, s0
	s_waitcnt lgkmcnt(0)
	v_lshlrev_b32_e32 v22, 16, v22
	s_waitcnt lgkmcnt(0)
	v_lshlrev_b32_e32 v23, 16, v23
	v_mul_f32_e32 v23, v190, v23
	v_fmac_f32_e32 v23, v187, v22
	s_waitcnt lgkmcnt(0)
	v_lshlrev_b32_e32 v22, 16, v63
	v_fmac_f32_e32 v23, v189, v22
	v_add_u32_e32 v22, 0x1400, v20
	v_add_f32_e32 v63, v188, v23
	v_ashrrev_i32_e32 v23, 31, v22
	v_lshl_add_u64 v[22:23], v[22:23], 1, s[50:51]
	global_store_short v[22:23], v18, off
	v_mul_f32_e32 v18, v19, v63
	v_cvt_pk_bf16_f32 v21, v18, s0
	v_add_u32_e32 v18, 0x1c00, v20
	v_ashrrev_i32_e32 v19, 31, v18
	v_lshl_add_u64 v[18:19], v[18:19], 1, s[50:51]
	global_store_short v[18:19], v21, off
	ds_read_u16 v18, v174 offset:14
	ds_read_u16 v19, v174 offset:16
	ds_read_u16 v21, v174 offset:18
	s_addk_i32 s92, 0x2000
	s_cmp_eq_u32 s92, 0x10000
	s_waitcnt lgkmcnt(0)
	v_lshlrev_b32_e32 v18, 16, v18
	s_waitcnt lgkmcnt(0)
	v_lshlrev_b32_e32 v19, 16, v19
	v_mul_f32_e32 v19, v190, v19
	v_fmac_f32_e32 v19, v187, v18
	s_waitcnt lgkmcnt(0)
	v_lshlrev_b32_e32 v18, 16, v21
	v_fmac_f32_e32 v19, v189, v18
	v_add_f32_e32 v18, v188, v19
	ds_read_u16 v19, v175 offset:14
	ds_read_u16 v21, v175 offset:16
	ds_read_u16 v22, v175 offset:18
	v_mul_f32_e32 v16, v16, v18
	v_add_u32_e32 v18, 0x1600, v20
	s_waitcnt lgkmcnt(0)
	v_lshlrev_b32_e32 v19, 16, v19
	s_waitcnt lgkmcnt(0)
	v_lshlrev_b32_e32 v21, 16, v21
	v_mul_f32_e32 v21, v190, v21
	v_fmac_f32_e32 v21, v187, v19
	s_waitcnt lgkmcnt(0)
	v_lshlrev_b32_e32 v19, 16, v22
	v_fmac_f32_e32 v21, v189, v19
	v_ashrrev_i32_e32 v19, 31, v18
	v_add_f32_e32 v21, v188, v21
	v_cvt_pk_bf16_f32 v16, v16, s0
	v_lshl_add_u64 v[18:19], v[18:19], 1, s[50:51]
	global_store_short v[18:19], v16, off
	v_mul_f32_e32 v16, v17, v21
	v_cvt_pk_bf16_f32 v18, v16, s0
	v_add_u32_e32 v16, 0x1e00, v20
	v_ashrrev_i32_e32 v17, 31, v16
	v_lshl_add_u64 v[16:17], v[16:17], 1, s[50:51]
	global_store_short v[16:17], v18, off
	s_cbranch_scc1 .LBB0_379

; __device__ __forceinline__ c2 cmul(c2 a, c2 b) { return (c2){a.x * b.x - a.y * b.y, a.x * b.y + a.y * b.x}; }
; __device__ __forceinline__ c2 mni(c2 a) { return (c2){a.y, -a.x}; }
; __device__ __forceinline__ void dft8(c2 (&x)[8]) {
;     const float s = 0.70710678118654752f;
;     const c2 a0 = x[0] + x[4], a4 = x[0] - x[4], a1 = x[1] + x[5], a5 = x[1] - x[5], a2 = x[2] + x[6], a6 = x[2] - x[6], a3 = x[3] + x[7], a7 = x[3] - x[7];
;     const c2 a5w = (c2){(a5.x + a5.y) * s, (a5.y - a5.x) * s};
;     const c2 a6w = mni(a6);
;     const c2 a7w = (c2){(a7.y - a7.x) * s, -(a7.x + a7.y) * s};
;     const c2 b0 = a0 + a2, b1 = a0 - a2, b2 = a1 + a3, b3 = mni(a1 - a3);
;     x[0] = b0 + b2; x[4] = b0 - b2; x[2] = b1 + b3; x[6] = b1 - b3;
;     const c2 c0 = a4 + a6w, c1 = a4 - a6w, c2_ = a5w + a7w, c3 = mni(a5w - a7w);
;     x[1] = c0 + c2_; x[5] = c0 - c2_; x[3] = c1 + c3; x[7] = c1 - c3;
; }
; __device__ __forceinline__ c2 mpi(c2 a) { return (c2){-a.y, a.x}; }
; __device__ __forceinline__ void idft8(c2 (&x)[8]) {
;     const float s = 0.70710678118654752f;
;     const c2 a0 = x[0] + x[4], a4 = x[0] - x[4], a1 = x[1] + x[5], a5 = x[1] - x[5], a2 = x[2] + x[6], a6 = x[2] - x[6], a3 = x[3] + x[7], a7 = x[3] - x[7];
;     const c2 a5w = (c2){(a5.x - a5.y) * s, (a5.x + a5.y) * s};
;     const c2 a6w = mpi(a6);
;     const c2 a7w = (c2){-(a7.x + a7.y) * s, (a7.x - a7.y) * s};
;     const c2 b0 = a0 + a2, b1 = a0 - a2, b2 = a1 + a3, b3 = mpi(a1 - a3);
;     x[0] = b0 + b2; x[4] = b0 - b2; x[2] = b1 + b3; x[6] = b1 - b3;
;     const c2 c0 = a4 + a6w, c1 = a4 - a6w, c2_ = a5w + a7w, c3 = mpi(a5w - a7w);
;     x[1] = c0 + c2_; x[5] = c0 - c2_; x[3] = c1 + c3; x[7] = c1 - c3;
; }
; __device__ __forceinline__ void fwd_s0(c2 (&x)[8], c2* buf, const c2* tws, int tid) {
;     dft8(x);
; #pragma unroll
;     for (int q = 1; q < 8; ++q) x[q] = cmul(x[q], tws[(q - 1) * 512 + tid]);
;     { c2* bp_ = buf + LP(tid);
; #pragma unroll
;     for (int q = 0; q < 8; ++q) bp_[576 * q] = x[q]; }
; }
.LBB0_480:
	s_or_b64 exec, exec, s[72:73]
	s_waitcnt vmcnt(0)
	v_pk_add_f32 v[16:17], v[2:3], v[10:11]
	v_sub_f32_e32 v56, v2, v10
	v_sub_f32_e32 v10, v3, v11
	v_pk_add_f32 v[2:3], v[6:7], v[14:15]
	v_sub_f32_e32 v15, v7, v15
	s_barrier
	v_sub_f32_e32 v11, v6, v14
	v_sub_f32_e32 v14, 0, v15
	v_add_f32_e32 v15, 0, v15
	v_pk_add_f32 v[18:19], v[16:17], v[2:3] neg_lo:[0,1] neg_hi:[0,1]
	v_add_f32_e32 v6, 0, v10
	v_sub_f32_e32 v7, 0, v10
	v_pk_mul_f32 v[14:15], v[14:15], s[20:21]
	v_pk_add_f32 v[2:3], v[16:17], v[2:3]
	v_pk_add_f32 v[16:17], v[18:19], 0 neg_lo:[1,1] neg_hi:[1,1]
	v_xor_b32_e32 v11, 0x80000000, v11
	v_mov_b32_e32 v10, v57
	v_mov_b32_e32 v20, v18
	v_mov_b32_e32 v21, v57
	v_mov_b32_e32 v16, v57
	v_pk_fma_f32 v[24:25], v[6:7], s[20:21], v[14:15] op_sel_hi:[1,0,1]
	v_pk_fma_f32 v[6:7], v[6:7], s[20:21], v[14:15] op_sel_hi:[1,0,1] neg_lo:[0,0,1] neg_hi:[0,0,1]
	v_pk_add_f32 v[22:23], v[20:21], v[16:17]
	v_pk_add_f32 v[16:17], v[20:21], v[16:17] neg_lo:[0,1] neg_hi:[0,1]
	v_pk_add_f32 v[20:21], v[56:57], v[10:11]
	v_pk_add_f32 v[10:11], v[56:57], v[10:11] neg_lo:[0,1] neg_hi:[0,1]
	v_xor_b32_e32 v15, 0x80000000, v6
	v_mov_b32_e32 v14, v7
	v_pk_add_f32 v[6:7], v[20:21], v[24:25]
	v_pk_add_f32 v[20:21], v[20:21], v[24:25] neg_lo:[0,1] neg_hi:[0,1]
	v_pk_add_f32 v[24:25], v[10:11], v[14:15]
	v_pk_add_f32 v[10:11], v[10:11], v[14:15] neg_lo:[0,1] neg_hi:[0,1]
	s_waitcnt lgkmcnt(0)
	v_pk_mul_f32 v[32:33], v[6:7], v[210:211] op_sel:[1,1] op_sel_hi:[1,0]
	v_pk_add_f32 v[18:19], v[2:3], v[2:3] op_sel:[0,1] op_sel_hi:[1,0]
	v_fma_f32 v34, v6, v210, -v32
	v_fma_f32 v35, v6, v211, v33
	s_waitcnt lgkmcnt(0)
	v_pk_mul_f32 v[6:7], v[22:23], v[212:213] op_sel:[1,1] op_sel_hi:[1,0]
	v_pk_add_f32 v[2:3], v[2:3], v[2:3] op_sel:[0,1] op_sel_hi:[0,1] neg_lo:[0,1] neg_hi:[0,1]
	v_fma_f32 v26, v22, v212, -v6
	v_fma_f32 v27, v22, v213, v7
	s_waitcnt lgkmcnt(0)
	v_pk_mul_f32 v[6:7], v[24:25], v[214:215] op_sel:[1,1] op_sel_hi:[1,0]
	v_mov_b32_e32 v19, v57
	v_fma_f32 v14, v24, v214, -v6
	v_fma_f32 v15, v24, v215, v7
	s_waitcnt lgkmcnt(0)
	v_pk_mul_f32 v[6:7], v[216:217], 0 op_sel_hi:[1,0]
	v_sub_f32_e32 v56, v0, v8
	v_fma_f32 v22, v2, v216, -v7
	v_fma_f32 v23, v3, v217, v6
	s_waitcnt lgkmcnt(0)
	v_pk_mul_f32 v[28:29], v[20:21], v[218:219] op_sel:[1,1] op_sel_hi:[1,0]
	v_mov_b64_e32 v[6:7], v[222:223]
	v_fma_f32 v30, v20, v218, -v28
	v_fma_f32 v31, v20, v219, v29
	s_waitcnt lgkmcnt(0)
	v_pk_mul_f32 v[20:21], v[16:17], v[220:221] op_sel:[1,1] op_sel_hi:[1,0]
	v_add_u32_e32 v63, 0x800, v117
	v_fma_f32 v24, v16, v220, -v20
	v_fma_f32 v25, v16, v221, v21
	s_waitcnt lgkmcnt(0)
	v_pk_mul_f32 v[2:3], v[10:11], v[6:7] op_sel:[1,1] op_sel_hi:[1,0]
	v_add_u32_e32 v191, 0x9000, v117
	v_fma_f32 v16, v10, v6, -v2
	v_fma_f32 v17, v10, v7, v3
	ds_write2st64_b64 v115, v[18:19], v[34:35] offset1:9
	ds_write2st64_b64 v115, v[26:27], v[14:15] offset0:18 offset1:27
	ds_write2st64_b64 v115, v[22:23], v[30:31] offset0:36 offset1:45
	ds_write2st64_b64 v115, v[24:25], v[16:17] offset0:54 offset1:63
	v_pk_add_f32 v[2:3], v[0:1], v[8:9]
	v_sub_f32_e32 v6, v1, v9
	v_pk_add_f32 v[0:1], v[4:5], v[12:13]
	v_sub_f32_e32 v9, v5, v13
	v_sub_f32_e32 v8, 0, v9
	v_add_f32_e32 v9, 0, v9
	v_pk_add_f32 v[10:11], v[2:3], v[0:1] neg_lo:[0,1] neg_hi:[0,1]
	v_sub_f32_e32 v7, v4, v12
	v_add_f32_e32 v4, 0, v6
	v_sub_f32_e32 v5, 0, v6
	v_pk_mul_f32 v[8:9], v[8:9], s[20:21]
	v_pk_add_f32 v[0:1], v[2:3], v[0:1]
	v_pk_add_f32 v[2:3], v[10:11], 0 neg_lo:[1,1] neg_hi:[1,1]
	v_xor_b32_e32 v7, 0x80000000, v7
	v_mov_b32_e32 v6, v57
	v_mov_b32_e32 v12, v10
	v_mov_b32_e32 v13, v57
	v_mov_b32_e32 v2, v57
	v_pk_fma_f32 v[16:17], v[4:5], s[20:21], v[8:9] op_sel_hi:[1,0,1]
	v_pk_fma_f32 v[4:5], v[4:5], s[20:21], v[8:9] op_sel_hi:[1,0,1] neg_lo:[0,0,1] neg_hi:[0,0,1]
	v_pk_add_f32 v[14:15], v[12:13], v[2:3]
	v_pk_add_f32 v[2:3], v[12:13], v[2:3] neg_lo:[0,1] neg_hi:[0,1]
	v_pk_add_f32 v[12:13], v[56:57], v[6:7]
	v_pk_add_f32 v[6:7], v[56:57], v[6:7] neg_lo:[0,1] neg_hi:[0,1]
	v_xor_b32_e32 v9, 0x80000000, v4
	v_mov_b32_e32 v8, v5
	v_pk_add_f32 v[4:5], v[12:13], v[16:17]
	v_pk_add_f32 v[12:13], v[12:13], v[16:17] neg_lo:[0,1] neg_hi:[0,1]
	v_pk_add_f32 v[16:17], v[6:7], v[8:9]
	v_pk_add_f32 v[6:7], v[6:7], v[8:9] neg_lo:[0,1] neg_hi:[0,1]
	s_waitcnt lgkmcnt(0)
	v_pk_mul_f32 v[24:25], v[4:5], v[210:211] op_sel:[1,1] op_sel_hi:[1,0]
	v_pk_add_f32 v[10:11], v[0:1], v[0:1] op_sel:[0,1] op_sel_hi:[1,0]
	v_fma_f32 v26, v4, v210, -v24
	v_fma_f32 v27, v4, v211, v25
	s_waitcnt lgkmcnt(0)
	v_pk_mul_f32 v[4:5], v[14:15], v[212:213] op_sel:[1,1] op_sel_hi:[1,0]
	v_pk_add_f32 v[0:1], v[0:1], v[0:1] op_sel:[0,1] op_sel_hi:[0,1] neg_lo:[0,1] neg_hi:[0,1]
	v_fma_f32 v18, v14, v212, -v4
	v_fma_f32 v19, v14, v213, v5
	s_waitcnt lgkmcnt(0)
	v_pk_mul_f32 v[4:5], v[16:17], v[214:215] op_sel:[1,1] op_sel_hi:[1,0]
	v_mov_b32_e32 v11, v57
	v_fma_f32 v8, v16, v214, -v4
	v_fma_f32 v9, v16, v215, v5
	s_waitcnt lgkmcnt(0)
	v_pk_mul_f32 v[4:5], v[216:217], 0 op_sel_hi:[1,0]
	v_add_u32_e32 v192, 0x9800, v117
	v_fma_f32 v14, v0, v216, -v5
	v_fma_f32 v15, v1, v217, v4
	s_waitcnt lgkmcnt(0)
	v_pk_mul_f32 v[20:21], v[12:13], v[218:219] op_sel:[1,1] op_sel_hi:[1,0]
	v_mov_b64_e32 v[4:5], v[222:223]
	v_fma_f32 v22, v12, v218, -v20
	v_fma_f32 v23, v12, v219, v21
	s_waitcnt lgkmcnt(0)
	v_pk_mul_f32 v[12:13], v[2:3], v[220:221] op_sel:[1,1] op_sel_hi:[1,0]
	v_add_u32_e32 v193, 0x9000, v119
	v_fma_f32 v16, v2, v220, -v12
	v_fma_f32 v17, v2, v221, v13
	s_waitcnt lgkmcnt(0)
	v_pk_mul_f32 v[0:1], v[6:7], v[4:5] op_sel:[1,1] op_sel_hi:[1,0]
	v_add_u32_e32 v194, 0x9000, v121
	v_fma_f32 v2, v6, v4, -v0
	v_fma_f32 v3, v6, v5, v1
	ds_write2st64_b64 v115, v[10:11], v[26:27] offset0:72 offset1:81
	ds_write2st64_b64 v115, v[18:19], v[8:9] offset0:90 offset1:99
	ds_write2st64_b64 v115, v[14:15], v[22:23] offset0:108 offset1:117
	ds_write_b64 v115, v[16:17] offset:64512
	ds_write_b64 v116, v[2:3] offset:32256
	s_waitcnt lgkmcnt(0)
	s_barrier
; __device__ __forceinline__ c2 cmul(c2 a, c2 b) { return (c2){a.x * b.x - a.y * b.y, a.x * b.y + a.y * b.x}; }
; template <int S> __device__ __forceinline__ void fwd_mid(c2* buf, const c2* tws, int tid) {
;     constexpr int lq = 9 - 3 * S, Q = 1 << lq; const c2* T = tws + (S == 1 ? 3584 : 4032);
;     const int k = tid & (Q - 1), base = ((tid >> lq) << (lq + 3)) + k;
;     c2 x[8];
;     c2* bp_ = buf + LP(base); constexpr int QP = Q + Q / 8;
; #pragma unroll
;     for (int r = 0; r < 8; ++r) x[r] = bp_[r * QP];
;     dft8(x);
; #pragma unroll
;     for (int q = 1; q < 8; ++q) x[q] = cmul(x[q], T[(q - 1) * Q + k]);
; #pragma unroll
;     for (int q = 0; q < 8; ++q) bp_[q * QP] = x[q];
; }
	ds_read2_b64 v[0:3], v117 offset1:72
	ds_read2_b64 v[4:7], v63 offset0:32 offset1:104
	ds_read2_b64 v[8:11], v117 offset0:144 offset1:216
	ds_read2_b64 v[12:15], v63 offset0:176 offset1:248
	v_mov_b64_e32 v[18:19], v[224:225]
	v_add_u32_e32 v195, 0x9020, v121
	v_add_u32_e32 v196, 0x9010, v121
	s_waitcnt lgkmcnt(0)
	v_pk_add_f32 v[16:17], v[0:1], v[4:5]
	v_pk_add_f32 v[0:1], v[0:1], v[4:5] neg_lo:[0,1] neg_hi:[0,1]
	v_pk_add_f32 v[4:5], v[2:3], v[6:7]
	v_pk_add_f32 v[2:3], v[2:3], v[6:7] neg_lo:[0,1] neg_hi:[0,1]
	s_waitcnt lgkmcnt(0)
	v_pk_add_f32 v[6:7], v[8:9], v[12:13]
	v_pk_add_f32 v[8:9], v[8:9], v[12:13] neg_lo:[0,1] neg_hi:[0,1]
	v_pk_add_f32 v[12:13], v[10:11], v[14:15]
	v_pk_add_f32 v[10:11], v[10:11], v[14:15] neg_lo:[0,1] neg_hi:[0,1]
	v_pk_add_f32 v[14:15], v[2:3], v[2:3] op_sel:[1,0]
	v_pk_add_f32 v[2:3], v[2:3], v[2:3] op_sel_hi:[1,0] neg_lo:[0,1] neg_hi:[0,1]
	v_add_u32_e32 v197, 0x9030, v121
	v_mov_b32_e32 v15, v3
	v_xor_b32_e32 v3, 0x80000000, v8
	v_mov_b32_e32 v2, v9
	v_pk_add_f32 v[8:9], v[10:11], v[10:11] op_sel:[1,0] neg_lo:[0,1] neg_hi:[0,1]
	v_pk_add_f32 v[10:11], v[10:11], v[10:11] op_sel_hi:[1,0]
	s_andn2_b64 vcc, exec, s[70:71]
	v_mov_b32_e32 v9, v11
	v_pk_add_f32 v[10:11], v[16:17], v[6:7]
	v_pk_add_f32 v[6:7], v[16:17], v[6:7] neg_lo:[0,1] neg_hi:[0,1]
	v_pk_add_f32 v[16:17], v[4:5], v[12:13]
	v_pk_add_f32 v[4:5], v[4:5], v[12:13] neg_lo:[0,1] neg_hi:[0,1]
	v_pk_mul_f32 v[8:9], v[8:9], s[20:21]
	v_xor_b32_e32 v13, 0x80000000, v4
	v_mov_b32_e32 v12, v5
	v_pk_add_f32 v[4:5], v[10:11], v[16:17]
	v_pk_add_f32 v[10:11], v[10:11], v[16:17] neg_lo:[0,1] neg_hi:[0,1]
	v_pk_add_f32 v[16:17], v[6:7], v[12:13]
	v_pk_add_f32 v[6:7], v[6:7], v[12:13] neg_lo:[0,1] neg_hi:[0,1]
	v_pk_add_f32 v[12:13], v[0:1], v[2:3]
	v_pk_add_f32 v[0:1], v[0:1], v[2:3] neg_lo:[0,1] neg_hi:[0,1]
	v_pk_fma_f32 v[2:3], v[14:15], s[20:21], v[8:9] op_sel_hi:[1,0,1]
	v_pk_fma_f32 v[8:9], v[14:15], s[20:21], v[8:9] op_sel_hi:[1,0,1] neg_lo:[0,0,1] neg_hi:[0,0,1]
	s_nop 0
	v_xor_b32_e32 v15, 0x80000000, v8
	v_mov_b32_e32 v14, v9
	v_pk_add_f32 v[8:9], v[12:13], v[2:3]
	v_pk_add_f32 v[2:3], v[12:13], v[2:3] neg_lo:[0,1] neg_hi:[0,1]
	v_pk_add_f32 v[12:13], v[0:1], v[14:15]
	v_pk_add_f32 v[0:1], v[0:1], v[14:15] neg_lo:[0,1] neg_hi:[0,1]
	s_waitcnt lgkmcnt(0)
	v_pk_mul_f32 v[24:25], v[18:19], v[8:9] op_sel:[1,1] op_sel_hi:[0,1]
	v_fma_f32 v26, v18, v8, -v24
	v_fma_f32 v27, v19, v8, v25
	s_nop 0
	s_waitcnt lgkmcnt(0)
	v_pk_mul_f32 v[8:9], v[226:227], v[16:17] op_sel:[1,1] op_sel_hi:[0,1]
	v_fma_f32 v18, v226, v16, -v8
	v_fma_f32 v19, v227, v16, v9
	s_waitcnt lgkmcnt(0)
	v_pk_mul_f32 v[8:9], v[228:229], v[12:13] op_sel:[1,1] op_sel_hi:[0,1]
	v_fma_f32 v14, v228, v12, -v8
	v_fma_f32 v15, v229, v12, v9
	s_waitcnt lgkmcnt(0)
	v_pk_mul_f32 v[20:21], v[232:233], v[2:3] op_sel:[1,1] op_sel_hi:[0,1]
	v_pk_mul_f32 v[8:9], v[10:11], v[230:231] op_sel:[1,1] op_sel_hi:[1,0]
	s_nop 0
	v_fma_f32 v12, v10, v230, -v8
	v_fma_f32 v13, v10, v231, v9
	v_mov_b64_e32 v[10:11], v[236:237]
	v_fma_f32 v22, v232, v2, -v20
	v_fma_f32 v23, v233, v2, v21
	ds_write2_b64 v117, v[4:5], v[26:27] offset1:72
	ds_write2_b64 v117, v[18:19], v[14:15] offset0:144 offset1:216
	s_waitcnt lgkmcnt(0)
	v_pk_mul_f32 v[2:3], v[6:7], v[234:235] op_sel:[1,1] op_sel_hi:[1,0]
	s_nop 0
	v_fma_f32 v16, v6, v234, -v2
	v_fma_f32 v17, v6, v235, v3
	s_waitcnt lgkmcnt(0)
	v_pk_mul_f32 v[2:3], v[10:11], v[0:1] op_sel:[1,1] op_sel_hi:[0,1]
	v_fma_f32 v8, v10, v0, -v2
	v_fma_f32 v9, v11, v0, v3
	ds_read2_b64 v[4:7], v192 offset0:32 offset1:104
	ds_read2_b64 v[0:3], v191 offset1:72
	ds_write2_b64 v63, v[12:13], v[22:23] offset0:32 offset1:104
	ds_write2_b64 v63, v[16:17], v[8:9] offset0:176 offset1:248
	ds_read2_b64 v[8:11], v191 offset0:144 offset1:216
	ds_read2_b64 v[12:15], v192 offset0:176 offset1:248
	v_mov_b64_e32 v[18:19], v[224:225]
	s_waitcnt lgkmcnt(0)
	v_pk_add_f32 v[16:17], v[0:1], v[4:5]
	v_pk_add_f32 v[0:1], v[0:1], v[4:5] neg_lo:[0,1] neg_hi:[0,1]
	v_pk_add_f32 v[4:5], v[2:3], v[6:7]
	v_pk_add_f32 v[2:3], v[2:3], v[6:7] neg_lo:[0,1] neg_hi:[0,1]
	s_waitcnt lgkmcnt(0)
	v_pk_add_f32 v[6:7], v[8:9], v[12:13]
	v_pk_add_f32 v[8:9], v[8:9], v[12:13] neg_lo:[0,1] neg_hi:[0,1]
	v_pk_add_f32 v[12:13], v[10:11], v[14:15]
	v_pk_add_f32 v[10:11], v[10:11], v[14:15] neg_lo:[0,1] neg_hi:[0,1]
	v_pk_add_f32 v[14:15], v[2:3], v[2:3] op_sel:[1,0]
	v_pk_add_f32 v[2:3], v[2:3], v[2:3] op_sel_hi:[1,0] neg_lo:[0,1] neg_hi:[0,1]
	s_nop 0
	v_mov_b32_e32 v15, v3
	v_xor_b32_e32 v3, 0x80000000, v8
	v_mov_b32_e32 v2, v9
	v_pk_add_f32 v[8:9], v[10:11], v[10:11] op_sel:[1,0] neg_lo:[0,1] neg_hi:[0,1]
	v_pk_add_f32 v[10:11], v[10:11], v[10:11] op_sel_hi:[1,0]
	s_nop 0
	v_mov_b32_e32 v9, v11
	v_pk_add_f32 v[10:11], v[16:17], v[6:7]
	v_pk_add_f32 v[6:7], v[16:17], v[6:7] neg_lo:[0,1] neg_hi:[0,1]
	v_pk_add_f32 v[16:17], v[4:5], v[12:13]
	v_pk_add_f32 v[4:5], v[4:5], v[12:13] neg_lo:[0,1] neg_hi:[0,1]
	v_pk_mul_f32 v[8:9], v[8:9], s[20:21]
	v_xor_b32_e32 v13, 0x80000000, v4
	v_mov_b32_e32 v12, v5
	v_pk_add_f32 v[4:5], v[10:11], v[16:17]
	v_pk_add_f32 v[10:11], v[10:11], v[16:17] neg_lo:[0,1] neg_hi:[0,1]
	v_pk_add_f32 v[16:17], v[6:7], v[12:13]
	v_pk_add_f32 v[6:7], v[6:7], v[12:13] neg_lo:[0,1] neg_hi:[0,1]
	v_pk_add_f32 v[12:13], v[0:1], v[2:3]
	v_pk_add_f32 v[0:1], v[0:1], v[2:3] neg_lo:[0,1] neg_hi:[0,1]
	v_pk_fma_f32 v[2:3], v[14:15], s[20:21], v[8:9] op_sel_hi:[1,0,1]
	v_pk_fma_f32 v[8:9], v[14:15], s[20:21], v[8:9] op_sel_hi:[1,0,1] neg_lo:[0,0,1] neg_hi:[0,0,1]
	s_nop 0
	v_xor_b32_e32 v15, 0x80000000, v8
	v_mov_b32_e32 v14, v9
	v_pk_add_f32 v[8:9], v[12:13], v[2:3]
	v_pk_add_f32 v[2:3], v[12:13], v[2:3] neg_lo:[0,1] neg_hi:[0,1]
	v_pk_add_f32 v[12:13], v[0:1], v[14:15]
	v_pk_add_f32 v[0:1], v[0:1], v[14:15] neg_lo:[0,1] neg_hi:[0,1]
	s_waitcnt lgkmcnt(0)
; __device__ __forceinline__ c2 cmul(c2 a, c2 b) { return (c2){a.x * b.x - a.y * b.y, a.x * b.y + a.y * b.x}; }
; template <int S> __device__ __forceinline__ void fwd_mid(c2* buf, const c2* tws, int tid) {
;     constexpr int lq = 9 - 3 * S, Q = 1 << lq; const c2* T = tws + (S == 1 ? 3584 : 4032);
;     const int k = tid & (Q - 1), base = ((tid >> lq) << (lq + 3)) + k;
;     c2 x[8];
;     c2* bp_ = buf + LP(base); constexpr int QP = Q + Q / 8;
; #pragma unroll
;     for (int r = 0; r < 8; ++r) x[r] = bp_[r * QP];
;     dft8(x);
; #pragma unroll
;     for (int q = 1; q < 8; ++q) x[q] = cmul(x[q], T[(q - 1) * Q + k]);
; #pragma unroll
;     for (int q = 0; q < 8; ++q) bp_[q * QP] = x[q];
; }
	v_pk_mul_f32 v[24:25], v[18:19], v[8:9] op_sel:[1,1] op_sel_hi:[0,1]
	v_fma_f32 v26, v18, v8, -v24
	v_fma_f32 v27, v19, v8, v25
	s_nop 0
	s_waitcnt lgkmcnt(0)
	v_pk_mul_f32 v[8:9], v[226:227], v[16:17] op_sel:[1,1] op_sel_hi:[0,1]
	v_fma_f32 v18, v226, v16, -v8
	v_fma_f32 v19, v227, v16, v9
	s_waitcnt lgkmcnt(0)
	v_pk_mul_f32 v[8:9], v[228:229], v[12:13] op_sel:[1,1] op_sel_hi:[0,1]
	v_fma_f32 v14, v228, v12, -v8
	v_fma_f32 v15, v229, v12, v9
	s_waitcnt lgkmcnt(0)
	v_pk_mul_f32 v[20:21], v[232:233], v[2:3] op_sel:[1,1] op_sel_hi:[0,1]
	v_pk_mul_f32 v[8:9], v[10:11], v[230:231] op_sel:[1,1] op_sel_hi:[1,0]
	s_nop 0
	v_fma_f32 v12, v10, v230, -v8
	v_fma_f32 v13, v10, v231, v9
	v_mov_b64_e32 v[8:9], v[234:235]
	v_mov_b64_e32 v[10:11], v[236:237]
	v_fma_f32 v22, v232, v2, -v20
	v_fma_f32 v23, v233, v2, v21
	s_nop 0
	s_waitcnt lgkmcnt(0)
	v_pk_mul_f32 v[2:3], v[6:7], v[8:9] op_sel:[1,1] op_sel_hi:[1,0]
	s_nop 0
	v_fma_f32 v16, v6, v8, -v2
	v_fma_f32 v17, v6, v9, v3
	s_waitcnt lgkmcnt(0)
	v_pk_mul_f32 v[2:3], v[10:11], v[0:1] op_sel:[1,1] op_sel_hi:[0,1]
	v_fma_f32 v6, v10, v0, -v2
	v_fma_f32 v7, v11, v0, v3
	s_nop 0
	ds_write2_b64 v191, v[4:5], v[26:27] offset1:72
	ds_write2_b64 v191, v[18:19], v[14:15] offset0:144 offset1:216
	ds_write2_b64 v192, v[12:13], v[22:23] offset0:32 offset1:104
	ds_write2_b64 v192, v[16:17], v[6:7] offset0:176 offset1:248
	s_waitcnt lgkmcnt(0)
	s_barrier
	ds_read2_b64 v[0:3], v119 offset1:9
	ds_read2_b64 v[4:7], v119 offset0:36 offset1:45
	ds_read2_b64 v[8:11], v119 offset0:18 offset1:27
	ds_read2_b64 v[12:15], v119 offset0:54 offset1:63
	v_mov_b64_e32 v[18:19], v[238:239]
	s_waitcnt lgkmcnt(0)
	v_pk_add_f32 v[16:17], v[0:1], v[4:5]
	v_pk_add_f32 v[0:1], v[0:1], v[4:5] neg_lo:[0,1] neg_hi:[0,1]
	v_pk_add_f32 v[4:5], v[2:3], v[6:7]
	v_pk_add_f32 v[2:3], v[2:3], v[6:7] neg_lo:[0,1] neg_hi:[0,1]
	s_waitcnt lgkmcnt(0)
	v_pk_add_f32 v[6:7], v[8:9], v[12:13]
	v_pk_add_f32 v[8:9], v[8:9], v[12:13] neg_lo:[0,1] neg_hi:[0,1]
	v_pk_add_f32 v[12:13], v[10:11], v[14:15]
	v_pk_add_f32 v[10:11], v[10:11], v[14:15] neg_lo:[0,1] neg_hi:[0,1]
	v_pk_add_f32 v[14:15], v[2:3], v[2:3] op_sel:[1,0]
	v_pk_add_f32 v[2:3], v[2:3], v[2:3] op_sel_hi:[1,0] neg_lo:[0,1] neg_hi:[0,1]
	s_nop 0
	v_mov_b32_e32 v15, v3
	v_xor_b32_e32 v3, 0x80000000, v8
	v_mov_b32_e32 v2, v9
	v_pk_add_f32 v[8:9], v[10:11], v[10:11] op_sel:[1,0] neg_lo:[0,1] neg_hi:[0,1]
	v_pk_add_f32 v[10:11], v[10:11], v[10:11] op_sel_hi:[1,0]
	s_nop 0
	v_mov_b32_e32 v9, v11
	v_pk_add_f32 v[10:11], v[16:17], v[6:7]
	v_pk_add_f32 v[6:7], v[16:17], v[6:7] neg_lo:[0,1] neg_hi:[0,1]
	v_pk_add_f32 v[16:17], v[4:5], v[12:13]
	v_pk_add_f32 v[4:5], v[4:5], v[12:13] neg_lo:[0,1] neg_hi:[0,1]
	v_pk_mul_f32 v[8:9], v[8:9], s[20:21]
	v_xor_b32_e32 v13, 0x80000000, v4
	v_mov_b32_e32 v12, v5
	v_pk_add_f32 v[4:5], v[10:11], v[16:17]
	v_pk_add_f32 v[10:11], v[10:11], v[16:17] neg_lo:[0,1] neg_hi:[0,1]
	v_pk_add_f32 v[16:17], v[6:7], v[12:13]
	v_pk_add_f32 v[6:7], v[6:7], v[12:13] neg_lo:[0,1] neg_hi:[0,1]
	v_pk_add_f32 v[12:13], v[0:1], v[2:3]
	v_pk_add_f32 v[0:1], v[0:1], v[2:3] neg_lo:[0,1] neg_hi:[0,1]
	v_pk_fma_f32 v[2:3], v[14:15], s[20:21], v[8:9] op_sel_hi:[1,0,1]
	v_pk_fma_f32 v[8:9], v[14:15], s[20:21], v[8:9] op_sel_hi:[1,0,1] neg_lo:[0,0,1] neg_hi:[0,0,1]
	s_nop 0
	v_xor_b32_e32 v15, 0x80000000, v8
	v_mov_b32_e32 v14, v9
	v_pk_add_f32 v[8:9], v[12:13], v[2:3]
	v_pk_add_f32 v[2:3], v[12:13], v[2:3] neg_lo:[0,1] neg_hi:[0,1]
	v_pk_add_f32 v[12:13], v[0:1], v[14:15]
	v_pk_add_f32 v[0:1], v[0:1], v[14:15] neg_lo:[0,1] neg_hi:[0,1]
	s_waitcnt lgkmcnt(0)
	v_pk_mul_f32 v[24:25], v[18:19], v[8:9] op_sel:[1,1] op_sel_hi:[0,1]
	v_fma_f32 v26, v18, v8, -v24
	v_fma_f32 v27, v19, v8, v25
	s_nop 0
	s_waitcnt lgkmcnt(0)
	v_pk_mul_f32 v[8:9], v[240:241], v[16:17] op_sel:[1,1] op_sel_hi:[0,1]
	v_fma_f32 v18, v240, v16, -v8
	v_fma_f32 v19, v241, v16, v9
	s_waitcnt lgkmcnt(0)
	v_pk_mul_f32 v[8:9], v[242:243], v[12:13] op_sel:[1,1] op_sel_hi:[0,1]
	v_fma_f32 v14, v242, v12, -v8
	v_fma_f32 v15, v243, v12, v9
	s_waitcnt lgkmcnt(0)
	v_pk_mul_f32 v[20:21], v[246:247], v[2:3] op_sel:[1,1] op_sel_hi:[0,1]
	v_pk_mul_f32 v[8:9], v[10:11], v[244:245] op_sel:[1,1] op_sel_hi:[1,0]
	s_nop 0
	v_fma_f32 v12, v10, v244, -v8
	v_fma_f32 v13, v10, v245, v9
	v_mov_b64_e32 v[10:11], v[250:251]
	v_fma_f32 v22, v246, v2, -v20
	v_fma_f32 v23, v247, v2, v21
	ds_write2_b64 v119, v[4:5], v[26:27] offset1:9
	ds_write2_b64 v119, v[18:19], v[14:15] offset0:18 offset1:27
	s_waitcnt lgkmcnt(0)
	v_pk_mul_f32 v[2:3], v[6:7], v[248:249] op_sel:[1,1] op_sel_hi:[1,0]
	s_nop 0
	v_fma_f32 v16, v6, v248, -v2
	v_fma_f32 v17, v6, v249, v3
	s_waitcnt lgkmcnt(0)
	v_pk_mul_f32 v[2:3], v[10:11], v[0:1] op_sel:[1,1] op_sel_hi:[0,1]
	v_fma_f32 v8, v10, v0, -v2
	v_fma_f32 v9, v11, v0, v3
	s_nop 0
	ds_read2_b64 v[0:3], v193 offset1:9
	ds_read2_b64 v[4:7], v193 offset0:36 offset1:45
	ds_write2_b64 v119, v[12:13], v[22:23] offset0:36 offset1:45
	ds_write2_b64 v119, v[16:17], v[8:9] offset0:54 offset1:63
	ds_read2_b64 v[8:11], v193 offset0:18 offset1:27
	ds_read2_b64 v[12:15], v193 offset0:54 offset1:63
	v_mov_b64_e32 v[18:19], v[238:239]
	s_waitcnt lgkmcnt(0)
	v_pk_add_f32 v[16:17], v[0:1], v[4:5]
	v_pk_add_f32 v[0:1], v[0:1], v[4:5] neg_lo:[0,1] neg_hi:[0,1]
	v_pk_add_f32 v[4:5], v[2:3], v[6:7]
	v_pk_add_f32 v[2:3], v[2:3], v[6:7] neg_lo:[0,1] neg_hi:[0,1]
	s_waitcnt lgkmcnt(0)
; __device__ __forceinline__ c2 cmul(c2 a, c2 b) { return (c2){a.x * b.x - a.y * b.y, a.x * b.y + a.y * b.x}; }
; template <int S> __device__ __forceinline__ void fwd_mid(c2* buf, const c2* tws, int tid) {
;     constexpr int lq = 9 - 3 * S, Q = 1 << lq; const c2* T = tws + (S == 1 ? 3584 : 4032);
;     const int k = tid & (Q - 1), base = ((tid >> lq) << (lq + 3)) + k;
;     c2 x[8];
;     c2* bp_ = buf + LP(base); constexpr int QP = Q + Q / 8;
; #pragma unroll
;     for (int r = 0; r < 8; ++r) x[r] = bp_[r * QP];
;     dft8(x);
; #pragma unroll
;     for (int q = 1; q < 8; ++q) x[q] = cmul(x[q], T[(q - 1) * Q + k]);
; #pragma unroll
;     for (int q = 0; q < 8; ++q) bp_[q * QP] = x[q];
; }
	v_pk_add_f32 v[6:7], v[8:9], v[12:13]
	v_pk_add_f32 v[8:9], v[8:9], v[12:13] neg_lo:[0,1] neg_hi:[0,1]
	v_pk_add_f32 v[12:13], v[10:11], v[14:15]
	v_pk_add_f32 v[10:11], v[10:11], v[14:15] neg_lo:[0,1] neg_hi:[0,1]
	v_pk_add_f32 v[14:15], v[2:3], v[2:3] op_sel:[1,0]
	v_pk_add_f32 v[2:3], v[2:3], v[2:3] op_sel_hi:[1,0] neg_lo:[0,1] neg_hi:[0,1]
	s_nop 0
	v_mov_b32_e32 v15, v3
	v_xor_b32_e32 v3, 0x80000000, v8
	v_mov_b32_e32 v2, v9
	v_pk_add_f32 v[8:9], v[10:11], v[10:11] op_sel:[1,0] neg_lo:[0,1] neg_hi:[0,1]
	v_pk_add_f32 v[10:11], v[10:11], v[10:11] op_sel_hi:[1,0]
	s_nop 0
	v_mov_b32_e32 v9, v11
	v_pk_add_f32 v[10:11], v[16:17], v[6:7]
	v_pk_add_f32 v[6:7], v[16:17], v[6:7] neg_lo:[0,1] neg_hi:[0,1]
	v_pk_add_f32 v[16:17], v[4:5], v[12:13]
	v_pk_add_f32 v[4:5], v[4:5], v[12:13] neg_lo:[0,1] neg_hi:[0,1]
	v_pk_mul_f32 v[8:9], v[8:9], s[20:21]
	v_xor_b32_e32 v13, 0x80000000, v4
	v_mov_b32_e32 v12, v5
	v_pk_add_f32 v[4:5], v[10:11], v[16:17]
	v_pk_add_f32 v[10:11], v[10:11], v[16:17] neg_lo:[0,1] neg_hi:[0,1]
	v_pk_add_f32 v[16:17], v[6:7], v[12:13]
	v_pk_add_f32 v[6:7], v[6:7], v[12:13] neg_lo:[0,1] neg_hi:[0,1]
	v_pk_add_f32 v[12:13], v[0:1], v[2:3]
	v_pk_add_f32 v[0:1], v[0:1], v[2:3] neg_lo:[0,1] neg_hi:[0,1]
	v_pk_fma_f32 v[2:3], v[14:15], s[20:21], v[8:9] op_sel_hi:[1,0,1]
	v_pk_fma_f32 v[8:9], v[14:15], s[20:21], v[8:9] op_sel_hi:[1,0,1] neg_lo:[0,0,1] neg_hi:[0,0,1]
	s_nop 0
	v_xor_b32_e32 v15, 0x80000000, v8
	v_mov_b32_e32 v14, v9
	v_pk_add_f32 v[8:9], v[12:13], v[2:3]
	v_pk_add_f32 v[2:3], v[12:13], v[2:3] neg_lo:[0,1] neg_hi:[0,1]
	v_pk_add_f32 v[12:13], v[0:1], v[14:15]
	v_pk_add_f32 v[0:1], v[0:1], v[14:15] neg_lo:[0,1] neg_hi:[0,1]
	s_waitcnt lgkmcnt(0)
	v_pk_mul_f32 v[24:25], v[18:19], v[8:9] op_sel:[1,1] op_sel_hi:[0,1]
	v_fma_f32 v26, v18, v8, -v24
	v_fma_f32 v27, v19, v8, v25
	s_nop 0
	s_waitcnt lgkmcnt(0)
	v_pk_mul_f32 v[8:9], v[240:241], v[16:17] op_sel:[1,1] op_sel_hi:[0,1]
	v_fma_f32 v18, v240, v16, -v8
	v_fma_f32 v19, v241, v16, v9
	s_waitcnt lgkmcnt(0)
	v_pk_mul_f32 v[8:9], v[242:243], v[12:13] op_sel:[1,1] op_sel_hi:[0,1]
	v_fma_f32 v14, v242, v12, -v8
	v_fma_f32 v15, v243, v12, v9
	s_waitcnt lgkmcnt(0)
	v_pk_mul_f32 v[20:21], v[246:247], v[2:3] op_sel:[1,1] op_sel_hi:[0,1]
	v_pk_mul_f32 v[8:9], v[10:11], v[244:245] op_sel:[1,1] op_sel_hi:[1,0]
	s_nop 0
	v_fma_f32 v12, v10, v244, -v8
	v_fma_f32 v13, v10, v245, v9
	v_mov_b64_e32 v[8:9], v[248:249]
	v_mov_b64_e32 v[10:11], v[250:251]
	v_fma_f32 v22, v246, v2, -v20
	v_fma_f32 v23, v247, v2, v21
	s_nop 0
	s_waitcnt lgkmcnt(0)
	v_pk_mul_f32 v[2:3], v[6:7], v[8:9] op_sel:[1,1] op_sel_hi:[1,0]
	s_nop 0
	v_fma_f32 v16, v6, v8, -v2
	v_fma_f32 v17, v6, v9, v3
	s_waitcnt lgkmcnt(0)
	v_pk_mul_f32 v[2:3], v[10:11], v[0:1] op_sel:[1,1] op_sel_hi:[0,1]
	v_fma_f32 v6, v10, v0, -v2
	v_fma_f32 v7, v11, v0, v3
	s_nop 0
	ds_write2_b64 v193, v[4:5], v[26:27] offset1:9
	ds_write2_b64 v193, v[18:19], v[14:15] offset0:18 offset1:27
	ds_write2_b64 v193, v[12:13], v[22:23] offset0:36 offset1:45
	ds_write2_b64 v193, v[16:17], v[6:7] offset0:54 offset1:63
	s_waitcnt lgkmcnt(0)
	s_barrier
; __device__ __forceinline__ c2 mni(c2 a) { return (c2){a.y, -a.x}; }
; __device__ __forceinline__ void dft8(c2 (&x)[8]) {
;     const float s = 0.70710678118654752f;
;     const c2 a0 = x[0] + x[4], a4 = x[0] - x[4], a1 = x[1] + x[5], a5 = x[1] - x[5], a2 = x[2] + x[6], a6 = x[2] - x[6], a3 = x[3] + x[7], a7 = x[3] - x[7];
;     const c2 a5w = (c2){(a5.x + a5.y) * s, (a5.y - a5.x) * s};
;     const c2 a6w = mni(a6);
;     const c2 a7w = (c2){(a7.y - a7.x) * s, -(a7.x + a7.y) * s};
;     const c2 b0 = a0 + a2, b1 = a0 - a2, b2 = a1 + a3, b3 = mni(a1 - a3);
;     x[0] = b0 + b2; x[4] = b0 - b2; x[2] = b1 + b3; x[6] = b1 - b3;
;     const c2 c0 = a4 + a6w, c1 = a4 - a6w, c2_ = a5w + a7w, c3 = mni(a5w - a7w);
;     x[1] = c0 + c2_; x[5] = c0 - c2_; x[3] = c1 + c3; x[7] = c1 - c3;
; }
; __device__ __forceinline__ void phase_conv(const Params& p, int o, unsigned char* smem, int wave) {
;     ...
;                 for (int q = 0; q < 8; ++q) { sK[((d + 7) * 8 + q) * 512 + tid] = x0[q]; if (d < 7) sK[((d + 8) * 8 + q) * 512 + tid] = x1[q]; }
	ds_read2_b64 v[0:3], v121 offset0:4 offset1:5
	ds_read2_b64 v[4:7], v121 offset1:1
	ds_read2_b64 v[8:11], v121 offset0:2 offset1:3
	ds_read2_b64 v[12:15], v121 offset0:6 offset1:7
	ds_read2_b64 v[26:29], v195 offset1:1
	ds_read2_b64 v[30:33], v196 offset1:1
	ds_read2_b64 v[38:41], v197 offset1:1
	s_waitcnt lgkmcnt(0)
	v_pk_add_f32 v[16:17], v[4:5], v[0:1]
	v_pk_add_f32 v[0:1], v[4:5], v[0:1] neg_lo:[0,1] neg_hi:[0,1]
	v_pk_add_f32 v[4:5], v[6:7], v[2:3]
	v_pk_add_f32 v[2:3], v[6:7], v[2:3] neg_lo:[0,1] neg_hi:[0,1]
	s_waitcnt lgkmcnt(0)
	v_pk_add_f32 v[6:7], v[8:9], v[12:13]
	v_pk_add_f32 v[8:9], v[8:9], v[12:13] neg_lo:[0,1] neg_hi:[0,1]
	v_pk_add_f32 v[18:19], v[10:11], v[14:15]
	v_pk_add_f32 v[10:11], v[10:11], v[14:15] neg_lo:[0,1] neg_hi:[0,1]
	v_pk_add_f32 v[22:23], v[2:3], v[2:3] op_sel:[1,0]
	v_pk_add_f32 v[2:3], v[2:3], v[2:3] op_sel_hi:[1,0] neg_lo:[0,1] neg_hi:[0,1]
	v_pk_add_f32 v[12:13], v[4:5], v[18:19]
	v_mov_b32_e32 v23, v3
	v_xor_b32_e32 v3, 0x80000000, v8
	v_mov_b32_e32 v2, v9
	v_pk_add_f32 v[8:9], v[10:11], v[10:11] op_sel:[1,0] neg_lo:[0,1] neg_hi:[0,1]
	v_pk_add_f32 v[10:11], v[10:11], v[10:11] op_sel_hi:[1,0]
	v_pk_add_f32 v[4:5], v[4:5], v[18:19] neg_lo:[0,1] neg_hi:[0,1]
	v_mov_b32_e32 v9, v11
	v_pk_mul_f32 v[24:25], v[8:9], s[20:21]
	v_pk_add_f32 v[8:9], v[16:17], v[6:7]
	v_pk_add_f32 v[10:11], v[16:17], v[6:7] neg_lo:[0,1] neg_hi:[0,1]
	v_pk_fma_f32 v[20:21], v[22:23], s[20:21], v[24:25] op_sel_hi:[1,0,1]
	v_pk_fma_f32 v[6:7], v[22:23], s[20:21], v[24:25] op_sel_hi:[1,0,1] neg_lo:[0,0,1] neg_hi:[0,0,1]
	ds_read2_b64 v[22:25], v194 offset1:1
	v_xor_b32_e32 v15, 0x80000000, v4
	v_mov_b32_e32 v14, v5
	v_pk_add_f32 v[16:17], v[0:1], v[2:3]
	v_pk_add_f32 v[0:1], v[0:1], v[2:3] neg_lo:[0,1] neg_hi:[0,1]
	s_waitcnt lgkmcnt(0)
	v_pk_add_f32 v[18:19], v[22:23], v[26:27]
	v_pk_add_f32 v[34:35], v[22:23], v[26:27] neg_lo:[0,1] neg_hi:[0,1]
	v_pk_add_f32 v[22:23], v[24:25], v[28:29] neg_lo:[0,1] neg_hi:[0,1]
	v_pk_add_f32 v[44:45], v[24:25], v[28:29]
	v_pk_add_f32 v[24:25], v[30:31], v[38:39]
	v_pk_add_f32 v[26:27], v[30:31], v[38:39] neg_lo:[0,1] neg_hi:[0,1]
	v_pk_add_f32 v[30:31], v[32:33], v[40:41] neg_lo:[0,1] neg_hi:[0,1]
	v_pk_add_f32 v[38:39], v[22:23], v[22:23] op_sel:[1,0]
	v_pk_add_f32 v[22:23], v[22:23], v[22:23] op_sel_hi:[1,0] neg_lo:[0,1] neg_hi:[0,1]
	v_pk_add_f32 v[28:29], v[32:33], v[40:41]
	v_mov_b32_e32 v39, v23
	v_xor_b32_e32 v33, 0x80000000, v26
	v_mov_b32_e32 v32, v27
	v_pk_add_f32 v[22:23], v[30:31], v[30:31] op_sel:[1,0] neg_lo:[0,1] neg_hi:[0,1]
	v_pk_add_f32 v[26:27], v[30:31], v[30:31] op_sel_hi:[1,0]
	v_pk_add_f32 v[30:31], v[34:35], v[32:33]
	v_mov_b32_e32 v23, v27
	v_pk_mul_f32 v[40:41], v[22:23], s[20:21]
	v_pk_add_f32 v[22:23], v[18:19], v[24:25]
	v_pk_add_f32 v[24:25], v[18:19], v[24:25] neg_lo:[0,1] neg_hi:[0,1]
	v_pk_add_f32 v[18:19], v[44:45], v[28:29] neg_lo:[0,1] neg_hi:[0,1]
	v_pk_add_f32 v[26:27], v[44:45], v[28:29]
	v_xor_b32_e32 v29, 0x80000000, v18
	v_mov_b32_e32 v28, v19
	v_pk_fma_f32 v[18:19], v[38:39], s[20:21], v[40:41] op_sel_hi:[1,0,1] neg_lo:[0,0,1] neg_hi:[0,0,1]
	v_pk_add_f32 v[32:33], v[34:35], v[32:33] neg_lo:[0,1] neg_hi:[0,1]
	v_pk_fma_f32 v[34:35], v[38:39], s[20:21], v[40:41] op_sel_hi:[1,0,1]
	v_xor_b32_e32 v39, 0x80000000, v18
	v_add_u32_e32 v18, s95, v113
	v_mov_b32_e32 v38, v19
	v_ashrrev_i32_e32 v19, 31, v18
	v_xor_b32_e32 v3, 0x80000000, v6
	v_mov_b32_e32 v2, v7
	v_lshl_add_u64 v[40:41], v[18:19], 3, s[8:9]
	v_cndmask_b32_e64 v19, 0, 1, s[70:71]
	v_pk_add_f32 v[42:43], v[8:9], v[12:13]
	v_pk_add_f32 v[4:5], v[10:11], v[14:15]
	v_pk_add_f32 v[36:37], v[16:17], v[20:21]
	v_pk_add_f32 v[6:7], v[0:1], v[2:3]
	v_cmp_ne_u32_e64 s[84:85], 1, v19
	global_store_dwordx2 v[40:41], v[42:43], off
	s_cbranch_vccnz .LBB0_482
	v_add_u32_e32 v48, 0x1000, v18
	v_ashrrev_i32_e32 v49, 31, v48
	v_pk_add_f32 v[46:47], v[22:23], v[26:27]
	v_lshl_add_u64 v[48:49], v[48:49], 3, s[8:9]
	global_store_dwordx2 v[48:49], v[46:47], off
	v_add_u32_e32 v46, 0x200, v18
	v_ashrrev_i32_e32 v47, 31, v46
	v_lshl_add_u64 v[46:47], v[46:47], 3, s[8:9]
	global_store_dwordx2 v[46:47], v[36:37], off
	v_add_u32_e32 v36, 0x1200, v18
	v_ashrrev_i32_e32 v37, 31, v36
	v_pk_add_f32 v[40:41], v[30:31], v[34:35]
	v_lshl_add_u64 v[36:37], v[36:37], 3, s[8:9]
	global_store_dwordx2 v[36:37], v[40:41], off
	v_add_u32_e32 v36, 0x400, v18
	v_ashrrev_i32_e32 v37, 31, v36
	v_pk_add_f32 v[42:43], v[32:33], v[38:39]
	v_pk_add_f32 v[44:45], v[24:25], v[28:29]
	v_lshl_add_u64 v[36:37], v[36:37], 3, s[8:9]
	global_store_dwordx2 v[36:37], v[4:5], off
	v_mov_b32_e32 v41, v178
	v_mov_b64_e32 v[36:37], v[44:45]
	v_mov_b32_e32 v40, v179
	v_mov_b64_e32 v[4:5], v[6:7]
	v_mov_b32_e32 v19, v180
	v_mov_b64_e32 v[6:7], v[42:43]
	s_branch .LBB0_483

; __device__ __forceinline__ c2 cmul(c2 a, c2 b) { return (c2){a.x * b.x - a.y * b.y, a.x * b.y + a.y * b.x}; }
; __device__ __forceinline__ c2 mni(c2 a) { return (c2){a.y, -a.x}; }
; __device__ __forceinline__ void dft8(c2 (&x)[8]) {
;     const float s = 0.70710678118654752f;
;     const c2 a0 = x[0] + x[4], a4 = x[0] - x[4], a1 = x[1] + x[5], a5 = x[1] - x[5], a2 = x[2] + x[6], a6 = x[2] - x[6], a3 = x[3] + x[7], a7 = x[3] - x[7];
;     const c2 a5w = (c2){(a5.x + a5.y) * s, (a5.y - a5.x) * s};
;     const c2 a6w = mni(a6);
;     const c2 a7w = (c2){(a7.y - a7.x) * s, -(a7.x + a7.y) * s};
;     const c2 b0 = a0 + a2, b1 = a0 - a2, b2 = a1 + a3, b3 = mni(a1 - a3);
;     x[0] = b0 + b2; x[4] = b0 - b2; x[2] = b1 + b3; x[6] = b1 - b3;
;     const c2 c0 = a4 + a6w, c1 = a4 - a6w, c2_ = a5w + a7w, c3 = mni(a5w - a7w);
;     x[1] = c0 + c2_; x[5] = c0 - c2_; x[3] = c1 + c3; x[7] = c1 - c3;
; }
; __device__ __forceinline__ c2 mpi(c2 a) { return (c2){-a.y, a.x}; }
; __device__ __forceinline__ void idft8(c2 (&x)[8]) {
;     const float s = 0.70710678118654752f;
;     const c2 a0 = x[0] + x[4], a4 = x[0] - x[4], a1 = x[1] + x[5], a5 = x[1] - x[5], a2 = x[2] + x[6], a6 = x[2] - x[6], a3 = x[3] + x[7], a7 = x[3] - x[7];
;     const c2 a5w = (c2){(a5.x - a5.y) * s, (a5.x + a5.y) * s};
;     const c2 a6w = mpi(a6);
;     const c2 a7w = (c2){-(a7.x + a7.y) * s, (a7.x - a7.y) * s};
;     const c2 b0 = a0 + a2, b1 = a0 - a2, b2 = a1 + a3, b3 = mpi(a1 - a3);
;     x[0] = b0 + b2; x[4] = b0 - b2; x[2] = b1 + b3; x[6] = b1 - b3;
;     const c2 c0 = a4 + a6w, c1 = a4 - a6w, c2_ = a5w + a7w, c3 = mpi(a5w - a7w);
;     x[1] = c0 + c2_; x[5] = c0 - c2_; x[3] = c1 + c3; x[7] = c1 - c3;
; }
; __device__ __forceinline__ void fwd_s0(c2 (&x)[8], c2* buf, const c2* tws, int tid) {
;     dft8(x);
; #pragma unroll
;     for (int q = 1; q < 8; ++q) x[q] = cmul(x[q], tws[(q - 1) * 512 + tid]);
;     { c2* bp_ = buf + LP(tid);
; #pragma unroll
;     for (int q = 0; q < 8; ++q) bp_[576 * q] = x[q]; }
; }
.LBB0_558:
	v_pk_add_f32 v[40:41], v[30:31], 0 op_sel_hi:[1,0]
	v_pk_add_f32 v[42:43], v[34:35], 0 op_sel_hi:[1,0]
	v_xor_b32_e32 v45, 0x80000000, v34
	v_sub_f32_e32 v34, 0, v35
	v_mov_b32_e32 v35, v43
	v_pk_add_f32 v[46:47], v[40:41], v[42:43] neg_lo:[0,1] neg_hi:[0,1]
	v_mov_b32_e32 v56, v30
	v_sub_f32_e32 v31, 0, v31
	v_mov_b32_e32 v30, v41
	v_pk_mul_f32 v[34:35], v[34:35], s[20:21]
	v_pk_add_f32 v[40:41], v[40:41], v[42:43]
	v_pk_add_f32 v[42:43], v[46:47], 0 neg_lo:[1,1] neg_hi:[1,1]
	v_mov_b32_e32 v44, v57
	v_mov_b32_e32 v48, v46
	v_mov_b32_e32 v49, v57
	v_mov_b32_e32 v42, v57
	v_pk_fma_f32 v[52:53], v[30:31], s[20:21], v[34:35] op_sel_hi:[1,0,1]
	v_pk_fma_f32 v[30:31], v[30:31], s[20:21], v[34:35] op_sel_hi:[1,0,1] neg_lo:[0,0,1] neg_hi:[0,0,1]
	v_pk_add_f32 v[50:51], v[48:49], v[42:43]
	v_pk_add_f32 v[42:43], v[48:49], v[42:43] neg_lo:[0,1] neg_hi:[0,1]
	v_pk_add_f32 v[48:49], v[56:57], v[44:45]
	v_pk_add_f32 v[44:45], v[56:57], v[44:45] neg_lo:[0,1] neg_hi:[0,1]
	v_xor_b32_e32 v35, 0x80000000, v30
	v_mov_b32_e32 v34, v31
	v_pk_add_f32 v[30:31], v[48:49], v[52:53]
	v_pk_add_f32 v[48:49], v[48:49], v[52:53] neg_lo:[0,1] neg_hi:[0,1]
	v_pk_add_f32 v[52:53], v[44:45], v[34:35]
	v_pk_add_f32 v[34:35], v[44:45], v[34:35] neg_lo:[0,1] neg_hi:[0,1]
	s_waitcnt lgkmcnt(0)
	v_pk_mul_f32 v[94:95], v[30:31], v[210:211] op_sel:[1,1] op_sel_hi:[1,0]
	v_pk_add_f32 v[46:47], v[40:41], v[40:41] op_sel:[0,1] op_sel_hi:[1,0]
	v_fma_f32 v96, v30, v210, -v94
	v_fma_f32 v97, v30, v211, v95
	s_waitcnt lgkmcnt(0)
	v_pk_mul_f32 v[30:31], v[50:51], v[212:213] op_sel:[1,1] op_sel_hi:[1,0]
	v_mov_b32_e32 v47, v57
	v_fma_f32 v54, v50, v212, -v30
	v_fma_f32 v55, v50, v213, v31
	s_waitcnt lgkmcnt(0)
	v_pk_mul_f32 v[30:31], v[52:53], v[214:215] op_sel:[1,1] op_sel_hi:[1,0]
	v_mov_b32_e32 v56, v28
	v_fma_f32 v44, v52, v214, -v30
	v_fma_f32 v45, v52, v215, v31
	v_pk_add_f32 v[30:31], v[40:41], v[40:41] op_sel:[0,1] op_sel_hi:[0,1] neg_lo:[0,1] neg_hi:[0,1]
	s_waitcnt lgkmcnt(0)
	v_pk_mul_f32 v[40:41], v[216:217], 0 op_sel_hi:[1,0]
	s_lshl_b32 s7, s40, 13
	v_fma_f32 v50, v30, v216, -v41
	v_fma_f32 v51, v31, v217, v40
	s_waitcnt lgkmcnt(0)
	v_pk_mul_f32 v[90:91], v[48:49], v[218:219] op_sel:[1,1] op_sel_hi:[1,0]
	v_mov_b64_e32 v[40:41], v[222:223]
	v_fma_f32 v92, v48, v218, -v90
	v_fma_f32 v93, v48, v219, v91
	s_waitcnt lgkmcnt(0)
	v_pk_mul_f32 v[48:49], v[42:43], v[220:221] op_sel:[1,1] op_sel_hi:[1,0]
	s_or_b32 s7, s7, s3
	v_fma_f32 v52, v42, v220, -v48
	v_fma_f32 v53, v42, v221, v49
	s_waitcnt lgkmcnt(0)
	v_pk_mul_f32 v[30:31], v[34:35], v[40:41] op_sel:[1,1] op_sel_hi:[1,0]
	s_or_b32 s16, s7, 0x200
	v_fma_f32 v42, v34, v40, -v30
	v_fma_f32 v43, v34, v41, v31
	ds_write2st64_b64 v115, v[46:47], v[96:97] offset1:9
	ds_write2st64_b64 v115, v[54:55], v[44:45] offset0:18 offset1:27
	ds_write2st64_b64 v115, v[50:51], v[92:93] offset0:36 offset1:45
	ds_write2st64_b64 v115, v[52:53], v[42:43] offset0:54 offset1:63
	v_pk_add_f32 v[30:31], v[28:29], 0 op_sel_hi:[1,0]
	v_pk_add_f32 v[34:35], v[32:33], 0 op_sel_hi:[1,0]
	v_xor_b32_e32 v41, 0x80000000, v32
	v_sub_f32_e32 v32, 0, v33
	v_mov_b32_e32 v33, v35
	v_pk_add_f32 v[42:43], v[30:31], v[34:35] neg_lo:[0,1] neg_hi:[0,1]
	v_sub_f32_e32 v29, 0, v29
	v_mov_b32_e32 v28, v31
	v_pk_mul_f32 v[32:33], v[32:33], s[20:21]
	v_pk_add_f32 v[30:31], v[30:31], v[34:35]
	v_pk_add_f32 v[34:35], v[42:43], 0 neg_lo:[1,1] neg_hi:[1,1]
	v_mov_b32_e32 v40, v57
	v_mov_b32_e32 v44, v42
	v_mov_b32_e32 v45, v57
	v_mov_b32_e32 v34, v57
	v_pk_fma_f32 v[48:49], v[28:29], s[20:21], v[32:33] op_sel_hi:[1,0,1]
	v_pk_fma_f32 v[28:29], v[28:29], s[20:21], v[32:33] op_sel_hi:[1,0,1] neg_lo:[0,0,1] neg_hi:[0,0,1]
	v_pk_add_f32 v[46:47], v[44:45], v[34:35]
	v_pk_add_f32 v[34:35], v[44:45], v[34:35] neg_lo:[0,1] neg_hi:[0,1]
	v_pk_add_f32 v[44:45], v[56:57], v[40:41]
	v_pk_add_f32 v[40:41], v[56:57], v[40:41] neg_lo:[0,1] neg_hi:[0,1]
	v_xor_b32_e32 v33, 0x80000000, v28
	v_mov_b32_e32 v32, v29
	v_pk_add_f32 v[28:29], v[44:45], v[48:49]
	v_pk_add_f32 v[44:45], v[44:45], v[48:49] neg_lo:[0,1] neg_hi:[0,1]
	v_pk_add_f32 v[48:49], v[40:41], v[32:33]
	v_pk_add_f32 v[32:33], v[40:41], v[32:33] neg_lo:[0,1] neg_hi:[0,1]
	s_waitcnt lgkmcnt(0)
	v_pk_mul_f32 v[90:91], v[28:29], v[210:211] op_sel:[1,1] op_sel_hi:[1,0]
	v_pk_add_f32 v[42:43], v[30:31], v[30:31] op_sel:[0,1] op_sel_hi:[1,0]
	v_fma_f32 v92, v28, v210, -v90
	v_fma_f32 v93, v28, v211, v91
	s_waitcnt lgkmcnt(0)
	v_pk_mul_f32 v[28:29], v[46:47], v[212:213] op_sel:[1,1] op_sel_hi:[1,0]
	v_mov_b32_e32 v43, v57
	v_fma_f32 v50, v46, v212, -v28
	v_fma_f32 v51, v46, v213, v29
	s_waitcnt lgkmcnt(0)
	v_pk_mul_f32 v[28:29], v[48:49], v[214:215] op_sel:[1,1] op_sel_hi:[1,0]
	s_xor_b64 s[70:71], s[62:63], -1
	v_fma_f32 v40, v48, v214, -v28
	v_fma_f32 v41, v48, v215, v29
	v_pk_add_f32 v[28:29], v[30:31], v[30:31] op_sel:[0,1] op_sel_hi:[0,1] neg_lo:[0,1] neg_hi:[0,1]
	s_waitcnt lgkmcnt(0)
	v_pk_mul_f32 v[30:31], v[216:217], 0 op_sel_hi:[1,0]
	s_mov_b32 s40, 1
	v_fma_f32 v46, v28, v216, -v31
	v_fma_f32 v47, v29, v217, v30
	s_waitcnt lgkmcnt(0)
	v_pk_mul_f32 v[52:53], v[44:45], v[218:219] op_sel:[1,1] op_sel_hi:[1,0]
	v_mov_b64_e32 v[30:31], v[222:223]
	v_fma_f32 v54, v44, v218, -v52
	v_fma_f32 v55, v44, v219, v53
	s_waitcnt lgkmcnt(0)
	v_pk_mul_f32 v[44:45], v[34:35], v[220:221] op_sel:[1,1] op_sel_hi:[1,0]
	s_mov_b64 s[62:63], 0
	v_fma_f32 v48, v34, v220, -v44
	v_fma_f32 v49, v34, v221, v45
	s_waitcnt lgkmcnt(0)
	v_pk_mul_f32 v[28:29], v[32:33], v[30:31] op_sel:[1,1] op_sel_hi:[1,0]
	s_and_b64 vcc, exec, s[70:71]
	v_fma_f32 v34, v32, v30, -v28
	v_fma_f32 v35, v32, v31, v29
	ds_write2st64_b64 v115, v[42:43], v[92:93] offset0:72 offset1:81
	ds_write2st64_b64 v115, v[50:51], v[40:41] offset0:90 offset1:99
	ds_write2st64_b64 v115, v[46:47], v[54:55] offset0:108 offset1:117
	ds_write_b64 v115, v[48:49] offset:64512
	ds_write_b64 v116, v[34:35] offset:32256
	s_waitcnt lgkmcnt(0)
	s_barrier
; __device__ __forceinline__ c2 cmul(c2 a, c2 b) { return (c2){a.x * b.x - a.y * b.y, a.x * b.y + a.y * b.x}; }
; template <int S> __device__ __forceinline__ void fwd_mid(c2* buf, const c2* tws, int tid) {
;     constexpr int lq = 9 - 3 * S, Q = 1 << lq; const c2* T = tws + (S == 1 ? 3584 : 4032);
;     const int k = tid & (Q - 1), base = ((tid >> lq) << (lq + 3)) + k;
;     c2 x[8];
;     c2* bp_ = buf + LP(base); constexpr int QP = Q + Q / 8;
; #pragma unroll
;     for (int r = 0; r < 8; ++r) x[r] = bp_[r * QP];
;     dft8(x);
; #pragma unroll
;     for (int q = 1; q < 8; ++q) x[q] = cmul(x[q], T[(q - 1) * Q + k]);
; #pragma unroll
;     for (int q = 0; q < 8; ++q) bp_[q * QP] = x[q];
; }
	ds_read2_b64 v[28:31], v117 offset1:72
	ds_read2_b64 v[32:35], v63 offset0:32 offset1:104
	ds_read2_b64 v[40:43], v117 offset0:144 offset1:216
	ds_read2_b64 v[44:47], v63 offset0:176 offset1:248
	v_mov_b64_e32 v[50:51], v[224:225]
	s_waitcnt lgkmcnt(0)
	v_pk_add_f32 v[48:49], v[28:29], v[32:33]
	v_pk_add_f32 v[28:29], v[28:29], v[32:33] neg_lo:[0,1] neg_hi:[0,1]
	v_pk_add_f32 v[32:33], v[30:31], v[34:35]
	v_pk_add_f32 v[30:31], v[30:31], v[34:35] neg_lo:[0,1] neg_hi:[0,1]
	s_waitcnt lgkmcnt(0)
	v_pk_add_f32 v[34:35], v[40:41], v[44:45]
	v_pk_add_f32 v[40:41], v[40:41], v[44:45] neg_lo:[0,1] neg_hi:[0,1]
	v_pk_add_f32 v[44:45], v[42:43], v[46:47]
	v_pk_add_f32 v[42:43], v[42:43], v[46:47] neg_lo:[0,1] neg_hi:[0,1]
	v_pk_add_f32 v[46:47], v[30:31], v[30:31] op_sel:[1,0]
	v_pk_add_f32 v[30:31], v[30:31], v[30:31] op_sel_hi:[1,0] neg_lo:[0,1] neg_hi:[0,1]
	s_nop 0
	v_mov_b32_e32 v47, v31
	v_xor_b32_e32 v31, 0x80000000, v40
	v_mov_b32_e32 v30, v41
	v_pk_add_f32 v[40:41], v[42:43], v[42:43] op_sel:[1,0] neg_lo:[0,1] neg_hi:[0,1]
	v_pk_add_f32 v[42:43], v[42:43], v[42:43] op_sel_hi:[1,0]
	s_nop 0
	v_mov_b32_e32 v41, v43
	v_pk_add_f32 v[42:43], v[48:49], v[34:35]
	v_pk_add_f32 v[34:35], v[48:49], v[34:35] neg_lo:[0,1] neg_hi:[0,1]
	v_pk_add_f32 v[48:49], v[32:33], v[44:45]
	v_pk_add_f32 v[32:33], v[32:33], v[44:45] neg_lo:[0,1] neg_hi:[0,1]
	v_pk_mul_f32 v[40:41], v[40:41], s[20:21]
	v_xor_b32_e32 v45, 0x80000000, v32
	v_mov_b32_e32 v44, v33
	v_pk_add_f32 v[32:33], v[42:43], v[48:49]
	v_pk_add_f32 v[42:43], v[42:43], v[48:49] neg_lo:[0,1] neg_hi:[0,1]
	v_pk_add_f32 v[48:49], v[34:35], v[44:45]
	v_pk_add_f32 v[34:35], v[34:35], v[44:45] neg_lo:[0,1] neg_hi:[0,1]
	v_pk_add_f32 v[44:45], v[28:29], v[30:31]
	v_pk_add_f32 v[28:29], v[28:29], v[30:31] neg_lo:[0,1] neg_hi:[0,1]
	v_pk_fma_f32 v[30:31], v[46:47], s[20:21], v[40:41] op_sel_hi:[1,0,1]
	v_pk_fma_f32 v[40:41], v[46:47], s[20:21], v[40:41] op_sel_hi:[1,0,1] neg_lo:[0,0,1] neg_hi:[0,0,1]
	s_nop 0
	v_xor_b32_e32 v47, 0x80000000, v40
	v_mov_b32_e32 v46, v41
	v_pk_add_f32 v[40:41], v[44:45], v[30:31]
	v_pk_add_f32 v[30:31], v[44:45], v[30:31] neg_lo:[0,1] neg_hi:[0,1]
	v_pk_add_f32 v[44:45], v[28:29], v[46:47]
	v_pk_add_f32 v[28:29], v[28:29], v[46:47] neg_lo:[0,1] neg_hi:[0,1]
	s_waitcnt lgkmcnt(0)
	v_pk_mul_f32 v[90:91], v[50:51], v[40:41] op_sel:[1,1] op_sel_hi:[0,1]
	v_fma_f32 v92, v50, v40, -v90
	v_fma_f32 v93, v51, v40, v91
	s_nop 0
	s_waitcnt lgkmcnt(0)
	v_pk_mul_f32 v[40:41], v[226:227], v[48:49] op_sel:[1,1] op_sel_hi:[0,1]
	v_fma_f32 v50, v226, v48, -v40
	v_fma_f32 v51, v227, v48, v41
	s_waitcnt lgkmcnt(0)
	v_pk_mul_f32 v[40:41], v[228:229], v[44:45] op_sel:[1,1] op_sel_hi:[0,1]
	v_fma_f32 v46, v228, v44, -v40
	v_fma_f32 v47, v229, v44, v41
	s_waitcnt lgkmcnt(0)
	v_pk_mul_f32 v[52:53], v[232:233], v[30:31] op_sel:[1,1] op_sel_hi:[0,1]
	v_pk_mul_f32 v[40:41], v[42:43], v[230:231] op_sel:[1,1] op_sel_hi:[1,0]
	s_nop 0
	v_fma_f32 v44, v42, v230, -v40
	v_fma_f32 v45, v42, v231, v41
	v_mov_b64_e32 v[42:43], v[236:237]
	v_fma_f32 v54, v232, v30, -v52
	v_fma_f32 v55, v233, v30, v53
	ds_write2_b64 v117, v[32:33], v[92:93] offset1:72
	ds_write2_b64 v117, v[50:51], v[46:47] offset0:144 offset1:216
	s_waitcnt lgkmcnt(0)
	v_pk_mul_f32 v[30:31], v[34:35], v[234:235] op_sel:[1,1] op_sel_hi:[1,0]
	s_nop 0
	v_fma_f32 v48, v34, v234, -v30
	v_fma_f32 v49, v34, v235, v31
	s_waitcnt lgkmcnt(0)
	v_pk_mul_f32 v[30:31], v[42:43], v[28:29] op_sel:[1,1] op_sel_hi:[0,1]
	v_fma_f32 v40, v42, v28, -v30
	v_fma_f32 v41, v43, v28, v31
	s_nop 0
	ds_read2_b64 v[28:31], v191 offset1:72
	ds_read2_b64 v[32:35], v192 offset0:32 offset1:104
	ds_write2_b64 v63, v[44:45], v[54:55] offset0:32 offset1:104
	ds_write2_b64 v63, v[48:49], v[40:41] offset0:176 offset1:248
	ds_read2_b64 v[40:43], v191 offset0:144 offset1:216
	ds_read2_b64 v[44:47], v192 offset0:176 offset1:248
	v_mov_b64_e32 v[50:51], v[224:225]
	s_waitcnt lgkmcnt(0)
	v_pk_add_f32 v[48:49], v[28:29], v[32:33]
	v_pk_add_f32 v[28:29], v[28:29], v[32:33] neg_lo:[0,1] neg_hi:[0,1]
	v_pk_add_f32 v[32:33], v[30:31], v[34:35]
	v_pk_add_f32 v[30:31], v[30:31], v[34:35] neg_lo:[0,1] neg_hi:[0,1]
	s_waitcnt lgkmcnt(0)
	v_pk_add_f32 v[34:35], v[40:41], v[44:45]
	v_pk_add_f32 v[40:41], v[40:41], v[44:45] neg_lo:[0,1] neg_hi:[0,1]
	v_pk_add_f32 v[44:45], v[42:43], v[46:47]
	v_pk_add_f32 v[42:43], v[42:43], v[46:47] neg_lo:[0,1] neg_hi:[0,1]
	v_pk_add_f32 v[46:47], v[30:31], v[30:31] op_sel:[1,0]
	v_pk_add_f32 v[30:31], v[30:31], v[30:31] op_sel_hi:[1,0] neg_lo:[0,1] neg_hi:[0,1]
	s_nop 0
	v_mov_b32_e32 v47, v31
	v_xor_b32_e32 v31, 0x80000000, v40
	v_mov_b32_e32 v30, v41
	v_pk_add_f32 v[40:41], v[42:43], v[42:43] op_sel:[1,0] neg_lo:[0,1] neg_hi:[0,1]
	v_pk_add_f32 v[42:43], v[42:43], v[42:43] op_sel_hi:[1,0]
	s_nop 0
	v_mov_b32_e32 v41, v43
	v_pk_add_f32 v[42:43], v[48:49], v[34:35]
	v_pk_add_f32 v[34:35], v[48:49], v[34:35] neg_lo:[0,1] neg_hi:[0,1]
	v_pk_add_f32 v[48:49], v[32:33], v[44:45]
	v_pk_add_f32 v[32:33], v[32:33], v[44:45] neg_lo:[0,1] neg_hi:[0,1]
	v_pk_mul_f32 v[40:41], v[40:41], s[20:21]
	v_xor_b32_e32 v45, 0x80000000, v32
	v_mov_b32_e32 v44, v33
	v_pk_add_f32 v[32:33], v[42:43], v[48:49]
	v_pk_add_f32 v[42:43], v[42:43], v[48:49] neg_lo:[0,1] neg_hi:[0,1]
	v_pk_add_f32 v[48:49], v[34:35], v[44:45]
	v_pk_add_f32 v[34:35], v[34:35], v[44:45] neg_lo:[0,1] neg_hi:[0,1]
	v_pk_add_f32 v[44:45], v[28:29], v[30:31]
	v_pk_add_f32 v[28:29], v[28:29], v[30:31] neg_lo:[0,1] neg_hi:[0,1]
	v_pk_fma_f32 v[30:31], v[46:47], s[20:21], v[40:41] op_sel_hi:[1,0,1]
	v_pk_fma_f32 v[40:41], v[46:47], s[20:21], v[40:41] op_sel_hi:[1,0,1] neg_lo:[0,0,1] neg_hi:[0,0,1]
	s_nop 0
	v_xor_b32_e32 v47, 0x80000000, v40
	v_mov_b32_e32 v46, v41
	v_pk_add_f32 v[40:41], v[44:45], v[30:31]
	v_pk_add_f32 v[30:31], v[44:45], v[30:31] neg_lo:[0,1] neg_hi:[0,1]
	v_pk_add_f32 v[44:45], v[28:29], v[46:47]
	v_pk_add_f32 v[28:29], v[28:29], v[46:47] neg_lo:[0,1] neg_hi:[0,1]
	s_waitcnt lgkmcnt(0)
; __device__ __forceinline__ c2 cmul(c2 a, c2 b) { return (c2){a.x * b.x - a.y * b.y, a.x * b.y + a.y * b.x}; }
; template <int S> __device__ __forceinline__ void fwd_mid(c2* buf, const c2* tws, int tid) {
;     constexpr int lq = 9 - 3 * S, Q = 1 << lq; const c2* T = tws + (S == 1 ? 3584 : 4032);
;     const int k = tid & (Q - 1), base = ((tid >> lq) << (lq + 3)) + k;
;     c2 x[8];
;     c2* bp_ = buf + LP(base); constexpr int QP = Q + Q / 8;
; #pragma unroll
;     for (int r = 0; r < 8; ++r) x[r] = bp_[r * QP];
;     dft8(x);
; #pragma unroll
;     for (int q = 1; q < 8; ++q) x[q] = cmul(x[q], T[(q - 1) * Q + k]);
; #pragma unroll
;     for (int q = 0; q < 8; ++q) bp_[q * QP] = x[q];
; }
	v_pk_mul_f32 v[90:91], v[50:51], v[40:41] op_sel:[1,1] op_sel_hi:[0,1]
	v_fma_f32 v92, v50, v40, -v90
	v_fma_f32 v93, v51, v40, v91
	s_nop 0
	s_waitcnt lgkmcnt(0)
	v_pk_mul_f32 v[40:41], v[226:227], v[48:49] op_sel:[1,1] op_sel_hi:[0,1]
	v_fma_f32 v50, v226, v48, -v40
	v_fma_f32 v51, v227, v48, v41
	s_waitcnt lgkmcnt(0)
	v_pk_mul_f32 v[40:41], v[228:229], v[44:45] op_sel:[1,1] op_sel_hi:[0,1]
	v_fma_f32 v46, v228, v44, -v40
	v_fma_f32 v47, v229, v44, v41
	s_waitcnt lgkmcnt(0)
	v_pk_mul_f32 v[52:53], v[232:233], v[30:31] op_sel:[1,1] op_sel_hi:[0,1]
	v_pk_mul_f32 v[40:41], v[42:43], v[230:231] op_sel:[1,1] op_sel_hi:[1,0]
	s_nop 0
	v_fma_f32 v44, v42, v230, -v40
	v_fma_f32 v45, v42, v231, v41
	v_mov_b64_e32 v[40:41], v[234:235]
	v_mov_b64_e32 v[42:43], v[236:237]
	v_fma_f32 v54, v232, v30, -v52
	v_fma_f32 v55, v233, v30, v53
	s_nop 0
	s_waitcnt lgkmcnt(0)
	v_pk_mul_f32 v[30:31], v[34:35], v[40:41] op_sel:[1,1] op_sel_hi:[1,0]
	s_nop 0
	v_fma_f32 v48, v34, v40, -v30
	v_fma_f32 v49, v34, v41, v31
	s_waitcnt lgkmcnt(0)
	v_pk_mul_f32 v[30:31], v[42:43], v[28:29] op_sel:[1,1] op_sel_hi:[0,1]
	v_fma_f32 v34, v42, v28, -v30
	v_fma_f32 v35, v43, v28, v31
	s_nop 0
	ds_write2_b64 v191, v[32:33], v[92:93] offset1:72
	ds_write2_b64 v191, v[50:51], v[46:47] offset0:144 offset1:216
	ds_write2_b64 v192, v[44:45], v[54:55] offset0:32 offset1:104
	ds_write2_b64 v192, v[48:49], v[34:35] offset0:176 offset1:248
	s_waitcnt lgkmcnt(0)
	s_barrier
	ds_read2_b64 v[28:31], v119 offset1:9
	ds_read2_b64 v[32:35], v119 offset0:36 offset1:45
	ds_read2_b64 v[40:43], v119 offset0:18 offset1:27
	ds_read2_b64 v[44:47], v119 offset0:54 offset1:63
	v_mov_b64_e32 v[50:51], v[238:239]
	s_waitcnt lgkmcnt(0)
	v_pk_add_f32 v[48:49], v[28:29], v[32:33]
	v_pk_add_f32 v[28:29], v[28:29], v[32:33] neg_lo:[0,1] neg_hi:[0,1]
	v_pk_add_f32 v[32:33], v[30:31], v[34:35]
	v_pk_add_f32 v[30:31], v[30:31], v[34:35] neg_lo:[0,1] neg_hi:[0,1]
	s_waitcnt lgkmcnt(0)
	v_pk_add_f32 v[34:35], v[40:41], v[44:45]
	v_pk_add_f32 v[40:41], v[40:41], v[44:45] neg_lo:[0,1] neg_hi:[0,1]
	v_pk_add_f32 v[44:45], v[42:43], v[46:47]
	v_pk_add_f32 v[42:43], v[42:43], v[46:47] neg_lo:[0,1] neg_hi:[0,1]
	v_pk_add_f32 v[46:47], v[30:31], v[30:31] op_sel:[1,0]
	v_pk_add_f32 v[30:31], v[30:31], v[30:31] op_sel_hi:[1,0] neg_lo:[0,1] neg_hi:[0,1]
	s_nop 0
	v_mov_b32_e32 v47, v31
	v_xor_b32_e32 v31, 0x80000000, v40
	v_mov_b32_e32 v30, v41
	v_pk_add_f32 v[40:41], v[42:43], v[42:43] op_sel:[1,0] neg_lo:[0,1] neg_hi:[0,1]
	v_pk_add_f32 v[42:43], v[42:43], v[42:43] op_sel_hi:[1,0]
	s_nop 0
	v_mov_b32_e32 v41, v43
	v_pk_add_f32 v[42:43], v[48:49], v[34:35]
	v_pk_add_f32 v[34:35], v[48:49], v[34:35] neg_lo:[0,1] neg_hi:[0,1]
	v_pk_add_f32 v[48:49], v[32:33], v[44:45]
	v_pk_add_f32 v[32:33], v[32:33], v[44:45] neg_lo:[0,1] neg_hi:[0,1]
	v_pk_mul_f32 v[40:41], v[40:41], s[20:21]
	v_xor_b32_e32 v45, 0x80000000, v32
	v_mov_b32_e32 v44, v33
	v_pk_add_f32 v[32:33], v[42:43], v[48:49]
	v_pk_add_f32 v[42:43], v[42:43], v[48:49] neg_lo:[0,1] neg_hi:[0,1]
	v_pk_add_f32 v[48:49], v[34:35], v[44:45]
	v_pk_add_f32 v[34:35], v[34:35], v[44:45] neg_lo:[0,1] neg_hi:[0,1]
	v_pk_add_f32 v[44:45], v[28:29], v[30:31]
	v_pk_add_f32 v[28:29], v[28:29], v[30:31] neg_lo:[0,1] neg_hi:[0,1]
	v_pk_fma_f32 v[30:31], v[46:47], s[20:21], v[40:41] op_sel_hi:[1,0,1]
	v_pk_fma_f32 v[40:41], v[46:47], s[20:21], v[40:41] op_sel_hi:[1,0,1] neg_lo:[0,0,1] neg_hi:[0,0,1]
	s_nop 0
	v_xor_b32_e32 v47, 0x80000000, v40
	v_mov_b32_e32 v46, v41
	v_pk_add_f32 v[40:41], v[44:45], v[30:31]
	v_pk_add_f32 v[30:31], v[44:45], v[30:31] neg_lo:[0,1] neg_hi:[0,1]
	v_pk_add_f32 v[44:45], v[28:29], v[46:47]
	v_pk_add_f32 v[28:29], v[28:29], v[46:47] neg_lo:[0,1] neg_hi:[0,1]
	s_waitcnt lgkmcnt(0)
	v_pk_mul_f32 v[90:91], v[50:51], v[40:41] op_sel:[1,1] op_sel_hi:[0,1]
	v_fma_f32 v92, v50, v40, -v90
	v_fma_f32 v93, v51, v40, v91
	s_nop 0
	s_waitcnt lgkmcnt(0)
	v_pk_mul_f32 v[40:41], v[240:241], v[48:49] op_sel:[1,1] op_sel_hi:[0,1]
	v_fma_f32 v50, v240, v48, -v40
	v_fma_f32 v51, v241, v48, v41
	s_waitcnt lgkmcnt(0)
	v_pk_mul_f32 v[40:41], v[242:243], v[44:45] op_sel:[1,1] op_sel_hi:[0,1]
	v_fma_f32 v46, v242, v44, -v40
	v_fma_f32 v47, v243, v44, v41
	s_waitcnt lgkmcnt(0)
	v_pk_mul_f32 v[52:53], v[246:247], v[30:31] op_sel:[1,1] op_sel_hi:[0,1]
	v_pk_mul_f32 v[40:41], v[42:43], v[244:245] op_sel:[1,1] op_sel_hi:[1,0]
	s_nop 0
	v_fma_f32 v44, v42, v244, -v40
	v_fma_f32 v45, v42, v245, v41
	v_mov_b64_e32 v[42:43], v[250:251]
	v_fma_f32 v54, v246, v30, -v52
	v_fma_f32 v55, v247, v30, v53
	ds_write2_b64 v119, v[32:33], v[92:93] offset1:9
	ds_write2_b64 v119, v[50:51], v[46:47] offset0:18 offset1:27
	s_waitcnt lgkmcnt(0)
	v_pk_mul_f32 v[30:31], v[34:35], v[248:249] op_sel:[1,1] op_sel_hi:[1,0]
	s_nop 0
	v_fma_f32 v48, v34, v248, -v30
	v_fma_f32 v49, v34, v249, v31
	s_waitcnt lgkmcnt(0)
	v_pk_mul_f32 v[30:31], v[42:43], v[28:29] op_sel:[1,1] op_sel_hi:[0,1]
	v_fma_f32 v40, v42, v28, -v30
	v_fma_f32 v41, v43, v28, v31
	s_nop 0
	ds_read2_b64 v[28:31], v193 offset1:9
	ds_read2_b64 v[32:35], v193 offset0:36 offset1:45
	ds_write2_b64 v119, v[44:45], v[54:55] offset0:36 offset1:45
	ds_write2_b64 v119, v[48:49], v[40:41] offset0:54 offset1:63
	ds_read2_b64 v[40:43], v193 offset0:18 offset1:27
	ds_read2_b64 v[44:47], v193 offset0:54 offset1:63
	v_mov_b64_e32 v[50:51], v[238:239]
	s_waitcnt lgkmcnt(0)
	v_pk_add_f32 v[48:49], v[28:29], v[32:33]
	v_pk_add_f32 v[28:29], v[28:29], v[32:33] neg_lo:[0,1] neg_hi:[0,1]
	v_pk_add_f32 v[32:33], v[30:31], v[34:35]
	v_pk_add_f32 v[30:31], v[30:31], v[34:35] neg_lo:[0,1] neg_hi:[0,1]
	s_waitcnt lgkmcnt(0)
; __device__ __forceinline__ c2 cmul(c2 a, c2 b) { return (c2){a.x * b.x - a.y * b.y, a.x * b.y + a.y * b.x}; }
; template <int S> __device__ __forceinline__ void fwd_mid(c2* buf, const c2* tws, int tid) {
;     constexpr int lq = 9 - 3 * S, Q = 1 << lq; const c2* T = tws + (S == 1 ? 3584 : 4032);
;     const int k = tid & (Q - 1), base = ((tid >> lq) << (lq + 3)) + k;
;     c2 x[8];
;     c2* bp_ = buf + LP(base); constexpr int QP = Q + Q / 8;
; #pragma unroll
;     for (int r = 0; r < 8; ++r) x[r] = bp_[r * QP];
;     dft8(x);
; #pragma unroll
;     for (int q = 1; q < 8; ++q) x[q] = cmul(x[q], T[(q - 1) * Q + k]);
; #pragma unroll
;     for (int q = 0; q < 8; ++q) bp_[q * QP] = x[q];
; }
; __device__ __forceinline__ void fwd_s3(c2 (&x)[8], const c2* buf, int tid) {
; #pragma unroll
;     for (int r = 0; r < 8; ++r) x[r] = buf[9 * tid + r];
;     dft8(x);
; }
	v_pk_add_f32 v[34:35], v[40:41], v[44:45]
	v_pk_add_f32 v[40:41], v[40:41], v[44:45] neg_lo:[0,1] neg_hi:[0,1]
	v_pk_add_f32 v[44:45], v[42:43], v[46:47]
	v_pk_add_f32 v[42:43], v[42:43], v[46:47] neg_lo:[0,1] neg_hi:[0,1]
	v_pk_add_f32 v[46:47], v[30:31], v[30:31] op_sel:[1,0]
	v_pk_add_f32 v[30:31], v[30:31], v[30:31] op_sel_hi:[1,0] neg_lo:[0,1] neg_hi:[0,1]
	s_nop 0
	v_mov_b32_e32 v47, v31
	v_xor_b32_e32 v31, 0x80000000, v40
	v_mov_b32_e32 v30, v41
	v_pk_add_f32 v[40:41], v[42:43], v[42:43] op_sel:[1,0] neg_lo:[0,1] neg_hi:[0,1]
	v_pk_add_f32 v[42:43], v[42:43], v[42:43] op_sel_hi:[1,0]
	s_nop 0
	v_mov_b32_e32 v41, v43
	v_pk_add_f32 v[42:43], v[48:49], v[34:35]
	v_pk_add_f32 v[34:35], v[48:49], v[34:35] neg_lo:[0,1] neg_hi:[0,1]
	v_pk_add_f32 v[48:49], v[32:33], v[44:45]
	v_pk_add_f32 v[32:33], v[32:33], v[44:45] neg_lo:[0,1] neg_hi:[0,1]
	v_pk_mul_f32 v[40:41], v[40:41], s[20:21]
	v_xor_b32_e32 v45, 0x80000000, v32
	v_mov_b32_e32 v44, v33
	v_pk_add_f32 v[32:33], v[42:43], v[48:49]
	v_pk_add_f32 v[42:43], v[42:43], v[48:49] neg_lo:[0,1] neg_hi:[0,1]
	v_pk_add_f32 v[48:49], v[34:35], v[44:45]
	v_pk_add_f32 v[34:35], v[34:35], v[44:45] neg_lo:[0,1] neg_hi:[0,1]
	v_pk_add_f32 v[44:45], v[28:29], v[30:31]
	v_pk_add_f32 v[28:29], v[28:29], v[30:31] neg_lo:[0,1] neg_hi:[0,1]
	v_pk_fma_f32 v[30:31], v[46:47], s[20:21], v[40:41] op_sel_hi:[1,0,1]
	v_pk_fma_f32 v[40:41], v[46:47], s[20:21], v[40:41] op_sel_hi:[1,0,1] neg_lo:[0,0,1] neg_hi:[0,0,1]
	s_nop 0
	v_xor_b32_e32 v47, 0x80000000, v40
	v_mov_b32_e32 v46, v41
	v_pk_add_f32 v[40:41], v[44:45], v[30:31]
	v_pk_add_f32 v[30:31], v[44:45], v[30:31] neg_lo:[0,1] neg_hi:[0,1]
	v_pk_add_f32 v[44:45], v[28:29], v[46:47]
	v_pk_add_f32 v[28:29], v[28:29], v[46:47] neg_lo:[0,1] neg_hi:[0,1]
	s_waitcnt lgkmcnt(0)
	v_pk_mul_f32 v[90:91], v[50:51], v[40:41] op_sel:[1,1] op_sel_hi:[0,1]
	v_fma_f32 v92, v50, v40, -v90
	v_fma_f32 v93, v51, v40, v91
	s_nop 0
	s_waitcnt lgkmcnt(0)
	v_pk_mul_f32 v[40:41], v[240:241], v[48:49] op_sel:[1,1] op_sel_hi:[0,1]
	v_fma_f32 v50, v240, v48, -v40
	v_fma_f32 v51, v241, v48, v41
	s_waitcnt lgkmcnt(0)
	v_pk_mul_f32 v[40:41], v[242:243], v[44:45] op_sel:[1,1] op_sel_hi:[0,1]
	v_fma_f32 v46, v242, v44, -v40
	v_fma_f32 v47, v243, v44, v41
	s_waitcnt lgkmcnt(0)
	v_pk_mul_f32 v[52:53], v[246:247], v[30:31] op_sel:[1,1] op_sel_hi:[0,1]
	v_pk_mul_f32 v[40:41], v[42:43], v[244:245] op_sel:[1,1] op_sel_hi:[1,0]
	s_nop 0
	v_fma_f32 v44, v42, v244, -v40
	v_fma_f32 v45, v42, v245, v41
	v_mov_b64_e32 v[40:41], v[248:249]
	v_mov_b64_e32 v[42:43], v[250:251]
	v_fma_f32 v54, v246, v30, -v52
	v_fma_f32 v55, v247, v30, v53
	s_nop 0
	s_waitcnt lgkmcnt(0)
	v_pk_mul_f32 v[30:31], v[34:35], v[40:41] op_sel:[1,1] op_sel_hi:[1,0]
	s_nop 0
	v_fma_f32 v48, v34, v40, -v30
	v_fma_f32 v49, v34, v41, v31
	s_waitcnt lgkmcnt(0)
	v_pk_mul_f32 v[30:31], v[42:43], v[28:29] op_sel:[1,1] op_sel_hi:[0,1]
	v_fma_f32 v34, v42, v28, -v30
	v_fma_f32 v35, v43, v28, v31
	s_nop 0
	ds_write2_b64 v193, v[32:33], v[92:93] offset1:9
	ds_write2_b64 v193, v[50:51], v[46:47] offset0:18 offset1:27
	ds_write2_b64 v193, v[44:45], v[54:55] offset0:36 offset1:45
	ds_write2_b64 v193, v[48:49], v[34:35] offset0:54 offset1:63
	s_waitcnt lgkmcnt(0)
	s_barrier
	ds_read2_b64 v[28:31], v121 offset1:1
	ds_read2_b64 v[32:35], v121 offset0:4 offset1:5
	ds_read2_b64 v[40:43], v121 offset0:2 offset1:3
	ds_read2_b64 v[44:47], v121 offset0:6 offset1:7
	s_waitcnt lgkmcnt(0)
	v_pk_add_f32 v[48:49], v[28:29], v[32:33]
	v_pk_add_f32 v[28:29], v[28:29], v[32:33] neg_lo:[0,1] neg_hi:[0,1]
	v_pk_add_f32 v[32:33], v[30:31], v[34:35]
	v_pk_add_f32 v[30:31], v[30:31], v[34:35] neg_lo:[0,1] neg_hi:[0,1]
	s_waitcnt lgkmcnt(0)
	v_pk_add_f32 v[34:35], v[40:41], v[44:45]
	v_pk_add_f32 v[40:41], v[40:41], v[44:45] neg_lo:[0,1] neg_hi:[0,1]
	v_pk_add_f32 v[44:45], v[42:43], v[46:47]
	v_pk_add_f32 v[42:43], v[42:43], v[46:47] neg_lo:[0,1] neg_hi:[0,1]
	v_pk_add_f32 v[46:47], v[30:31], v[30:31] op_sel:[1,0]
	v_pk_add_f32 v[30:31], v[30:31], v[30:31] op_sel_hi:[1,0] neg_lo:[0,1] neg_hi:[0,1]
	s_nop 0
	v_mov_b32_e32 v47, v31
	v_xor_b32_e32 v31, 0x80000000, v40
	v_mov_b32_e32 v30, v41
	v_pk_add_f32 v[40:41], v[42:43], v[42:43] op_sel:[1,0] neg_lo:[0,1] neg_hi:[0,1]
	v_pk_add_f32 v[42:43], v[42:43], v[42:43] op_sel_hi:[1,0]
	s_nop 0
	v_mov_b32_e32 v41, v43
	v_pk_mul_f32 v[40:41], v[40:41], s[20:21]
	v_pk_add_f32 v[42:43], v[48:49], v[34:35]
	v_pk_add_f32 v[34:35], v[48:49], v[34:35] neg_lo:[0,1] neg_hi:[0,1]
	v_pk_add_f32 v[48:49], v[32:33], v[44:45]
	v_pk_add_f32 v[32:33], v[32:33], v[44:45] neg_lo:[0,1] neg_hi:[0,1]
	v_pk_add_f32 v[50:51], v[42:43], v[48:49]
	v_xor_b32_e32 v45, 0x80000000, v32
	v_mov_b32_e32 v44, v33
	v_pk_add_f32 v[48:49], v[42:43], v[48:49] neg_lo:[0,1] neg_hi:[0,1]
	v_pk_add_f32 v[32:33], v[28:29], v[30:31]
	v_pk_add_f32 v[42:43], v[28:29], v[30:31] neg_lo:[0,1] neg_hi:[0,1]
	v_pk_fma_f32 v[28:29], v[46:47], s[20:21], v[40:41] op_sel_hi:[1,0,1]
	v_pk_fma_f32 v[30:31], v[46:47], s[20:21], v[40:41] op_sel_hi:[1,0,1] neg_lo:[0,0,1] neg_hi:[0,0,1]
	v_pk_add_f32 v[52:53], v[34:35], v[44:45]
	v_pk_add_f32 v[54:55], v[34:35], v[44:45] neg_lo:[0,1] neg_hi:[0,1]
	v_xor_b32_e32 v41, 0x80000000, v30
	v_mov_b32_e32 v40, v31
	v_pk_add_f32 v[90:91], v[32:33], v[28:29]
	v_pk_add_f32 v[92:93], v[32:33], v[28:29] neg_lo:[0,1] neg_hi:[0,1]
	ds_read2_b64 v[28:31], v194 offset1:1
	ds_read2_b64 v[32:35], v195 offset1:1
	v_pk_add_f32 v[94:95], v[42:43], v[40:41]
	v_pk_add_f32 v[96:97], v[42:43], v[40:41] neg_lo:[0,1] neg_hi:[0,1]
	ds_read2_b64 v[40:43], v196 offset1:1
	ds_read2_b64 v[44:47], v197 offset1:1
	s_waitcnt lgkmcnt(0)
; __device__ __forceinline__ c2 mni(c2 a) { return (c2){a.y, -a.x}; }
; #define ZVAL(r, t) ((o == 0) ? dwl((r), (t), zw0, zw1, zw2, zb) : bf2f((r)[8 + (t)]))
; __device__ __forceinline__ void dft8(c2 (&x)[8]) {
;     const float s = 0.70710678118654752f;
;     const c2 a0 = x[0] + x[4], a4 = x[0] - x[4], a1 = x[1] + x[5], a5 = x[1] - x[5], a2 = x[2] + x[6], a6 = x[2] - x[6], a3 = x[3] + x[7], a7 = x[3] - x[7];
;     const c2 a5w = (c2){(a5.x + a5.y) * s, (a5.y - a5.x) * s};
;     const c2 a6w = mni(a6);
;     const c2 a7w = (c2){(a7.y - a7.x) * s, -(a7.x + a7.y) * s};
;     const c2 b0 = a0 + a2, b1 = a0 - a2, b2 = a1 + a3, b3 = mni(a1 - a3);
;     x[0] = b0 + b2; x[4] = b0 - b2; x[2] = b1 + b3; x[6] = b1 - b3;
;     const c2 c0 = a4 + a6w, c1 = a4 - a6w, c2_ = a5w + a7w, c3 = mni(a5w - a7w);
;     x[1] = c0 + c2_; x[5] = c0 - c2_; x[3] = c1 + c3; x[7] = c1 - c3;
; }
; __device__ __forceinline__ void phase_conv(const Params& p, int o, unsigned char* smem, int wave) {
;     ...
;                         c2 x0[8], x1[8];
; #pragma unroll
;                         for (int r = 0; r < 4; ++r) { const int t = tid + 512 * r; x0[r] = (c2){ZVAL(raw + (2 * hh) * RAWROW, t), 0.f}; x1[r] = (c2){ZVAL(raw + (2 * hh + 1) * RAWROW, t), 0.f}; x0[4 + r] = (c2){0.f, 0.f}; x1[4 + r] = (c2){0.f, 0.f}; }
;                         fft_fwd_regs2(x0, x1, buf0, buf1, tws, tid);
; #pragma unroll
;                         for (int q = 0; q < 8; ++q) { sZ[((4 * a + 2 * hh) * 8 + q) * 512 + tid] = x0[q]; sZ[((4 * a + 2 * hh + 1) * 8 + q) * 512 + tid] = x1[q]; }
;                         __syncthreads();
	v_pk_add_f32 v[98:99], v[28:29], v[32:33]
	v_pk_add_f32 v[28:29], v[28:29], v[32:33] neg_lo:[0,1] neg_hi:[0,1]
	v_pk_add_f32 v[32:33], v[30:31], v[34:35]
	v_pk_add_f32 v[30:31], v[30:31], v[34:35] neg_lo:[0,1] neg_hi:[0,1]
	s_waitcnt lgkmcnt(0)
	v_pk_add_f32 v[34:35], v[40:41], v[44:45]
	v_pk_add_f32 v[40:41], v[40:41], v[44:45] neg_lo:[0,1] neg_hi:[0,1]
	v_pk_add_f32 v[44:45], v[42:43], v[46:47]
	v_pk_add_f32 v[42:43], v[42:43], v[46:47] neg_lo:[0,1] neg_hi:[0,1]
	v_pk_add_f32 v[46:47], v[30:31], v[30:31] op_sel:[1,0]
	v_pk_add_f32 v[30:31], v[30:31], v[30:31] op_sel_hi:[1,0] neg_lo:[0,1] neg_hi:[0,1]
	s_nop 0
	v_mov_b32_e32 v47, v31
	v_xor_b32_e32 v31, 0x80000000, v40
	v_mov_b32_e32 v30, v41
	v_pk_add_f32 v[40:41], v[42:43], v[42:43] op_sel:[1,0] neg_lo:[0,1] neg_hi:[0,1]
	v_pk_add_f32 v[42:43], v[42:43], v[42:43] op_sel_hi:[1,0]
	s_nop 0
	v_mov_b32_e32 v41, v43
	v_pk_add_f32 v[42:43], v[98:99], v[34:35]
	v_pk_add_f32 v[34:35], v[98:99], v[34:35] neg_lo:[0,1] neg_hi:[0,1]
	v_pk_add_f32 v[98:99], v[32:33], v[44:45]
	v_pk_add_f32 v[32:33], v[32:33], v[44:45] neg_lo:[0,1] neg_hi:[0,1]
	v_pk_mul_f32 v[40:41], v[40:41], s[20:21]
	v_xor_b32_e32 v45, 0x80000000, v32
	v_mov_b32_e32 v44, v33
	v_pk_add_f32 v[32:33], v[42:43], v[98:99]
	v_pk_add_f32 v[42:43], v[42:43], v[98:99] neg_lo:[0,1] neg_hi:[0,1]
	v_pk_add_f32 v[98:99], v[34:35], v[44:45]
	v_pk_add_f32 v[34:35], v[34:35], v[44:45] neg_lo:[0,1] neg_hi:[0,1]
	v_pk_add_f32 v[44:45], v[28:29], v[30:31]
	v_pk_add_f32 v[28:29], v[28:29], v[30:31] neg_lo:[0,1] neg_hi:[0,1]
	v_pk_fma_f32 v[30:31], v[46:47], s[20:21], v[40:41] op_sel_hi:[1,0,1]
	v_pk_fma_f32 v[40:41], v[46:47], s[20:21], v[40:41] op_sel_hi:[1,0,1] neg_lo:[0,0,1] neg_hi:[0,0,1]
	s_nop 0
	v_xor_b32_e32 v47, 0x80000000, v40
	v_mov_b32_e32 v46, v41
	v_pk_add_f32 v[40:41], v[44:45], v[30:31]
	v_pk_add_f32 v[30:31], v[44:45], v[30:31] neg_lo:[0,1] neg_hi:[0,1]
	v_pk_add_f32 v[44:45], v[28:29], v[46:47]
	v_pk_add_f32 v[28:29], v[28:29], v[46:47] neg_lo:[0,1] neg_hi:[0,1]
	v_add_u32_e32 v46, s7, v113
	v_ashrrev_i32_e32 v47, 31, v46
	v_lshl_add_u64 v[46:47], v[46:47], 3, s[18:19]
	global_store_dwordx2 v[46:47], v[50:51], off
	v_add_u32_e32 v46, s7, v124
	v_ashrrev_i32_e32 v47, 31, v46
	v_lshl_add_u64 v[46:47], v[46:47], 3, s[18:19]
	global_store_dwordx2 v[46:47], v[32:33], off
	v_add_u32_e32 v32, s16, v113
	v_ashrrev_i32_e32 v33, 31, v32
	v_lshl_add_u64 v[32:33], v[32:33], 3, s[18:19]
	global_store_dwordx2 v[32:33], v[90:91], off
	v_add_u32_e32 v32, s16, v124
	v_ashrrev_i32_e32 v33, 31, v32
	v_lshl_add_u64 v[32:33], v[32:33], 3, s[18:19]
	s_or_b32 s16, s7, 0x400
	global_store_dwordx2 v[32:33], v[40:41], off
	v_add_u32_e32 v32, s16, v113
	v_ashrrev_i32_e32 v33, 31, v32
	v_lshl_add_u64 v[32:33], v[32:33], 3, s[18:19]
	global_store_dwordx2 v[32:33], v[52:53], off
	v_add_u32_e32 v32, s16, v124
	v_ashrrev_i32_e32 v33, 31, v32
	v_lshl_add_u64 v[32:33], v[32:33], 3, s[18:19]
	s_or_b32 s16, s7, 0x600
	global_store_dwordx2 v[32:33], v[98:99], off
	v_add_u32_e32 v32, s16, v113
	v_ashrrev_i32_e32 v33, 31, v32
	v_lshl_add_u64 v[32:33], v[32:33], 3, s[18:19]
	global_store_dwordx2 v[32:33], v[94:95], off
	v_add_u32_e32 v32, s16, v124
	v_ashrrev_i32_e32 v33, 31, v32
	v_lshl_add_u64 v[32:33], v[32:33], 3, s[18:19]
	s_or_b32 s16, s7, 0x800
	global_store_dwordx2 v[32:33], v[44:45], off
	v_add_u32_e32 v32, s16, v113
	v_ashrrev_i32_e32 v33, 31, v32
	v_lshl_add_u64 v[32:33], v[32:33], 3, s[18:19]
	global_store_dwordx2 v[32:33], v[48:49], off
	v_add_u32_e32 v32, s16, v124
	v_ashrrev_i32_e32 v33, 31, v32
	v_lshl_add_u64 v[32:33], v[32:33], 3, s[18:19]
	s_or_b32 s16, s7, 0xa00
	global_store_dwordx2 v[32:33], v[42:43], off
	v_add_u32_e32 v32, s16, v113
	v_ashrrev_i32_e32 v33, 31, v32
	v_lshl_add_u64 v[32:33], v[32:33], 3, s[18:19]
	global_store_dwordx2 v[32:33], v[92:93], off
	v_add_u32_e32 v32, s16, v124
	v_ashrrev_i32_e32 v33, 31, v32
	v_lshl_add_u64 v[32:33], v[32:33], 3, s[18:19]
	s_or_b32 s16, s7, 0xc00
	global_store_dwordx2 v[32:33], v[30:31], off
	v_add_u32_e32 v30, s16, v113
	v_ashrrev_i32_e32 v31, 31, v30
	v_lshl_add_u64 v[30:31], v[30:31], 3, s[18:19]
	global_store_dwordx2 v[30:31], v[54:55], off
	v_add_u32_e32 v30, s16, v124
	v_ashrrev_i32_e32 v31, 31, v30
	v_lshl_add_u64 v[30:31], v[30:31], 3, s[18:19]
	s_or_b32 s7, s7, 0xe00
	global_store_dwordx2 v[30:31], v[34:35], off
	v_add_u32_e32 v30, s7, v113
	v_ashrrev_i32_e32 v31, 31, v30
	v_lshl_add_u64 v[30:31], v[30:31], 3, s[18:19]
	global_store_dwordx2 v[30:31], v[96:97], off
	v_add_u32_e32 v30, s7, v124
	v_ashrrev_i32_e32 v31, 31, v30
	v_lshl_add_u64 v[30:31], v[30:31], 3, s[18:19]
	global_store_dwordx2 v[30:31], v[28:29], off
	s_barrier
	s_cbranch_vccnz .LBB0_526

; __device__ __forceinline__ void idft8(c2 (&x)[8]) {
;     const float s = 0.70710678118654752f;
;     const c2 a0 = x[0] + x[4], a4 = x[0] - x[4], a1 = x[1] + x[5], a5 = x[1] - x[5], a2 = x[2] + x[6], a6 = x[2] - x[6], a3 = x[3] + x[7], a7 = x[3] - x[7];
;     const c2 a5w = (c2){(a5.x - a5.y) * s, (a5.x + a5.y) * s};
;     const c2 a6w = mpi(a6);
;     const c2 a7w = (c2){-(a7.x + a7.y) * s, (a7.x - a7.y) * s};
;     const c2 b0 = a0 + a2, b1 = a0 - a2, b2 = a1 + a3, b3 = mpi(a1 - a3);
;     x[0] = b0 + b2; x[4] = b0 - b2; x[2] = b1 + b3; x[6] = b1 - b3;
;     const c2 c0 = a4 + a6w, c1 = a4 - a6w, c2_ = a5w + a7w, c3 = mpi(a5w - a7w);
;     x[1] = c0 + c2_; x[5] = c0 - c2_; x[3] = c1 + c3; x[7] = c1 - c3;
; }
; __device__ __forceinline__ void fwd_s0(c2 (&x)[8], c2* buf, const c2* tws, int tid) {
;     dft8(x);
; #pragma unroll
;     for (int q = 1; q < 8; ++q) x[q] = cmul(x[q], tws[(q - 1) * 512 + tid]);
;     { c2* bp_ = buf + LP(tid);
; #pragma unroll
;     for (int q = 0; q < 8; ++q) bp_[576 * q] = x[q]; }
; }
; template <int S> __device__ __forceinline__ void fwd_mid(c2* buf, const c2* tws, int tid) {
;     constexpr int lq = 9 - 3 * S, Q = 1 << lq; const c2* T = tws + (S == 1 ? 3584 : 4032);
;     const int k = tid & (Q - 1), base = ((tid >> lq) << (lq + 3)) + k;
;     c2 x[8];
;     c2* bp_ = buf + LP(base); constexpr int QP = Q + Q / 8;
; #pragma unroll
;     for (int r = 0; r < 8; ++r) x[r] = bp_[r * QP];
;     dft8(x);
; #pragma unroll
;     for (int q = 1; q < 8; ++q) x[q] = cmul(x[q], T[(q - 1) * Q + k]);
; #pragma unroll
;     for (int q = 0; q < 8; ++q) bp_[q * QP] = x[q];
; }
; __device__ __forceinline__ void fwd_s3(c2 (&x)[8], const c2* buf, int tid) {
; #pragma unroll
;     for (int r = 0; r < 8; ++r) x[r] = buf[9 * tid + r];
;     dft8(x);
; }
; __device__ __forceinline__ void inv_s3(c2 (&x)[8], c2* buf, int tid) {
;     idft8(x);
; #pragma unroll
;     for (int q = 0; q < 8; ++q) buf[9 * tid + q] = x[q];
; }
; __device__ __forceinline__ void phase_conv(const Params& p, int o, unsigned char* smem, int wave) {
;     ...
;                     c2 x0[8], x1[8];
; #pragma unroll
;                     for (int q = 0; q < 8; ++q) { x0[q] = sZ[((2 * a) * 8 + q) * 512 + tid]; x1[q] = sZ[((2 * a + 1) * 8 + q) * 512 + tid]; }
;                     fft_inv_regs2(x0, x1, buf0, buf1, tws, tid);
.LBB0_633:
	s_or_b32 s7, s3, 0x200
	v_add_u32_e32 v16, s3, v113
	v_add_u32_e32 v18, s7, v113
	v_ashrrev_i32_e32 v17, 31, v16
	v_ashrrev_i32_e32 v19, 31, v18
	v_lshl_add_u64 v[16:17], v[16:17], 3, s[18:19]
	v_lshl_add_u64 v[18:19], v[18:19], 3, s[18:19]
	global_load_dwordx2 v[22:23], v[16:17], off
	global_load_dwordx2 v[26:27], v[18:19], off
	v_add_u32_e32 v18, s7, v124
	s_or_b32 s7, s3, 0x400
	v_add_u32_e32 v16, s3, v124
	v_add_u32_e32 v20, s7, v113
	v_ashrrev_i32_e32 v17, 31, v16
	v_ashrrev_i32_e32 v19, 31, v18
	v_ashrrev_i32_e32 v21, 31, v20
	v_lshl_add_u64 v[16:17], v[16:17], 3, s[18:19]
	v_lshl_add_u64 v[18:19], v[18:19], 3, s[18:19]
	v_lshl_add_u64 v[20:21], v[20:21], 3, s[18:19]
	global_load_dwordx2 v[16:17], v[16:17], off
	s_mov_b32 s62, s21
	global_load_dwordx2 v[18:19], v[18:19], off
	s_mov_b32 s63, s20
	global_load_dwordx2 v[30:31], v[20:21], off
	v_add_u32_e32 v20, s7, v124
	s_or_b32 s7, s3, 0x600
	v_add_u32_e32 v24, s7, v113
	v_ashrrev_i32_e32 v21, 31, v20
	v_ashrrev_i32_e32 v25, 31, v24
	v_lshl_add_u64 v[20:21], v[20:21], 3, s[18:19]
	v_lshl_add_u64 v[24:25], v[24:25], 3, s[18:19]
	global_load_dwordx2 v[20:21], v[20:21], off
	s_and_b64 vcc, exec, s[30:31]
	global_load_dwordx2 v[32:33], v[24:25], off
	v_add_u32_e32 v24, s7, v124
	s_or_b32 s7, s3, 0x800
	v_add_u32_e32 v28, s7, v113
	v_ashrrev_i32_e32 v25, 31, v24
	v_ashrrev_i32_e32 v29, 31, v28
	v_lshl_add_u64 v[24:25], v[24:25], 3, s[18:19]
	v_lshl_add_u64 v[28:29], v[28:29], 3, s[18:19]
	global_load_dwordx2 v[24:25], v[24:25], off
	s_nop 0
	global_load_dwordx2 v[34:35], v[28:29], off
	v_add_u32_e32 v28, s7, v124
	s_or_b32 s7, s3, 0xa00
	v_add_u32_e32 v36, s7, v113
	v_add_u32_e32 v38, s7, v124
	s_or_b32 s7, s3, 0xc00
	v_add_u32_e32 v40, s7, v113
	v_add_u32_e32 v42, s7, v124
	s_or_b32 s7, s3, 0xe00
	v_ashrrev_i32_e32 v29, 31, v28
	v_ashrrev_i32_e32 v37, 31, v36
	v_add_u32_e32 v44, s7, v113
	v_lshl_add_u64 v[28:29], v[28:29], 3, s[18:19]
	v_lshl_add_u64 v[36:37], v[36:37], 3, s[18:19]
	v_ashrrev_i32_e32 v39, 31, v38
	v_ashrrev_i32_e32 v41, 31, v40
	v_ashrrev_i32_e32 v43, 31, v42
	v_ashrrev_i32_e32 v45, 31, v44
	global_load_dwordx2 v[28:29], v[28:29], off
	v_lshl_add_u64 v[38:39], v[38:39], 3, s[18:19]
	global_load_dwordx2 v[36:37], v[36:37], off
	v_lshl_add_u64 v[40:41], v[40:41], 3, s[18:19]
	v_lshl_add_u64 v[42:43], v[42:43], 3, s[18:19]
	v_lshl_add_u64 v[44:45], v[44:45], 3, s[18:19]
	global_load_dwordx2 v[38:39], v[38:39], off
	v_add_u32_e32 v46, s7, v124
	global_load_dwordx2 v[40:41], v[40:41], off
	v_ashrrev_i32_e32 v47, 31, v46
	global_load_dwordx2 v[42:43], v[42:43], off
	v_lshl_add_u64 v[46:47], v[46:47], 3, s[18:19]
	global_load_dwordx2 v[44:45], v[44:45], off
	s_waitcnt vmcnt(6)
	v_pk_add_f32 v[48:49], v[22:23], v[34:35]
	global_load_dwordx2 v[46:47], v[46:47], off
	v_pk_add_f32 v[22:23], v[22:23], v[34:35] neg_lo:[0,1] neg_hi:[0,1]
	s_waitcnt vmcnt(5)
	v_pk_add_f32 v[34:35], v[26:27], v[36:37]
	v_pk_add_f32 v[26:27], v[26:27], v[36:37] neg_lo:[0,1] neg_hi:[0,1]
	s_waitcnt vmcnt(3)
	v_pk_add_f32 v[36:37], v[30:31], v[40:41]
	v_pk_add_f32 v[30:31], v[30:31], v[40:41] neg_lo:[0,1] neg_hi:[0,1]
	s_waitcnt vmcnt(1)
	v_pk_add_f32 v[40:41], v[32:33], v[44:45]
	v_pk_add_f32 v[32:33], v[32:33], v[44:45] neg_lo:[0,1] neg_hi:[0,1]
	v_pk_add_f32 v[44:45], v[26:27], v[26:27] op_sel:[0,1] neg_lo:[0,1] neg_hi:[0,1]
	v_pk_add_f32 v[26:27], v[26:27], v[26:27] op_sel_hi:[0,1]
	v_mov_b32_e32 v45, v27
	v_xor_b32_e32 v26, 0x80000000, v31
	v_mov_b32_e32 v27, v30
	v_pk_add_f32 v[30:31], v[32:33], v[32:33] op_sel:[0,1]
	v_pk_add_f32 v[32:33], v[32:33], v[32:33] op_sel_hi:[0,1] neg_lo:[0,1] neg_hi:[0,1]
	v_mov_b32_e32 v31, v33
	v_pk_add_f32 v[32:33], v[48:49], v[36:37]
	v_pk_add_f32 v[36:37], v[48:49], v[36:37] neg_lo:[0,1] neg_hi:[0,1]
	v_pk_add_f32 v[48:49], v[34:35], v[40:41]
	v_pk_add_f32 v[34:35], v[34:35], v[40:41] neg_lo:[0,1] neg_hi:[0,1]
	v_pk_mul_f32 v[30:31], v[30:31], s[62:63]
	v_xor_b32_e32 v40, 0x80000000, v35
	v_mov_b32_e32 v41, v34
	v_pk_add_f32 v[34:35], v[32:33], v[48:49]
	v_pk_add_f32 v[32:33], v[32:33], v[48:49] neg_lo:[0,1] neg_hi:[0,1]
	v_pk_add_f32 v[48:49], v[36:37], v[40:41]
	v_pk_add_f32 v[36:37], v[36:37], v[40:41] neg_lo:[0,1] neg_hi:[0,1]
	v_pk_add_f32 v[40:41], v[22:23], v[26:27]
	v_pk_add_f32 v[22:23], v[22:23], v[26:27] neg_lo:[0,1] neg_hi:[0,1]
	v_pk_fma_f32 v[26:27], v[44:45], s[20:21], v[30:31] op_sel_hi:[1,0,1]
	v_pk_fma_f32 v[30:31], v[44:45], s[20:21], v[30:31] op_sel_hi:[1,0,1] neg_lo:[0,0,1] neg_hi:[0,0,1]
	s_nop 0
	v_xor_b32_e32 v44, 0x80000000, v31
	v_mov_b32_e32 v45, v30
	v_pk_add_f32 v[30:31], v[40:41], v[26:27]
	v_pk_add_f32 v[26:27], v[40:41], v[26:27] neg_lo:[0,1] neg_hi:[0,1]
	v_pk_add_f32 v[40:41], v[22:23], v[44:45]
	v_pk_add_f32 v[22:23], v[22:23], v[44:45] neg_lo:[0,1] neg_hi:[0,1]
	ds_write2_b64 v121, v[34:35], v[30:31] offset1:1
	ds_write2_b64 v121, v[48:49], v[40:41] offset0:2 offset1:3
	ds_write2_b64 v121, v[32:33], v[26:27] offset0:4 offset1:5
	ds_write2_b64 v121, v[36:37], v[22:23] offset0:6 offset1:7
	v_pk_add_f32 v[26:27], v[18:19], v[38:39]
	v_pk_add_f32 v[18:19], v[18:19], v[38:39] neg_lo:[0,1] neg_hi:[0,1]
	v_pk_add_f32 v[22:23], v[16:17], v[28:29]
	v_pk_add_f32 v[16:17], v[16:17], v[28:29] neg_lo:[0,1] neg_hi:[0,1]
	v_pk_add_f32 v[28:29], v[20:21], v[42:43]
	v_pk_add_f32 v[20:21], v[20:21], v[42:43] neg_lo:[0,1] neg_hi:[0,1]
	v_pk_add_f32 v[32:33], v[18:19], v[18:19] op_sel:[0,1] neg_lo:[0,1] neg_hi:[0,1]
	v_pk_add_f32 v[18:19], v[18:19], v[18:19] op_sel_hi:[0,1]
	v_mov_b32_e32 v33, v19
	v_xor_b32_e32 v18, 0x80000000, v21
	v_mov_b32_e32 v19, v20
	s_waitcnt vmcnt(0)
; __device__ __forceinline__ c2 cmulc(c2 a, c2 b) { return (c2){a.x * b.x + a.y * b.y, a.y * b.x - a.x * b.y}; }
; __device__ __forceinline__ c2 mpi(c2 a) { return (c2){-a.y, a.x}; }
; __device__ __forceinline__ void idft8(c2 (&x)[8]) {
;     const float s = 0.70710678118654752f;
;     const c2 a0 = x[0] + x[4], a4 = x[0] - x[4], a1 = x[1] + x[5], a5 = x[1] - x[5], a2 = x[2] + x[6], a6 = x[2] - x[6], a3 = x[3] + x[7], a7 = x[3] - x[7];
;     const c2 a5w = (c2){(a5.x - a5.y) * s, (a5.x + a5.y) * s};
;     const c2 a6w = mpi(a6);
;     const c2 a7w = (c2){-(a7.x + a7.y) * s, (a7.x - a7.y) * s};
;     const c2 b0 = a0 + a2, b1 = a0 - a2, b2 = a1 + a3, b3 = mpi(a1 - a3);
;     x[0] = b0 + b2; x[4] = b0 - b2; x[2] = b1 + b3; x[6] = b1 - b3;
;     const c2 c0 = a4 + a6w, c1 = a4 - a6w, c2_ = a5w + a7w, c3 = mpi(a5w - a7w);
;     x[1] = c0 + c2_; x[5] = c0 - c2_; x[3] = c1 + c3; x[7] = c1 - c3;
; }
; template <int S> __device__ __forceinline__ void inv_mid(c2* buf, const c2* tws, int tid) {
;     constexpr int lq = 9 - 3 * S, Q = 1 << lq; const c2* T = tws + (S == 1 ? 3584 : 4032);
;     const int k = tid & (Q - 1), base = ((tid >> lq) << (lq + 3)) + k;
;     c2 x[8];
;     c2* bp_ = buf + LP(base); constexpr int QP = Q + Q / 8;
; #pragma unroll
;     for (int r = 0; r < 8; ++r) { c2 v = bp_[r * QP]; if (r) v = cmulc(v, T[(r - 1) * Q + k]); x[r] = v; }
;     idft8(x);
; #pragma unroll
;     for (int q = 0; q < 8; ++q) bp_[q * QP] = x[q];
; }
	v_pk_add_f32 v[30:31], v[24:25], v[46:47]
	v_pk_add_f32 v[24:25], v[24:25], v[46:47] neg_lo:[0,1] neg_hi:[0,1]
	s_nop 0
	v_pk_add_f32 v[20:21], v[24:25], v[24:25] op_sel:[0,1]
	v_pk_add_f32 v[24:25], v[24:25], v[24:25] op_sel_hi:[0,1] neg_lo:[0,1] neg_hi:[0,1]
	v_mov_b32_e32 v21, v25
	v_pk_add_f32 v[24:25], v[22:23], v[28:29]
	v_pk_add_f32 v[22:23], v[22:23], v[28:29] neg_lo:[0,1] neg_hi:[0,1]
	v_pk_add_f32 v[28:29], v[26:27], v[30:31]
	v_pk_add_f32 v[26:27], v[26:27], v[30:31] neg_lo:[0,1] neg_hi:[0,1]
	v_pk_mul_f32 v[20:21], v[20:21], s[62:63]
	v_xor_b32_e32 v30, 0x80000000, v27
	v_mov_b32_e32 v31, v26
	v_pk_add_f32 v[26:27], v[24:25], v[28:29]
	v_pk_add_f32 v[24:25], v[24:25], v[28:29] neg_lo:[0,1] neg_hi:[0,1]
	v_pk_add_f32 v[28:29], v[22:23], v[30:31]
	v_pk_add_f32 v[22:23], v[22:23], v[30:31] neg_lo:[0,1] neg_hi:[0,1]
	v_pk_add_f32 v[30:31], v[16:17], v[18:19]
	v_pk_add_f32 v[16:17], v[16:17], v[18:19] neg_lo:[0,1] neg_hi:[0,1]
	v_pk_fma_f32 v[18:19], v[32:33], s[20:21], v[20:21] op_sel_hi:[1,0,1]
	v_pk_fma_f32 v[20:21], v[32:33], s[20:21], v[20:21] op_sel_hi:[1,0,1] neg_lo:[0,0,1] neg_hi:[0,0,1]
	s_nop 0
	v_xor_b32_e32 v32, 0x80000000, v21
	v_mov_b32_e32 v33, v20
	v_pk_add_f32 v[20:21], v[30:31], v[18:19]
	v_pk_add_f32 v[18:19], v[30:31], v[18:19] neg_lo:[0,1] neg_hi:[0,1]
	v_pk_add_f32 v[30:31], v[16:17], v[32:33]
	v_pk_add_f32 v[16:17], v[16:17], v[32:33] neg_lo:[0,1] neg_hi:[0,1]
	ds_write2_b64 v194, v[26:27], v[20:21] offset1:1
	ds_write2_b64 v196, v[28:29], v[30:31] offset1:1
	ds_write2_b64 v195, v[24:25], v[18:19] offset1:1
	ds_write2_b64 v197, v[22:23], v[16:17] offset1:1
	s_waitcnt lgkmcnt(0)
	s_barrier
	ds_read2_b64 v[16:19], v119 offset1:9
	v_mov_b64_e32 v[32:33], v[238:239]
	ds_read2_b64 v[20:23], v119 offset0:18 offset1:27
	v_mov_b64_e32 v[34:35], v[240:241]
	v_mov_b64_e32 v[36:37], v[242:243]
	ds_read2_b64 v[24:27], v119 offset0:36 offset1:45
	v_mov_b64_e32 v[38:39], v[244:245]
	v_mov_b64_e32 v[40:41], v[246:247]
	ds_read2_b64 v[28:31], v119 offset0:54 offset1:63
	v_mov_b64_e32 v[42:43], v[248:249]
	s_waitcnt lgkmcnt(0)
	v_pk_mul_f32 v[46:47], v[30:31], v[250:251] op_sel:[1,1] op_sel_hi:[0,1]
	v_fma_f32 v48, v30, v250, v46
	v_fma_f32 v49, v31, v250, -v47
	s_nop 0
	v_pk_mul_f32 v[30:31], v[18:19], v[32:33] op_sel:[1,1] op_sel_hi:[0,1]
	v_fma_f32 v44, v18, v32, v30
	v_fma_f32 v45, v19, v32, -v31
	s_nop 0
	v_pk_mul_f32 v[18:19], v[20:21], v[34:35] op_sel:[1,1] op_sel_hi:[0,1]
	v_fma_f32 v30, v20, v34, v18
	v_fma_f32 v31, v21, v34, -v19
	s_nop 0
	v_pk_mul_f32 v[18:19], v[22:23], v[36:37] op_sel:[1,1] op_sel_hi:[0,1]
	v_fma_f32 v20, v22, v36, v18
	v_fma_f32 v21, v23, v36, -v19
	s_nop 0
	v_pk_mul_f32 v[18:19], v[24:25], v[38:39] op_sel:[1,1] op_sel_hi:[0,1]
	v_fma_f32 v22, v24, v38, v18
	v_fma_f32 v23, v25, v38, -v19
	s_nop 0
	v_pk_mul_f32 v[18:19], v[26:27], v[40:41] op_sel:[1,1] op_sel_hi:[0,1]
	v_fma_f32 v24, v26, v40, v18
	v_fma_f32 v25, v27, v40, -v19
	s_nop 0
	v_pk_mul_f32 v[18:19], v[28:29], v[42:43] op_sel:[1,1] op_sel_hi:[0,1]
	v_fma_f32 v26, v28, v42, v18
	v_fma_f32 v27, v29, v42, -v19
	s_nop 0
	v_pk_add_f32 v[18:19], v[16:17], v[22:23]
	v_pk_add_f32 v[16:17], v[16:17], v[22:23] neg_lo:[0,1] neg_hi:[0,1]
	v_pk_add_f32 v[22:23], v[44:45], v[24:25]
	v_pk_add_f32 v[24:25], v[44:45], v[24:25] neg_lo:[0,1] neg_hi:[0,1]
	v_pk_add_f32 v[28:29], v[30:31], v[26:27]
	v_pk_add_f32 v[26:27], v[30:31], v[26:27] neg_lo:[0,1] neg_hi:[0,1]
	v_pk_add_f32 v[30:31], v[20:21], v[48:49]
	v_pk_add_f32 v[20:21], v[20:21], v[48:49] neg_lo:[0,1] neg_hi:[0,1]
	v_pk_add_f32 v[32:33], v[24:25], v[24:25] op_sel:[0,1] neg_lo:[0,1] neg_hi:[0,1]
	v_pk_add_f32 v[24:25], v[24:25], v[24:25] op_sel_hi:[0,1]
	v_mov_b32_e32 v33, v25
	v_xor_b32_e32 v24, 0x80000000, v27
	v_mov_b32_e32 v25, v26
	v_pk_add_f32 v[26:27], v[20:21], v[20:21] op_sel:[0,1]
	v_pk_add_f32 v[20:21], v[20:21], v[20:21] op_sel_hi:[0,1] neg_lo:[0,1] neg_hi:[0,1]
	v_mov_b32_e32 v27, v21
	v_pk_mul_f32 v[20:21], v[26:27], s[62:63]
	v_pk_add_f32 v[26:27], v[18:19], v[28:29]
	v_pk_add_f32 v[18:19], v[18:19], v[28:29] neg_lo:[0,1] neg_hi:[0,1]
	v_pk_add_f32 v[28:29], v[22:23], v[30:31]
	v_pk_add_f32 v[22:23], v[22:23], v[30:31] neg_lo:[0,1] neg_hi:[0,1]
	s_nop 0
	v_xor_b32_e32 v30, 0x80000000, v23
	v_mov_b32_e32 v31, v22
	v_pk_add_f32 v[22:23], v[26:27], v[28:29]
	v_pk_add_f32 v[26:27], v[26:27], v[28:29] neg_lo:[0,1] neg_hi:[0,1]
	v_pk_add_f32 v[28:29], v[18:19], v[30:31]
	v_pk_add_f32 v[18:19], v[18:19], v[30:31] neg_lo:[0,1] neg_hi:[0,1]
	v_pk_add_f32 v[30:31], v[16:17], v[24:25]
	v_pk_add_f32 v[16:17], v[16:17], v[24:25] neg_lo:[0,1] neg_hi:[0,1]
	v_pk_fma_f32 v[24:25], v[32:33], s[20:21], v[20:21] op_sel_hi:[1,0,1]
	v_pk_fma_f32 v[20:21], v[32:33], s[20:21], v[20:21] op_sel_hi:[1,0,1] neg_lo:[0,0,1] neg_hi:[0,0,1]
	s_nop 0
	v_xor_b32_e32 v32, 0x80000000, v21
	v_mov_b32_e32 v33, v20
	v_pk_add_f32 v[20:21], v[30:31], v[24:25]
	v_pk_add_f32 v[24:25], v[30:31], v[24:25] neg_lo:[0,1] neg_hi:[0,1]
	v_pk_add_f32 v[30:31], v[16:17], v[32:33]
	v_pk_add_f32 v[16:17], v[16:17], v[32:33] neg_lo:[0,1] neg_hi:[0,1]
	ds_write2_b64 v119, v[22:23], v[20:21] offset1:9
	ds_write2_b64 v119, v[28:29], v[30:31] offset0:18 offset1:27
	ds_write2_b64 v119, v[26:27], v[24:25] offset0:36 offset1:45
	ds_write2_b64 v119, v[18:19], v[16:17] offset0:54 offset1:63
	ds_read2_b64 v[16:19], v193 offset1:9
	v_mov_b64_e32 v[32:33], v[238:239]
	ds_read2_b64 v[20:23], v193 offset0:18 offset1:27
	v_mov_b64_e32 v[34:35], v[240:241]
	v_mov_b64_e32 v[36:37], v[242:243]
	ds_read2_b64 v[24:27], v193 offset0:36 offset1:45
	v_mov_b64_e32 v[38:39], v[244:245]
	v_mov_b64_e32 v[40:41], v[246:247]
	ds_read2_b64 v[28:31], v193 offset0:54 offset1:63
	v_mov_b64_e32 v[42:43], v[248:249]
	s_waitcnt lgkmcnt(0)
; __device__ __forceinline__ c2 cmulc(c2 a, c2 b) { return (c2){a.x * b.x + a.y * b.y, a.y * b.x - a.x * b.y}; }
; __device__ __forceinline__ c2 mpi(c2 a) { return (c2){-a.y, a.x}; }
; __device__ __forceinline__ void idft8(c2 (&x)[8]) {
;     const float s = 0.70710678118654752f;
;     const c2 a0 = x[0] + x[4], a4 = x[0] - x[4], a1 = x[1] + x[5], a5 = x[1] - x[5], a2 = x[2] + x[6], a6 = x[2] - x[6], a3 = x[3] + x[7], a7 = x[3] - x[7];
;     const c2 a5w = (c2){(a5.x - a5.y) * s, (a5.x + a5.y) * s};
;     const c2 a6w = mpi(a6);
;     const c2 a7w = (c2){-(a7.x + a7.y) * s, (a7.x - a7.y) * s};
;     const c2 b0 = a0 + a2, b1 = a0 - a2, b2 = a1 + a3, b3 = mpi(a1 - a3);
;     x[0] = b0 + b2; x[4] = b0 - b2; x[2] = b1 + b3; x[6] = b1 - b3;
;     const c2 c0 = a4 + a6w, c1 = a4 - a6w, c2_ = a5w + a7w, c3 = mpi(a5w - a7w);
;     x[1] = c0 + c2_; x[5] = c0 - c2_; x[3] = c1 + c3; x[7] = c1 - c3;
; }
; template <int S> __device__ __forceinline__ void inv_mid(c2* buf, const c2* tws, int tid) {
;     constexpr int lq = 9 - 3 * S, Q = 1 << lq; const c2* T = tws + (S == 1 ? 3584 : 4032);
;     const int k = tid & (Q - 1), base = ((tid >> lq) << (lq + 3)) + k;
;     c2 x[8];
;     c2* bp_ = buf + LP(base); constexpr int QP = Q + Q / 8;
; #pragma unroll
;     for (int r = 0; r < 8; ++r) { c2 v = bp_[r * QP]; if (r) v = cmulc(v, T[(r - 1) * Q + k]); x[r] = v; }
;     idft8(x);
; #pragma unroll
;     for (int q = 0; q < 8; ++q) bp_[q * QP] = x[q];
; }
	v_pk_mul_f32 v[46:47], v[30:31], v[250:251] op_sel:[1,1] op_sel_hi:[0,1]
	v_fma_f32 v48, v30, v250, v46
	v_fma_f32 v49, v31, v250, -v47
	s_nop 0
	v_pk_mul_f32 v[30:31], v[18:19], v[32:33] op_sel:[1,1] op_sel_hi:[0,1]
	v_fma_f32 v44, v18, v32, v30
	v_fma_f32 v45, v19, v32, -v31
	s_nop 0
	v_pk_mul_f32 v[18:19], v[20:21], v[34:35] op_sel:[1,1] op_sel_hi:[0,1]
	v_fma_f32 v30, v20, v34, v18
	v_fma_f32 v31, v21, v34, -v19
	s_nop 0
	v_pk_mul_f32 v[18:19], v[22:23], v[36:37] op_sel:[1,1] op_sel_hi:[0,1]
	v_fma_f32 v20, v22, v36, v18
	v_fma_f32 v21, v23, v36, -v19
	s_nop 0
	v_pk_mul_f32 v[18:19], v[24:25], v[38:39] op_sel:[1,1] op_sel_hi:[0,1]
	v_fma_f32 v22, v24, v38, v18
	v_fma_f32 v23, v25, v38, -v19
	s_nop 0
	v_pk_mul_f32 v[18:19], v[26:27], v[40:41] op_sel:[1,1] op_sel_hi:[0,1]
	v_fma_f32 v24, v26, v40, v18
	v_fma_f32 v25, v27, v40, -v19
	s_nop 0
	v_pk_mul_f32 v[18:19], v[28:29], v[42:43] op_sel:[1,1] op_sel_hi:[0,1]
	v_fma_f32 v26, v28, v42, v18
	v_fma_f32 v27, v29, v42, -v19
	s_nop 0
	v_pk_add_f32 v[18:19], v[16:17], v[22:23]
	v_pk_add_f32 v[16:17], v[16:17], v[22:23] neg_lo:[0,1] neg_hi:[0,1]
	v_pk_add_f32 v[22:23], v[44:45], v[24:25]
	v_pk_add_f32 v[24:25], v[44:45], v[24:25] neg_lo:[0,1] neg_hi:[0,1]
	v_pk_add_f32 v[28:29], v[30:31], v[26:27]
	v_pk_add_f32 v[26:27], v[30:31], v[26:27] neg_lo:[0,1] neg_hi:[0,1]
	v_pk_add_f32 v[30:31], v[20:21], v[48:49]
	v_pk_add_f32 v[20:21], v[20:21], v[48:49] neg_lo:[0,1] neg_hi:[0,1]
	v_pk_add_f32 v[32:33], v[24:25], v[24:25] op_sel:[0,1] neg_lo:[0,1] neg_hi:[0,1]
	v_pk_add_f32 v[24:25], v[24:25], v[24:25] op_sel_hi:[0,1]
	v_mov_b32_e32 v33, v25
	v_xor_b32_e32 v24, 0x80000000, v27
	v_mov_b32_e32 v25, v26
	v_pk_add_f32 v[26:27], v[20:21], v[20:21] op_sel:[0,1]
	v_pk_add_f32 v[20:21], v[20:21], v[20:21] op_sel_hi:[0,1] neg_lo:[0,1] neg_hi:[0,1]
	v_mov_b32_e32 v27, v21
	v_pk_mul_f32 v[20:21], v[26:27], s[62:63]
	v_pk_add_f32 v[26:27], v[18:19], v[28:29]
	v_pk_add_f32 v[18:19], v[18:19], v[28:29] neg_lo:[0,1] neg_hi:[0,1]
	v_pk_add_f32 v[28:29], v[22:23], v[30:31]
	v_pk_add_f32 v[22:23], v[22:23], v[30:31] neg_lo:[0,1] neg_hi:[0,1]
	s_nop 0
	v_xor_b32_e32 v30, 0x80000000, v23
	v_mov_b32_e32 v31, v22
	v_pk_add_f32 v[22:23], v[26:27], v[28:29]
	v_pk_add_f32 v[26:27], v[26:27], v[28:29] neg_lo:[0,1] neg_hi:[0,1]
	v_pk_add_f32 v[28:29], v[18:19], v[30:31]
	v_pk_add_f32 v[18:19], v[18:19], v[30:31] neg_lo:[0,1] neg_hi:[0,1]
	v_pk_add_f32 v[30:31], v[16:17], v[24:25]
	v_pk_add_f32 v[16:17], v[16:17], v[24:25] neg_lo:[0,1] neg_hi:[0,1]
	v_pk_fma_f32 v[24:25], v[32:33], s[20:21], v[20:21] op_sel_hi:[1,0,1]
	v_pk_fma_f32 v[20:21], v[32:33], s[20:21], v[20:21] op_sel_hi:[1,0,1] neg_lo:[0,0,1] neg_hi:[0,0,1]
	s_nop 0
	v_xor_b32_e32 v32, 0x80000000, v21
	v_mov_b32_e32 v33, v20
	v_pk_add_f32 v[20:21], v[30:31], v[24:25]
	v_pk_add_f32 v[24:25], v[30:31], v[24:25] neg_lo:[0,1] neg_hi:[0,1]
	v_pk_add_f32 v[30:31], v[16:17], v[32:33]
	v_pk_add_f32 v[16:17], v[16:17], v[32:33] neg_lo:[0,1] neg_hi:[0,1]
	ds_write2_b64 v193, v[22:23], v[20:21] offset1:9
	ds_write2_b64 v193, v[28:29], v[30:31] offset0:18 offset1:27
	ds_write2_b64 v193, v[26:27], v[24:25] offset0:36 offset1:45
	ds_write2_b64 v193, v[18:19], v[16:17] offset0:54 offset1:63
	s_waitcnt lgkmcnt(0)
	s_barrier
	ds_read2_b64 v[16:19], v117 offset1:72
	v_mov_b64_e32 v[32:33], v[224:225]
	ds_read2_b64 v[20:23], v117 offset0:144 offset1:216
	v_mov_b64_e32 v[34:35], v[226:227]
	v_mov_b64_e32 v[36:37], v[228:229]
	ds_read2_b64 v[24:27], v63 offset0:32 offset1:104
	v_mov_b64_e32 v[38:39], v[230:231]
	v_mov_b64_e32 v[40:41], v[232:233]
	ds_read2_b64 v[28:31], v63 offset0:176 offset1:248
	v_mov_b64_e32 v[42:43], v[234:235]
	s_waitcnt lgkmcnt(0)
	v_pk_mul_f32 v[46:47], v[30:31], v[236:237] op_sel:[1,1] op_sel_hi:[0,1]
	v_fma_f32 v48, v30, v236, v46
	v_fma_f32 v49, v31, v236, -v47
	s_nop 0
	v_pk_mul_f32 v[30:31], v[18:19], v[32:33] op_sel:[1,1] op_sel_hi:[0,1]
	v_fma_f32 v44, v18, v32, v30
	v_fma_f32 v45, v19, v32, -v31
	s_nop 0
	v_pk_mul_f32 v[18:19], v[20:21], v[34:35] op_sel:[1,1] op_sel_hi:[0,1]
	v_fma_f32 v30, v20, v34, v18
	v_fma_f32 v31, v21, v34, -v19
	s_nop 0
	v_pk_mul_f32 v[18:19], v[22:23], v[36:37] op_sel:[1,1] op_sel_hi:[0,1]
	v_fma_f32 v20, v22, v36, v18
	v_fma_f32 v21, v23, v36, -v19
	s_nop 0
	v_pk_mul_f32 v[18:19], v[24:25], v[38:39] op_sel:[1,1] op_sel_hi:[0,1]
	v_fma_f32 v22, v24, v38, v18
	v_fma_f32 v23, v25, v38, -v19
	s_nop 0
	v_pk_mul_f32 v[18:19], v[26:27], v[40:41] op_sel:[1,1] op_sel_hi:[0,1]
	v_fma_f32 v24, v26, v40, v18
	v_fma_f32 v25, v27, v40, -v19
	s_nop 0
	v_pk_mul_f32 v[18:19], v[28:29], v[42:43] op_sel:[1,1] op_sel_hi:[0,1]
	v_fma_f32 v26, v28, v42, v18
	v_fma_f32 v27, v29, v42, -v19
	s_nop 0
	v_pk_add_f32 v[18:19], v[16:17], v[22:23]
	v_pk_add_f32 v[16:17], v[16:17], v[22:23] neg_lo:[0,1] neg_hi:[0,1]
	v_pk_add_f32 v[22:23], v[44:45], v[24:25]
	v_pk_add_f32 v[24:25], v[44:45], v[24:25] neg_lo:[0,1] neg_hi:[0,1]
	v_pk_add_f32 v[28:29], v[30:31], v[26:27]
	v_pk_add_f32 v[26:27], v[30:31], v[26:27] neg_lo:[0,1] neg_hi:[0,1]
	v_pk_add_f32 v[30:31], v[20:21], v[48:49]
	v_pk_add_f32 v[20:21], v[20:21], v[48:49] neg_lo:[0,1] neg_hi:[0,1]
	v_pk_add_f32 v[32:33], v[24:25], v[24:25] op_sel:[0,1] neg_lo:[0,1] neg_hi:[0,1]
	v_pk_add_f32 v[24:25], v[24:25], v[24:25] op_sel_hi:[0,1]
	v_mov_b32_e32 v33, v25
	v_xor_b32_e32 v24, 0x80000000, v27
	v_mov_b32_e32 v25, v26
	v_pk_add_f32 v[26:27], v[20:21], v[20:21] op_sel:[0,1]
	v_pk_add_f32 v[20:21], v[20:21], v[20:21] op_sel_hi:[0,1] neg_lo:[0,1] neg_hi:[0,1]
	v_mov_b32_e32 v27, v21
	v_pk_mul_f32 v[20:21], v[26:27], s[62:63]
	v_pk_add_f32 v[26:27], v[18:19], v[28:29]
	v_pk_add_f32 v[18:19], v[18:19], v[28:29] neg_lo:[0,1] neg_hi:[0,1]
; __device__ __forceinline__ c2 cmulc(c2 a, c2 b) { return (c2){a.x * b.x + a.y * b.y, a.y * b.x - a.x * b.y}; }
; __device__ __forceinline__ c2 mpi(c2 a) { return (c2){-a.y, a.x}; }
; __device__ __forceinline__ void idft8(c2 (&x)[8]) {
;     const float s = 0.70710678118654752f;
;     const c2 a0 = x[0] + x[4], a4 = x[0] - x[4], a1 = x[1] + x[5], a5 = x[1] - x[5], a2 = x[2] + x[6], a6 = x[2] - x[6], a3 = x[3] + x[7], a7 = x[3] - x[7];
;     const c2 a5w = (c2){(a5.x - a5.y) * s, (a5.x + a5.y) * s};
;     const c2 a6w = mpi(a6);
;     const c2 a7w = (c2){-(a7.x + a7.y) * s, (a7.x - a7.y) * s};
;     const c2 b0 = a0 + a2, b1 = a0 - a2, b2 = a1 + a3, b3 = mpi(a1 - a3);
;     x[0] = b0 + b2; x[4] = b0 - b2; x[2] = b1 + b3; x[6] = b1 - b3;
;     const c2 c0 = a4 + a6w, c1 = a4 - a6w, c2_ = a5w + a7w, c3 = mpi(a5w - a7w);
;     x[1] = c0 + c2_; x[5] = c0 - c2_; x[3] = c1 + c3; x[7] = c1 - c3;
; }
; template <int S> __device__ __forceinline__ void inv_mid(c2* buf, const c2* tws, int tid) {
;     constexpr int lq = 9 - 3 * S, Q = 1 << lq; const c2* T = tws + (S == 1 ? 3584 : 4032);
;     const int k = tid & (Q - 1), base = ((tid >> lq) << (lq + 3)) + k;
;     c2 x[8];
;     c2* bp_ = buf + LP(base); constexpr int QP = Q + Q / 8;
; #pragma unroll
;     for (int r = 0; r < 8; ++r) { c2 v = bp_[r * QP]; if (r) v = cmulc(v, T[(r - 1) * Q + k]); x[r] = v; }
;     idft8(x);
; #pragma unroll
;     for (int q = 0; q < 8; ++q) bp_[q * QP] = x[q];
; }
; __device__ __forceinline__ void inv_s0(c2 (&x)[8], const c2* buf, const c2* tws, int tid) {
;     const c2* bp_ = buf + LP(tid);
; #pragma unroll
;     for (int r = 0; r < 8; ++r) { c2 v = bp_[576 * r]; if (r) v = cmulc(v, tws[(r - 1) * 512 + tid]); x[r] = v; }
;     idft8(x);
; }
	v_pk_add_f32 v[28:29], v[22:23], v[30:31]
	v_pk_add_f32 v[22:23], v[22:23], v[30:31] neg_lo:[0,1] neg_hi:[0,1]
	s_nop 0
	v_xor_b32_e32 v30, 0x80000000, v23
	v_mov_b32_e32 v31, v22
	v_pk_add_f32 v[22:23], v[26:27], v[28:29]
	v_pk_add_f32 v[26:27], v[26:27], v[28:29] neg_lo:[0,1] neg_hi:[0,1]
	v_pk_add_f32 v[28:29], v[18:19], v[30:31]
	v_pk_add_f32 v[18:19], v[18:19], v[30:31] neg_lo:[0,1] neg_hi:[0,1]
	v_pk_add_f32 v[30:31], v[16:17], v[24:25]
	v_pk_add_f32 v[16:17], v[16:17], v[24:25] neg_lo:[0,1] neg_hi:[0,1]
	v_pk_fma_f32 v[24:25], v[32:33], s[20:21], v[20:21] op_sel_hi:[1,0,1]
	v_pk_fma_f32 v[20:21], v[32:33], s[20:21], v[20:21] op_sel_hi:[1,0,1] neg_lo:[0,0,1] neg_hi:[0,0,1]
	s_nop 0
	v_xor_b32_e32 v32, 0x80000000, v21
	v_mov_b32_e32 v33, v20
	v_pk_add_f32 v[20:21], v[30:31], v[24:25]
	v_pk_add_f32 v[24:25], v[30:31], v[24:25] neg_lo:[0,1] neg_hi:[0,1]
	v_pk_add_f32 v[30:31], v[16:17], v[32:33]
	v_pk_add_f32 v[16:17], v[16:17], v[32:33] neg_lo:[0,1] neg_hi:[0,1]
	ds_write2_b64 v117, v[22:23], v[20:21] offset1:72
	ds_write2_b64 v117, v[28:29], v[30:31] offset0:144 offset1:216
	ds_write2_b64 v63, v[26:27], v[24:25] offset0:32 offset1:104
	ds_write2_b64 v63, v[18:19], v[16:17] offset0:176 offset1:248
	ds_read2_b64 v[16:19], v191 offset1:72
	v_mov_b64_e32 v[32:33], v[224:225]
	ds_read2_b64 v[20:23], v191 offset0:144 offset1:216
	v_mov_b64_e32 v[34:35], v[226:227]
	v_mov_b64_e32 v[36:37], v[228:229]
	ds_read2_b64 v[24:27], v192 offset0:32 offset1:104
	v_mov_b64_e32 v[38:39], v[230:231]
	v_mov_b64_e32 v[40:41], v[232:233]
	ds_read2_b64 v[28:31], v192 offset0:176 offset1:248
	v_mov_b64_e32 v[42:43], v[234:235]
	s_waitcnt lgkmcnt(0)
	v_pk_mul_f32 v[46:47], v[30:31], v[236:237] op_sel:[1,1] op_sel_hi:[0,1]
	v_fma_f32 v48, v30, v236, v46
	v_fma_f32 v49, v31, v236, -v47
	s_nop 0
	v_pk_mul_f32 v[30:31], v[18:19], v[32:33] op_sel:[1,1] op_sel_hi:[0,1]
	v_fma_f32 v44, v18, v32, v30
	v_fma_f32 v45, v19, v32, -v31
	s_nop 0
	v_pk_mul_f32 v[18:19], v[20:21], v[34:35] op_sel:[1,1] op_sel_hi:[0,1]
	v_fma_f32 v30, v20, v34, v18
	v_fma_f32 v31, v21, v34, -v19
	s_nop 0
	v_pk_mul_f32 v[18:19], v[22:23], v[36:37] op_sel:[1,1] op_sel_hi:[0,1]
	v_fma_f32 v20, v22, v36, v18
	v_fma_f32 v21, v23, v36, -v19
	s_nop 0
	v_pk_mul_f32 v[18:19], v[24:25], v[38:39] op_sel:[1,1] op_sel_hi:[0,1]
	v_fma_f32 v22, v24, v38, v18
	v_fma_f32 v23, v25, v38, -v19
	s_nop 0
	v_pk_mul_f32 v[18:19], v[26:27], v[40:41] op_sel:[1,1] op_sel_hi:[0,1]
	v_fma_f32 v24, v26, v40, v18
	v_fma_f32 v25, v27, v40, -v19
	s_nop 0
	v_pk_mul_f32 v[18:19], v[28:29], v[42:43] op_sel:[1,1] op_sel_hi:[0,1]
	v_fma_f32 v26, v28, v42, v18
	v_fma_f32 v27, v29, v42, -v19
	s_nop 0
	v_pk_add_f32 v[18:19], v[16:17], v[22:23]
	v_pk_add_f32 v[16:17], v[16:17], v[22:23] neg_lo:[0,1] neg_hi:[0,1]
	v_pk_add_f32 v[22:23], v[44:45], v[24:25]
	v_pk_add_f32 v[24:25], v[44:45], v[24:25] neg_lo:[0,1] neg_hi:[0,1]
	v_pk_add_f32 v[28:29], v[30:31], v[26:27]
	v_pk_add_f32 v[26:27], v[30:31], v[26:27] neg_lo:[0,1] neg_hi:[0,1]
	v_pk_add_f32 v[30:31], v[20:21], v[48:49]
	v_pk_add_f32 v[20:21], v[20:21], v[48:49] neg_lo:[0,1] neg_hi:[0,1]
	v_pk_add_f32 v[32:33], v[24:25], v[24:25] op_sel:[0,1] neg_lo:[0,1] neg_hi:[0,1]
	v_pk_add_f32 v[24:25], v[24:25], v[24:25] op_sel_hi:[0,1]
	v_mov_b32_e32 v33, v25
	v_xor_b32_e32 v24, 0x80000000, v27
	v_mov_b32_e32 v25, v26
	v_pk_add_f32 v[26:27], v[20:21], v[20:21] op_sel:[0,1]
	v_pk_add_f32 v[20:21], v[20:21], v[20:21] op_sel_hi:[0,1] neg_lo:[0,1] neg_hi:[0,1]
	v_mov_b32_e32 v27, v21
	v_pk_mul_f32 v[20:21], v[26:27], s[62:63]
	v_pk_add_f32 v[26:27], v[18:19], v[28:29]
	v_pk_add_f32 v[18:19], v[18:19], v[28:29] neg_lo:[0,1] neg_hi:[0,1]
	v_pk_add_f32 v[28:29], v[22:23], v[30:31]
	v_pk_add_f32 v[22:23], v[22:23], v[30:31] neg_lo:[0,1] neg_hi:[0,1]
	s_mov_b64 s[62:63], -1
	v_xor_b32_e32 v30, 0x80000000, v23
	v_mov_b32_e32 v31, v22
	v_pk_add_f32 v[22:23], v[26:27], v[28:29]
	v_pk_add_f32 v[26:27], v[26:27], v[28:29] neg_lo:[0,1] neg_hi:[0,1]
	v_pk_add_f32 v[28:29], v[18:19], v[30:31]
	v_pk_add_f32 v[18:19], v[18:19], v[30:31] neg_lo:[0,1] neg_hi:[0,1]
	v_pk_add_f32 v[30:31], v[16:17], v[24:25]
	v_pk_add_f32 v[16:17], v[16:17], v[24:25] neg_lo:[0,1] neg_hi:[0,1]
	v_pk_fma_f32 v[24:25], v[32:33], s[20:21], v[20:21] op_sel_hi:[1,0,1]
	v_pk_fma_f32 v[20:21], v[32:33], s[20:21], v[20:21] op_sel_hi:[1,0,1] neg_lo:[0,0,1] neg_hi:[0,0,1]
	s_nop 0
	v_xor_b32_e32 v32, 0x80000000, v21
	v_mov_b32_e32 v33, v20
	v_pk_add_f32 v[20:21], v[30:31], v[24:25]
	v_pk_add_f32 v[24:25], v[30:31], v[24:25] neg_lo:[0,1] neg_hi:[0,1]
	v_pk_add_f32 v[30:31], v[16:17], v[32:33]
	v_pk_add_f32 v[16:17], v[16:17], v[32:33] neg_lo:[0,1] neg_hi:[0,1]
	ds_write2_b64 v191, v[22:23], v[20:21] offset1:72
	ds_write2_b64 v191, v[28:29], v[30:31] offset0:144 offset1:216
	ds_write2_b64 v192, v[26:27], v[24:25] offset0:32 offset1:104
	ds_write2_b64 v192, v[18:19], v[16:17] offset0:176 offset1:248
	s_waitcnt lgkmcnt(0)
	s_barrier
	ds_read2st64_b64 v[40:43], v115 offset1:9
	v_mov_b64_e32 v[28:29], v[210:211]
	v_mov_b64_e32 v[30:31], v[212:213]
	ds_read2st64_b64 v[52:55], v115 offset0:18 offset1:27
	v_mov_b64_e32 v[24:25], v[214:215]
	v_mov_b64_e32 v[26:27], v[216:217]
	ds_read2st64_b64 v[48:51], v115 offset0:36 offset1:45
	v_mov_b64_e32 v[20:21], v[218:219]
	v_mov_b64_e32 v[22:23], v[220:221]
	ds_read2st64_b64 v[44:47], v115 offset0:54 offset1:63
	v_mov_b64_e32 v[90:91], v[222:223]
	ds_read2st64_b64 v[16:19], v115 offset0:72 offset1:81
	ds_read2st64_b64 v[36:39], v115 offset0:90 offset1:99
	ds_read2st64_b64 v[32:35], v115 offset0:108 offset1:117
	ds_read_b64 v[94:95], v115 offset:64512
	ds_read_b64 v[92:93], v116 offset:32256
	s_cbranch_vccnz .LBB0_674
	s_andn2_b64 vcc, exec, s[62:63]
	s_cbranch_vccz .LBB0_675

; __device__ __forceinline__ c2 cmulc(c2 a, c2 b) { return (c2){a.x * b.x + a.y * b.y, a.y * b.x - a.x * b.y}; }
; __device__ __forceinline__ void inv_s0(c2 (&x)[8], const c2* buf, const c2* tws, int tid) {
;     const c2* bp_ = buf + LP(tid);
; #pragma unroll
;     for (int r = 0; r < 8; ++r) { c2 v = bp_[576 * r]; if (r) v = cmulc(v, tws[(r - 1) * 512 + tid]); x[r] = v; }
;     idft8(x);
; }
.LBB0_638:
	s_waitcnt lgkmcnt(0)
	v_pk_mul_f32 v[98:99], v[42:43], v[28:29] op_sel:[0,1]
	s_or_b32 s16, s3, 0x10000
	v_fma_f32 v96, v42, v28, v99
	v_fma_f32 v97, v43, v28, -v98
	s_or_b32 s7, s3, 0x10800
	s_waitcnt lgkmcnt(0)
	v_pk_mul_f32 v[42:43], v[52:53], v[30:31] op_sel:[0,1]
	s_mov_b64 s[62:63], -1
	v_fma_f32 v98, v52, v30, v43
	v_fma_f32 v99, v53, v30, -v42
	s_and_b64 vcc, exec, s[84:85]
	s_waitcnt lgkmcnt(0)
	v_pk_mul_f32 v[42:43], v[54:55], v[24:25] op_sel:[0,1]
	s_nop 0
	v_fma_f32 v52, v54, v24, v43
	v_fma_f32 v53, v55, v24, -v42
	s_nop 0
	s_waitcnt lgkmcnt(0)
	v_pk_mul_f32 v[42:43], v[48:49], v[26:27] op_sel:[0,1]
	s_nop 0
	v_fma_f32 v54, v48, v26, v43
	v_fma_f32 v55, v49, v26, -v42
	s_nop 0
	s_waitcnt lgkmcnt(0)
	v_pk_mul_f32 v[42:43], v[50:51], v[20:21] op_sel:[0,1]
	s_nop 0
	v_fma_f32 v100, v50, v20, v43
	v_fma_f32 v101, v51, v20, -v42
	s_nop 0
	s_waitcnt lgkmcnt(0)
	v_pk_mul_f32 v[42:43], v[44:45], v[22:23] op_sel:[0,1]
	s_nop 0
	v_fma_f32 v50, v44, v22, v43
	v_fma_f32 v51, v45, v22, -v42
	v_pk_add_f32 v[44:45], v[96:97], v[100:101]
	s_waitcnt lgkmcnt(0)
	v_pk_mul_f32 v[42:43], v[46:47], v[90:91] op_sel:[0,1]
	s_nop 0
	v_fma_f32 v102, v46, v90, v43
	v_fma_f32 v103, v47, v90, -v42
	v_pk_add_f32 v[46:47], v[98:99], v[50:51]
	v_pk_add_f32 v[42:43], v[40:41], v[54:55]
	v_pk_add_f32 v[48:49], v[52:53], v[102:103]
	v_pk_add_f32 v[204:205], v[42:43], v[46:47]
	v_pk_add_f32 v[206:207], v[44:45], v[48:49]
	s_nop 0
	v_pk_add_f32 v[204:205], v[204:205], v[206:207]
	ds_read_u16 v206, v160 offset:14
	ds_read_u16 v207, v160 offset:16
	ds_read_u16 v208, v160 offset:18
	v_pk_mul_f32 v[204:205], v[66:67], v[204:205]
	s_waitcnt lgkmcnt(0)
	v_lshlrev_b32_e32 v206, 16, v206
	s_waitcnt lgkmcnt(0)
	v_lshlrev_b32_e32 v207, 16, v207
	v_mul_f32_e32 v207, v190, v207
	v_fmac_f32_e32 v207, v187, v206
	s_waitcnt lgkmcnt(0)
	v_lshlrev_b32_e32 v206, 16, v208
	v_fmac_f32_e32 v207, v189, v206
	v_add_f32_e32 v206, v188, v207
	ds_read_u16 v207, v161 offset:14
	ds_read_u16 v208, v161 offset:16
	ds_read_u16 v209, v161 offset:18
	v_fma_f32 v202, v184, v202, v204
	v_mul_f32_e32 v202, v202, v206
	s_waitcnt lgkmcnt(0)
	v_lshlrev_b32_e32 v207, 16, v207
	s_waitcnt lgkmcnt(0)
	v_lshlrev_b32_e32 v208, 16, v208
	v_mul_f32_e32 v208, v190, v208
	v_fmac_f32_e32 v208, v187, v207
	s_waitcnt lgkmcnt(0)
	v_lshlrev_b32_e32 v207, 16, v209
	v_add_u32_e32 v206, s16, v113
	v_fmac_f32_e32 v208, v189, v207
	v_ashrrev_i32_e32 v207, 31, v206
	v_add_f32_e32 v208, v188, v208
	v_cvt_pk_bf16_f32 v202, v202, s0
	v_lshl_add_u64 v[206:207], v[206:207], 1, s[50:51]
	v_fmac_f32_e32 v205, v184, v203
	global_store_short v[206:207], v202, off
	v_mul_f32_e32 v202, v205, v208
	v_cvt_pk_bf16_f32 v204, v202, s0
	v_add_u32_e32 v202, s7, v113
	v_ashrrev_i32_e32 v203, 31, v202
	v_lshl_add_u64 v[202:203], v[202:203], 1, s[50:51]
	global_store_short v[202:203], v204, off
	s_cbranch_vccz .LBB0_677
	s_andn2_b64 vcc, exec, s[62:63]
	s_cbranch_vccz .LBB0_678

; __device__ __forceinline__ c2 cmulc(c2 a, c2 b) { return (c2){a.x * b.x + a.y * b.y, a.y * b.x - a.x * b.y}; }
; __device__ __forceinline__ void inv_s0(c2 (&x)[8], const c2* buf, const c2* tws, int tid) {
;     const c2* bp_ = buf + LP(tid);
; #pragma unroll
;     for (int r = 0; r < 8; ++r) { c2 v = bp_[576 * r]; if (r) v = cmulc(v, tws[(r - 1) * 512 + tid]); x[r] = v; }
;     idft8(x);
; }
.LBB0_658:
	v_mov_b32_e32 v42, v28
	v_mov_b32_e32 v43, v28
	v_mov_b32_e32 v28, v29
	v_pk_mul_f32 v[96:97], v[28:29], v[18:19]
	v_mov_b32_e32 v44, v30
	v_mov_b32_e32 v45, v30
	v_mov_b32_e32 v30, v31
	v_fma_f32 v28, v42, v18, v97
	v_fma_f32 v29, v43, v19, -v96
	v_mov_b32_e32 v46, v24
	v_pk_mul_f32 v[18:19], v[30:31], v[36:37]
	v_mov_b32_e32 v47, v24
	v_mov_b32_e32 v24, v25
	v_fma_f32 v30, v44, v36, v19
	v_fma_f32 v31, v45, v37, -v18
	v_mov_b32_e32 v48, v26
	v_pk_mul_f32 v[18:19], v[24:25], v[38:39]
	v_mov_b32_e32 v49, v26
	v_mov_b32_e32 v26, v27
	v_fma_f32 v36, v46, v38, v19
	v_fma_f32 v37, v47, v39, -v18
	v_mov_b32_e32 v50, v20
	v_pk_mul_f32 v[18:19], v[26:27], v[32:33]
	v_mov_b32_e32 v51, v20
	v_mov_b32_e32 v20, v21
	v_fma_f32 v26, v48, v32, v19
	v_fma_f32 v27, v49, v33, -v18
	v_mov_b32_e32 v52, v22
	v_pk_mul_f32 v[18:19], v[20:21], v[34:35]
	v_mov_b32_e32 v53, v22
	v_mov_b32_e32 v22, v23
	v_fma_f32 v32, v50, v34, v19
	v_fma_f32 v33, v51, v35, -v18
	v_mov_b32_e32 v54, v90
	v_pk_mul_f32 v[18:19], v[22:23], v[94:95]
	v_mov_b32_e32 v55, v90
	v_mov_b32_e32 v90, v91
	v_fma_f32 v34, v52, v94, v19
	v_fma_f32 v35, v53, v95, -v18
	v_pk_add_f32 v[20:21], v[28:29], v[32:33]
	v_pk_mul_f32 v[18:19], v[90:91], v[92:93]
	v_pk_add_f32 v[22:23], v[30:31], v[34:35]
	v_fma_f32 v38, v54, v92, v19
	v_fma_f32 v39, v55, v93, -v18
	s_or_b32 s7, s3, 0x11000
	v_pk_add_f32 v[18:19], v[16:17], v[26:27]
	v_pk_add_f32 v[24:25], v[36:37], v[38:39]
	v_pk_add_f32 v[42:43], v[18:19], v[22:23]
	v_pk_add_f32 v[44:45], v[20:21], v[24:25]
	s_or_b32 s3, s3, 0x11800
	v_pk_add_f32 v[42:43], v[42:43], v[44:45]
	ds_read_u16 v44, v168 offset:14
	ds_read_u16 v45, v168 offset:16
	ds_read_u16 v46, v168 offset:18
	ds_read_u16 v47, v169 offset:14
	ds_read_u16 v48, v169 offset:16
	ds_read_u16 v49, v169 offset:18
	s_waitcnt lgkmcnt(0)
	v_lshlrev_b32_e32 v45, 16, v45
	v_lshlrev_b32_e32 v44, 16, v44
	v_mul_f32_e32 v45, v190, v45
	v_fmac_f32_e32 v45, v187, v44
	s_waitcnt lgkmcnt(0)
	v_lshlrev_b32_e32 v44, 16, v46
	v_pk_mul_f32 v[42:43], v[66:67], v[42:43]
	v_fmac_f32_e32 v45, v189, v44
	s_waitcnt lgkmcnt(0)
	v_lshlrev_b32_e32 v46, 16, v48
	v_add_f32_e32 v44, v188, v45
	v_lshlrev_b32_e32 v45, 16, v47
	v_mul_f32_e32 v46, v190, v46
	v_fma_f32 v40, v184, v40, v42
	v_fmac_f32_e32 v46, v187, v45
	s_waitcnt lgkmcnt(0)
	v_lshlrev_b32_e32 v45, 16, v49
	v_mul_f32_e32 v40, v40, v44
	v_add_u32_e32 v44, s7, v113
	v_fmac_f32_e32 v46, v189, v45
	v_ashrrev_i32_e32 v45, 31, v44
	v_add_f32_e32 v46, v188, v46
	v_cvt_pk_bf16_f32 v40, v40, s0
	v_lshl_add_u64 v[44:45], v[44:45], 1, s[50:51]
	v_fmac_f32_e32 v43, v184, v41
	global_store_short v[44:45], v40, off
	v_mul_f32_e32 v40, v43, v46
	v_cvt_pk_bf16_f32 v42, v40, s0
	v_add_u32_e32 v40, s3, v113
	v_ashrrev_i32_e32 v41, 31, v40
	v_lshl_add_u64 v[40:41], v[40:41], 1, s[50:51]
	s_and_b64 vcc, exec, s[84:85]
	s_mov_b64 s[62:63], -1
	global_store_short v[40:41], v42, off
	s_cbranch_vccz .LBB0_689
	s_andn2_b64 vcc, exec, s[62:63]
	s_cbranch_vccz .LBB0_690
